# diff-attn: V tile LDS row pitch 272->320 B (conflict-free transposed reads), row max as 4 parallel max3 chains + permlane32 swap instead of an 18-deep chain + ds_bpermute, per-head RMSNorm butterflies
# speedup vs baseline: 1.0559x; 1.0132x over previous
.LBB0_33:
	v_rcp_f32_e32 v98, v67
	v_lshlrev_b32_e32 v67, 2, v145
	v_rcp_f32_e32 v94, v69
	v_rcp_f32_e32 v90, v71
	v_rcp_f32_e32 v86, v73
	global_load_dword v69, v67, s[50:51]
	global_load_dword v71, v67, s[50:51] offset:128
	global_load_dword v73, v67, s[50:51] offset:256
	v_readlane_b32 s4, v251, 48
	global_load_dword v67, v67, s[50:51] offset:384
	v_rcp_f32_e32 v88, v72
	v_rcp_f32_e32 v72, v77
	v_rcp_f32_e32 v96, v68
	v_rcp_f32_e32 v68, v79
	v_rcp_f32_e32 v84, v74
	v_rcp_f32_e32 v82, v75
	v_rcp_f32_e32 v100, v66
	v_mov_b32_e32 v106, v34
	v_mov_b32_e32 v107, v18
	s_mov_b32 s10, 0x800000
	v_rcp_f32_e32 v66, v80
	v_ashrrev_i32_e32 v80, 3, v172
	v_rcp_f32_e32 v92, v70
	v_rcp_f32_e32 v70, v78
	v_rcp_f32_e32 v0, v81
	v_and_b32_e32 v81, 0xffffffc, v80
	v_rcp_f32_e32 v76, v76
	s_waitcnt vmcnt(3)
	v_mul_f32_e32 v69, 0x3f24fd5c, v69
	s_waitcnt vmcnt(2)
	v_mul_f32_e32 v71, 0x3f24fd5c, v71
	s_waitcnt vmcnt(1)
	v_mul_f32_e32 v73, 0x3f24fd5c, v73
	s_waitcnt vmcnt(0)
	v_mul_f32_e32 v77, 0x3f24fd5c, v67
	v_mov_b32_e32 v67, s4
	s_nop 0
	v_add_u32_e32 v79, 0, v160
	ds_read2st64_b32 v[74:75], v79 offset1:1
	v_add_u32_e32 v67, 0, v67
	v_lshl_add_u32 v78, v145, 1, v67
	s_waitcnt lgkmcnt(0)
	v_lshlrev_b32_e32 v102, 16, v74
	v_and_b32_e32 v103, 0xffff0000, v74
	v_lshlrev_b32_e32 v105, 16, v75
	v_and_b32_e32 v104, 0xffff0000, v75
	v_mov_b32_e32 v74, v2
	v_mov_b32_e32 v75, v50
	v_pk_mul_f32 v[74:75], v[74:75], v[100:101] op_sel_hi:[1,0]
	v_pk_mul_f32 v[100:101], v[106:107], v[100:101] op_sel_hi:[1,0]
	v_pk_fma_f32 v[102:103], v[142:143], v[74:75], v[102:103] neg_lo:[1,0,0] neg_hi:[1,0,0]
	v_pk_fma_f32 v[100:101], v[142:143], v[100:101], v[104:105] neg_lo:[1,0,0] neg_hi:[1,0,0]
	v_pk_mul_f32 v[74:75], v[102:103], v[102:103]
	v_pk_mul_f32 v[104:105], v[100:101], v[100:101]
	v_add_f32_e32 v2, v74, v75
	v_add_f32_e32 v2, v2, v105
	v_add_f32_e32 v2, v104, v2
	v_mad_u64_u32 v[74:75], s[4:5], v81, s77, v[78:79]
	s_waitcnt lgkmcnt(0)
	s_nop 1
	v_add_f32_dpp v2, v2, v2 quad_perm:[1,0,3,2] row_mask:0xf bank_mask:0xf
	s_waitcnt lgkmcnt(0)
	s_nop 1
	v_add_f32_dpp v2, v2, v2 quad_perm:[2,3,0,1] row_mask:0xf bank_mask:0xf
	s_waitcnt lgkmcnt(0)
	s_nop 1
	v_add_f32_dpp v2, v2, v2 row_half_mirror row_mask:0xf bank_mask:0xf
	s_waitcnt lgkmcnt(0)
	s_nop 1
	v_add_f32_dpp v2, v2, v2 row_mirror row_mask:0xf bank_mask:0xf
	ds_bpermute_b32 v18, v170, v2
	s_waitcnt lgkmcnt(0)
	v_add_f32_e32 v2, v2, v18
	v_fmamk_f32 v2, v2, 0x3c000000, v249
	v_cmp_gt_f32_e32 vcc, s10, v2
	v_mul_f32_e32 v18, 0x4b800000, v2
	s_nop 0
	v_cndmask_b32_e32 v2, v2, v18, vcc
	v_rsq_f32_e32 v2, v2
	s_nop 0
	v_mul_f32_e32 v18, 0x45800000, v2
	v_cndmask_b32_e32 v2, v2, v18, vcc
	v_mul_f32_e32 v18, v102, v2
	v_mul_f32_e32 v18, v69, v18
	v_cvt_pk_bf16_f32 v18, v18, s0
	ds_write_b16 v74, v18
	v_mul_f32_e32 v18, v103, v2
	v_mul_f32_e32 v18, v71, v18
	v_cvt_pk_bf16_f32 v18, v18, s0
	ds_write_b16 v74, v18 offset:64
	v_mul_f32_e32 v18, v101, v2
	v_mul_f32_e32 v2, v100, v2
	v_mul_f32_e32 v18, v73, v18
	v_mul_f32_e32 v2, v77, v2
	v_cvt_pk_bf16_f32 v18, v18, s0
	v_cvt_pk_bf16_f32 v2, v2, s0
	ds_write_b16 v74, v18 offset:128
	ds_write_b16 v74, v2 offset:192
	ds_read2st64_b32 v[100:101], v79 offset0:2 offset1:3
	v_mov_b32_e32 v50, v3
	v_pk_mul_f32 v[50:51], v[50:51], v[98:99] op_sel_hi:[1,0]
	v_mov_b32_e32 v18, v35
	v_pk_mul_f32 v[18:19], v[18:19], v[98:99] op_sel_hi:[1,0]
	s_waitcnt lgkmcnt(0)
	v_lshlrev_b32_e32 v2, 16, v100
	v_and_b32_e32 v3, 0xffff0000, v100
	v_lshlrev_b32_e32 v103, 16, v101
	v_and_b32_e32 v102, 0xffff0000, v101
	v_pk_fma_f32 v[2:3], v[142:143], v[50:51], v[2:3] neg_lo:[1,0,0] neg_hi:[1,0,0]
	v_pk_fma_f32 v[18:19], v[142:143], v[18:19], v[102:103] neg_lo:[1,0,0] neg_hi:[1,0,0]
	v_pk_mul_f32 v[50:51], v[2:3], v[2:3]
	v_pk_mul_f32 v[34:35], v[18:19], v[18:19]
	v_add_f32_e32 v50, v50, v51
	v_add_f32_e32 v35, v50, v35
	v_add_f32_e32 v34, v34, v35
	s_waitcnt lgkmcnt(0)
	s_nop 1
	v_add_f32_dpp v34, v34, v34 quad_perm:[1,0,3,2] row_mask:0xf bank_mask:0xf
	s_waitcnt lgkmcnt(0)
	s_nop 1
	v_add_f32_dpp v34, v34, v34 quad_perm:[2,3,0,1] row_mask:0xf bank_mask:0xf
	s_waitcnt lgkmcnt(0)
	s_nop 1
	v_add_f32_dpp v34, v34, v34 row_half_mirror row_mask:0xf bank_mask:0xf
	s_waitcnt lgkmcnt(0)
	s_nop 1
	v_add_f32_dpp v34, v34, v34 row_mirror row_mask:0xf bank_mask:0xf
	ds_bpermute_b32 v35, v170, v34
	s_waitcnt lgkmcnt(0)
	v_add_f32_e32 v34, v34, v35
	v_fmamk_f32 v34, v34, 0x3c000000, v249
	v_mul_f32_e32 v35, 0x4b800000, v34
	v_cmp_gt_f32_e32 vcc, s10, v34
	s_nop 1
	v_cndmask_b32_e32 v34, v34, v35, vcc
	v_rsq_f32_e32 v34, v34
	s_nop 0
	v_mul_f32_e32 v35, 0x45800000, v34
	v_cndmask_b32_e32 v34, v34, v35, vcc
	v_mul_f32_e32 v2, v2, v34
	v_mul_f32_e32 v3, v3, v34
	v_mul_f32_e32 v19, v19, v34
	v_mul_f32_e32 v18, v18, v34
	v_mul_f32_e32 v2, v69, v2
	v_mul_f32_e32 v3, v71, v3
	v_mul_f32_e32 v19, v73, v19
	v_mul_f32_e32 v18, v77, v18
	v_cvt_pk_bf16_f32 v2, v2, s0
	v_cvt_pk_bf16_f32 v3, v3, s0
	v_cvt_pk_bf16_f32 v19, v19, s0
	v_cvt_pk_bf16_f32 v18, v18, s0
	ds_write_b16 v74, v2 offset:272
	ds_write_b16 v74, v3 offset:336
	ds_write_b16 v74, v19 offset:400
	ds_write_b16 v74, v18 offset:464
	ds_read2st64_b32 v[2:3], v79 offset0:4 offset1:5
	v_mov_b32_e32 v18, v4
	v_mov_b32_e32 v19, v52
	s_waitcnt lgkmcnt(0)
	v_lshlrev_b32_e32 v34, 16, v2
	v_and_b32_e32 v35, 0xffff0000, v2
	v_lshlrev_b32_e32 v51, 16, v3
	v_and_b32_e32 v50, 0xffff0000, v3
	v_pk_mul_f32 v[2:3], v[18:19], v[96:97] op_sel_hi:[1,0]
	s_nop 0
	v_pk_fma_f32 v[2:3], v[142:143], v[2:3], v[34:35] neg_lo:[1,0,0] neg_hi:[1,0,0]
	v_mov_b32_e32 v34, v36
	v_mov_b32_e32 v35, v20
	v_pk_mul_f32 v[34:35], v[34:35], v[96:97] op_sel_hi:[1,0]
	v_pk_mul_f32 v[18:19], v[2:3], v[2:3]
	v_pk_fma_f32 v[34:35], v[142:143], v[34:35], v[50:51] neg_lo:[1,0,0] neg_hi:[1,0,0]
	v_add_f32_e32 v4, v18, v19
	v_pk_mul_f32 v[50:51], v[34:35], v[34:35]
	s_nop 0
	v_add_f32_e32 v4, v4, v51
	v_add_f32_e32 v4, v50, v4
	s_waitcnt lgkmcnt(0)
	s_nop 1
	v_add_f32_dpp v4, v4, v4 quad_perm:[1,0,3,2] row_mask:0xf bank_mask:0xf
	s_waitcnt lgkmcnt(0)
	s_nop 1
	v_add_f32_dpp v4, v4, v4 quad_perm:[2,3,0,1] row_mask:0xf bank_mask:0xf
	s_waitcnt lgkmcnt(0)
	s_nop 1
	v_add_f32_dpp v4, v4, v4 row_half_mirror row_mask:0xf bank_mask:0xf
	s_waitcnt lgkmcnt(0)
	s_nop 1
	v_add_f32_dpp v4, v4, v4 row_mirror row_mask:0xf bank_mask:0xf
	ds_bpermute_b32 v18, v170, v4
	s_waitcnt lgkmcnt(0)
	v_add_f32_e32 v4, v4, v18
	v_fmamk_f32 v4, v4, 0x3c000000, v249
	v_mul_f32_e32 v18, 0x4b800000, v4
	v_cmp_gt_f32_e32 vcc, s10, v4
	s_nop 1
	v_cndmask_b32_e32 v4, v4, v18, vcc
	v_rsq_f32_e32 v4, v4
	s_nop 0
	v_mul_f32_e32 v18, 0x45800000, v4
	v_cndmask_b32_e32 v4, v4, v18, vcc
	v_mul_f32_e32 v2, v2, v4
	v_mul_f32_e32 v3, v3, v4
	v_mul_f32_e32 v18, v35, v4
	v_mul_f32_e32 v4, v34, v4
	v_mul_f32_e32 v2, v69, v2
	v_mul_f32_e32 v3, v71, v3
	v_mul_f32_e32 v18, v73, v18
	v_mul_f32_e32 v4, v77, v4
	v_cvt_pk_bf16_f32 v2, v2, s0
	v_cvt_pk_bf16_f32 v3, v3, s0
	v_cvt_pk_bf16_f32 v18, v18, s0
	v_cvt_pk_bf16_f32 v4, v4, s0
	ds_write_b16 v74, v2 offset:544
	ds_write_b16 v74, v3 offset:608
	ds_write_b16 v74, v18 offset:672
	ds_write_b16 v74, v4 offset:736
	ds_read2st64_b32 v[2:3], v79 offset0:6 offset1:7
	v_mov_b32_e32 v52, v5
	v_mov_b32_e32 v20, v37
	s_waitcnt lgkmcnt(0)
	v_lshlrev_b32_e32 v18, 16, v2
	v_and_b32_e32 v19, 0xffff0000, v2
	v_lshlrev_b32_e32 v35, 16, v3
	v_and_b32_e32 v34, 0xffff0000, v3
	v_pk_mul_f32 v[2:3], v[52:53], v[94:95] op_sel_hi:[1,0]
	s_nop 0
	v_pk_fma_f32 v[4:5], v[142:143], v[2:3], v[18:19] neg_lo:[1,0,0] neg_hi:[1,0,0]
	v_pk_mul_f32 v[18:19], v[20:21], v[94:95] op_sel_hi:[1,0]
	v_pk_mul_f32 v[2:3], v[4:5], v[4:5]
	v_pk_fma_f32 v[18:19], v[142:143], v[18:19], v[34:35] neg_lo:[1,0,0] neg_hi:[1,0,0]
	v_add_f32_e32 v2, v2, v3
	v_pk_mul_f32 v[20:21], v[18:19], v[18:19]
	s_nop 0
	v_add_f32_e32 v2, v2, v21
	v_add_f32_e32 v2, v20, v2
	s_waitcnt lgkmcnt(0)
	s_nop 1
	v_add_f32_dpp v2, v2, v2 quad_perm:[1,0,3,2] row_mask:0xf bank_mask:0xf
	s_waitcnt lgkmcnt(0)
	s_nop 1
	v_add_f32_dpp v2, v2, v2 quad_perm:[2,3,0,1] row_mask:0xf bank_mask:0xf
	s_waitcnt lgkmcnt(0)
	s_nop 1
	v_add_f32_dpp v2, v2, v2 row_half_mirror row_mask:0xf bank_mask:0xf
	s_waitcnt lgkmcnt(0)
	s_nop 1
	v_add_f32_dpp v2, v2, v2 row_mirror row_mask:0xf bank_mask:0xf
	ds_bpermute_b32 v3, v170, v2
	s_waitcnt lgkmcnt(0)
	v_add_f32_e32 v2, v2, v3
	v_fmamk_f32 v2, v2, 0x3c000000, v249
	v_cmp_gt_f32_e32 vcc, s10, v2
	v_mul_f32_e32 v3, 0x4b800000, v2
	s_nop 0
	v_cndmask_b32_e32 v2, v2, v3, vcc
	v_rsq_f32_e32 v2, v2
	s_nop 0
	v_mul_f32_e32 v3, 0x45800000, v2
	v_cndmask_b32_e32 v20, v2, v3, vcc
	v_or_b32_e32 v2, 3, v80
	v_mad_u64_u32 v[2:3], s[4:5], v2, s77, v[78:79]
	v_mul_f32_e32 v3, v4, v20
	v_mul_f32_e32 v3, v69, v3
	v_cvt_pk_bf16_f32 v3, v3, s0
	ds_write_b16 v2, v3
	v_mul_f32_e32 v3, v5, v20
	v_mul_f32_e32 v3, v71, v3
	v_cvt_pk_bf16_f32 v3, v3, s0
	ds_write_b16 v2, v3 offset:64
	v_mul_f32_e32 v3, v19, v20
	v_mul_f32_e32 v3, v73, v3
	v_cvt_pk_bf16_f32 v3, v3, s0
	ds_write_b16 v2, v3 offset:128
	v_mul_f32_e32 v3, v18, v20
	v_mul_f32_e32 v3, v77, v3
	v_cvt_pk_bf16_f32 v3, v3, s0
	ds_write_b16 v2, v3 offset:192
	ds_read2st64_b32 v[4:5], v79 offset0:8 offset1:9
	v_mov_b32_e32 v18, v6
	v_mov_b32_e32 v19, v54
	s_waitcnt lgkmcnt(0)
	v_lshlrev_b32_e32 v20, 16, v4
	v_and_b32_e32 v21, 0xffff0000, v4
	v_lshlrev_b32_e32 v35, 16, v5
	v_and_b32_e32 v34, 0xffff0000, v5
	v_pk_mul_f32 v[4:5], v[18:19], v[92:93] op_sel_hi:[1,0]
	s_nop 0
	v_pk_fma_f32 v[4:5], v[142:143], v[4:5], v[20:21] neg_lo:[1,0,0] neg_hi:[1,0,0]
	v_mov_b32_e32 v20, v38
	v_mov_b32_e32 v21, v22
	v_pk_mul_f32 v[20:21], v[20:21], v[92:93] op_sel_hi:[1,0]
	v_pk_mul_f32 v[18:19], v[4:5], v[4:5]
	v_pk_fma_f32 v[20:21], v[142:143], v[20:21], v[34:35] neg_lo:[1,0,0] neg_hi:[1,0,0]
	v_add_f32_e32 v3, v18, v19
	v_pk_mul_f32 v[34:35], v[20:21], v[20:21]
	s_nop 0
	v_add_f32_e32 v3, v3, v35
	v_add_f32_e32 v3, v34, v3
	s_waitcnt lgkmcnt(0)
	s_nop 1
	v_add_f32_dpp v3, v3, v3 quad_perm:[1,0,3,2] row_mask:0xf bank_mask:0xf
	s_waitcnt lgkmcnt(0)
	s_nop 1
	v_add_f32_dpp v3, v3, v3 quad_perm:[2,3,0,1] row_mask:0xf bank_mask:0xf
	s_waitcnt lgkmcnt(0)
	s_nop 1
	v_add_f32_dpp v3, v3, v3 row_half_mirror row_mask:0xf bank_mask:0xf
	s_waitcnt lgkmcnt(0)
	s_nop 1
	v_add_f32_dpp v3, v3, v3 row_mirror row_mask:0xf bank_mask:0xf
	ds_bpermute_b32 v6, v170, v3
	s_waitcnt lgkmcnt(0)
	v_add_f32_e32 v3, v3, v6
	v_fmamk_f32 v3, v3, 0x3c000000, v249
	v_mul_f32_e32 v6, 0x4b800000, v3
	v_cmp_gt_f32_e32 vcc, s10, v3
	s_nop 1
	v_cndmask_b32_e32 v3, v3, v6, vcc
	v_rsq_f32_e32 v3, v3
	s_nop 0
	v_mul_f32_e32 v6, 0x45800000, v3
	v_cndmask_b32_e32 v3, v3, v6, vcc
	v_mul_f32_e32 v4, v4, v3
	v_mul_f32_e32 v5, v5, v3
	v_mul_f32_e32 v6, v21, v3
	v_mul_f32_e32 v3, v20, v3
	v_mul_f32_e32 v4, v69, v4
	v_mul_f32_e32 v5, v71, v5
	v_mul_f32_e32 v6, v73, v6
	v_mul_f32_e32 v3, v77, v3
	v_cvt_pk_bf16_f32 v4, v4, s0
	v_cvt_pk_bf16_f32 v5, v5, s0
	v_cvt_pk_bf16_f32 v6, v6, s0
	v_cvt_pk_bf16_f32 v3, v3, s0
	ds_write_b16 v74, v4 offset:2176
	ds_write_b16 v74, v5 offset:2240
	ds_write_b16 v74, v6 offset:2304
	ds_write_b16 v74, v3 offset:2368
	ds_read2st64_b32 v[4:5], v79 offset0:10 offset1:11
	v_mov_b32_e32 v54, v7
	v_mov_b32_e32 v22, v39
	v_pk_mul_f32 v[20:21], v[22:23], v[90:91] op_sel_hi:[1,0]
	s_waitcnt lgkmcnt(0)
	v_lshlrev_b32_e32 v6, 16, v4
	v_and_b32_e32 v7, 0xffff0000, v4
	v_lshlrev_b32_e32 v19, 16, v5
	v_and_b32_e32 v18, 0xffff0000, v5
	v_pk_mul_f32 v[4:5], v[54:55], v[90:91] op_sel_hi:[1,0]
	v_pk_fma_f32 v[18:19], v[142:143], v[20:21], v[18:19] neg_lo:[1,0,0] neg_hi:[1,0,0]
	v_pk_fma_f32 v[4:5], v[142:143], v[4:5], v[6:7] neg_lo:[1,0,0] neg_hi:[1,0,0]
	v_pk_mul_f32 v[20:21], v[18:19], v[18:19]
	v_pk_mul_f32 v[6:7], v[4:5], v[4:5]
	s_nop 0
	v_add_f32_e32 v3, v6, v7
	v_add_f32_e32 v3, v3, v21
	v_add_f32_e32 v3, v20, v3
	s_waitcnt lgkmcnt(0)
	s_nop 1
	v_add_f32_dpp v3, v3, v3 quad_perm:[1,0,3,2] row_mask:0xf bank_mask:0xf
	s_waitcnt lgkmcnt(0)
	s_nop 1
	v_add_f32_dpp v3, v3, v3 quad_perm:[2,3,0,1] row_mask:0xf bank_mask:0xf
	s_waitcnt lgkmcnt(0)
	s_nop 1
	v_add_f32_dpp v3, v3, v3 row_half_mirror row_mask:0xf bank_mask:0xf
	s_waitcnt lgkmcnt(0)
	s_nop 1
	v_add_f32_dpp v3, v3, v3 row_mirror row_mask:0xf bank_mask:0xf
	ds_bpermute_b32 v6, v170, v3
	s_waitcnt lgkmcnt(0)
	v_add_f32_e32 v3, v3, v6
	v_fmamk_f32 v3, v3, 0x3c000000, v249
	v_mul_f32_e32 v6, 0x4b800000, v3
	v_cmp_gt_f32_e32 vcc, s10, v3
	s_nop 1
	v_cndmask_b32_e32 v3, v3, v6, vcc
	v_rsq_f32_e32 v3, v3
	s_nop 0
	v_mul_f32_e32 v6, 0x45800000, v3
	v_cndmask_b32_e32 v3, v3, v6, vcc
	v_mul_f32_e32 v4, v4, v3
	v_mul_f32_e32 v5, v5, v3
	v_mul_f32_e32 v6, v19, v3
	v_mul_f32_e32 v3, v18, v3
	v_mul_f32_e32 v4, v69, v4
	v_mul_f32_e32 v5, v71, v5
	v_mul_f32_e32 v6, v73, v6
	v_mul_f32_e32 v3, v77, v3
	v_cvt_pk_bf16_f32 v4, v4, s0
	v_cvt_pk_bf16_f32 v5, v5, s0
	v_cvt_pk_bf16_f32 v6, v6, s0
	v_cvt_pk_bf16_f32 v3, v3, s0
	ds_write_b16 v74, v4 offset:2448
	ds_write_b16 v74, v5 offset:2512
	ds_write_b16 v74, v6 offset:2576
	ds_write_b16 v74, v3 offset:2640
	ds_read2st64_b32 v[4:5], v79 offset0:12 offset1:13
	v_mov_b32_e32 v6, v8
	v_mov_b32_e32 v7, v56
	s_waitcnt lgkmcnt(0)
	v_lshlrev_b32_e32 v18, 16, v4
	v_and_b32_e32 v19, 0xffff0000, v4
	v_lshlrev_b32_e32 v21, 16, v5
	v_and_b32_e32 v20, 0xffff0000, v5
	v_pk_mul_f32 v[4:5], v[6:7], v[88:89] op_sel_hi:[1,0]
	s_nop 0
	v_pk_fma_f32 v[4:5], v[142:143], v[4:5], v[18:19] neg_lo:[1,0,0] neg_hi:[1,0,0]
	v_mov_b32_e32 v18, v40
	v_mov_b32_e32 v19, v24
	v_pk_mul_f32 v[18:19], v[18:19], v[88:89] op_sel_hi:[1,0]
	v_pk_mul_f32 v[6:7], v[4:5], v[4:5]
	v_pk_fma_f32 v[18:19], v[142:143], v[18:19], v[20:21] neg_lo:[1,0,0] neg_hi:[1,0,0]
	v_add_f32_e32 v3, v6, v7
	v_pk_mul_f32 v[20:21], v[18:19], v[18:19]
	s_nop 0
	v_add_f32_e32 v3, v3, v21
	v_add_f32_e32 v3, v20, v3
	s_waitcnt lgkmcnt(0)
	s_nop 1
	v_add_f32_dpp v3, v3, v3 quad_perm:[1,0,3,2] row_mask:0xf bank_mask:0xf
	s_waitcnt lgkmcnt(0)
	s_nop 1
	v_add_f32_dpp v3, v3, v3 quad_perm:[2,3,0,1] row_mask:0xf bank_mask:0xf
	s_waitcnt lgkmcnt(0)
	s_nop 1
	v_add_f32_dpp v3, v3, v3 row_half_mirror row_mask:0xf bank_mask:0xf
	s_waitcnt lgkmcnt(0)
	s_nop 1
	v_add_f32_dpp v3, v3, v3 row_mirror row_mask:0xf bank_mask:0xf
	ds_bpermute_b32 v6, v170, v3
	s_waitcnt lgkmcnt(0)
	v_add_f32_e32 v3, v3, v6
	v_fmamk_f32 v3, v3, 0x3c000000, v249
	v_mul_f32_e32 v6, 0x4b800000, v3
	v_cmp_gt_f32_e32 vcc, s10, v3
	s_nop 1
	v_cndmask_b32_e32 v3, v3, v6, vcc
	v_rsq_f32_e32 v3, v3
	s_nop 0
	v_mul_f32_e32 v6, 0x45800000, v3
	v_cndmask_b32_e32 v3, v3, v6, vcc
	v_mul_f32_e32 v4, v4, v3
	v_mul_f32_e32 v5, v5, v3
	v_mul_f32_e32 v6, v19, v3
	v_mul_f32_e32 v3, v18, v3
	v_mul_f32_e32 v4, v69, v4
	v_mul_f32_e32 v5, v71, v5
	v_mul_f32_e32 v6, v73, v6
	v_mul_f32_e32 v3, v77, v3
	v_cvt_pk_bf16_f32 v4, v4, s0
	v_cvt_pk_bf16_f32 v5, v5, s0
	v_cvt_pk_bf16_f32 v6, v6, s0
	v_cvt_pk_bf16_f32 v3, v3, s0
	ds_write_b16 v74, v4 offset:2720
	ds_write_b16 v74, v5 offset:2784
	ds_write_b16 v74, v6 offset:2848
	ds_write_b16 v74, v3 offset:2912
	ds_read2st64_b32 v[4:5], v79 offset0:14 offset1:15
	v_mov_b32_e32 v56, v9
	v_mov_b32_e32 v24, v41
	v_pk_mul_f32 v[18:19], v[24:25], v[86:87] op_sel_hi:[1,0]
	s_waitcnt lgkmcnt(0)
	v_lshlrev_b32_e32 v6, 16, v4
	v_and_b32_e32 v7, 0xffff0000, v4
	v_lshlrev_b32_e32 v9, 16, v5
	v_and_b32_e32 v8, 0xffff0000, v5
	v_pk_mul_f32 v[4:5], v[56:57], v[86:87] op_sel_hi:[1,0]
	v_pk_fma_f32 v[8:9], v[142:143], v[18:19], v[8:9] neg_lo:[1,0,0] neg_hi:[1,0,0]
	v_pk_fma_f32 v[4:5], v[142:143], v[4:5], v[6:7] neg_lo:[1,0,0] neg_hi:[1,0,0]
	v_pk_mul_f32 v[18:19], v[8:9], v[8:9]
	v_pk_mul_f32 v[6:7], v[4:5], v[4:5]
	s_nop 0
	v_add_f32_e32 v3, v6, v7
	v_add_f32_e32 v3, v3, v19
	v_add_f32_e32 v3, v18, v3
	s_waitcnt lgkmcnt(0)
	s_nop 1
	v_add_f32_dpp v3, v3, v3 quad_perm:[1,0,3,2] row_mask:0xf bank_mask:0xf
	s_waitcnt lgkmcnt(0)
	s_nop 1
	v_add_f32_dpp v3, v3, v3 quad_perm:[2,3,0,1] row_mask:0xf bank_mask:0xf
	s_waitcnt lgkmcnt(0)
	s_nop 1
	v_add_f32_dpp v3, v3, v3 row_half_mirror row_mask:0xf bank_mask:0xf
	s_waitcnt lgkmcnt(0)
	s_nop 1
	v_add_f32_dpp v3, v3, v3 row_mirror row_mask:0xf bank_mask:0xf
	ds_bpermute_b32 v6, v170, v3
	s_waitcnt lgkmcnt(0)
	v_add_f32_e32 v3, v3, v6
	v_fmamk_f32 v3, v3, 0x3c000000, v249
	v_mul_f32_e32 v6, 0x4b800000, v3
	v_cmp_gt_f32_e32 vcc, s10, v3
	s_nop 1
	v_cndmask_b32_e32 v3, v3, v6, vcc
	v_rsq_f32_e32 v3, v3
	s_nop 0
	v_mul_f32_e32 v6, 0x45800000, v3
	v_cndmask_b32_e32 v3, v3, v6, vcc
	v_mul_f32_e32 v4, v4, v3
	v_mul_f32_e32 v5, v5, v3
	v_mul_f32_e32 v6, v9, v3
	v_mul_f32_e32 v3, v8, v3
	v_mul_f32_e32 v4, v69, v4
	v_mul_f32_e32 v5, v71, v5
	v_mul_f32_e32 v6, v73, v6
	v_mul_f32_e32 v3, v77, v3
	v_cvt_pk_bf16_f32 v4, v4, s0
	v_cvt_pk_bf16_f32 v5, v5, s0
	v_cvt_pk_bf16_f32 v6, v6, s0
	v_cvt_pk_bf16_f32 v3, v3, s0
	ds_write_b16 v2, v4 offset:2176
	ds_write_b16 v2, v5 offset:2240
	ds_write_b16 v2, v6 offset:2304
	ds_write_b16 v2, v3 offset:2368
	ds_read2st64_b32 v[4:5], v79 offset0:16 offset1:17
	v_mov_b32_e32 v6, v10
	v_mov_b32_e32 v7, v58
	s_waitcnt lgkmcnt(0)
	v_lshlrev_b32_e32 v8, 16, v4
	v_and_b32_e32 v9, 0xffff0000, v4
	v_lshlrev_b32_e32 v19, 16, v5
	v_and_b32_e32 v18, 0xffff0000, v5
	v_pk_mul_f32 v[4:5], v[6:7], v[84:85] op_sel_hi:[1,0]
	s_nop 0
	v_pk_fma_f32 v[4:5], v[142:143], v[4:5], v[8:9] neg_lo:[1,0,0] neg_hi:[1,0,0]
	v_mov_b32_e32 v8, v42
	v_mov_b32_e32 v9, v26
	v_pk_mul_f32 v[8:9], v[8:9], v[84:85] op_sel_hi:[1,0]
	v_pk_mul_f32 v[6:7], v[4:5], v[4:5]
	v_pk_fma_f32 v[8:9], v[142:143], v[8:9], v[18:19] neg_lo:[1,0,0] neg_hi:[1,0,0]
	v_add_f32_e32 v3, v6, v7
	v_pk_mul_f32 v[18:19], v[8:9], v[8:9]
	s_nop 0
	v_add_f32_e32 v3, v3, v19
	v_add_f32_e32 v3, v18, v3
	s_waitcnt lgkmcnt(0)
	s_nop 1
	v_add_f32_dpp v3, v3, v3 quad_perm:[1,0,3,2] row_mask:0xf bank_mask:0xf
	s_waitcnt lgkmcnt(0)
	s_nop 1
	v_add_f32_dpp v3, v3, v3 quad_perm:[2,3,0,1] row_mask:0xf bank_mask:0xf
	s_waitcnt lgkmcnt(0)
	s_nop 1
	v_add_f32_dpp v3, v3, v3 row_half_mirror row_mask:0xf bank_mask:0xf
	s_waitcnt lgkmcnt(0)
	s_nop 1
	v_add_f32_dpp v3, v3, v3 row_mirror row_mask:0xf bank_mask:0xf
	ds_bpermute_b32 v6, v170, v3
	s_waitcnt lgkmcnt(0)
	v_add_f32_e32 v3, v3, v6
	v_fmamk_f32 v3, v3, 0x3c000000, v249
	v_mul_f32_e32 v6, 0x4b800000, v3
	v_cmp_gt_f32_e32 vcc, s10, v3
	s_nop 1
	v_cndmask_b32_e32 v3, v3, v6, vcc
	v_rsq_f32_e32 v3, v3
	s_nop 0
	v_mul_f32_e32 v6, 0x45800000, v3
	v_cndmask_b32_e32 v3, v3, v6, vcc
	v_mul_f32_e32 v4, v4, v3
	v_mul_f32_e32 v5, v5, v3
	v_mul_f32_e32 v6, v9, v3
	v_mul_f32_e32 v3, v8, v3
	v_mul_f32_e32 v4, v69, v4
	v_mul_f32_e32 v5, v71, v5
	v_mul_f32_e32 v6, v73, v6
	v_mul_f32_e32 v3, v77, v3
	v_cvt_pk_bf16_f32 v4, v4, s0
	v_cvt_pk_bf16_f32 v5, v5, s0
	v_cvt_pk_bf16_f32 v6, v6, s0
	v_cvt_pk_bf16_f32 v3, v3, s0
	ds_write_b16 v74, v4 offset:4352
	ds_write_b16 v74, v5 offset:4416
	ds_write_b16 v74, v6 offset:4480
	ds_write_b16 v74, v3 offset:4544
	ds_read2st64_b32 v[4:5], v79 offset0:18 offset1:19
	v_mov_b32_e32 v58, v11
	v_mov_b32_e32 v26, v43
	v_pk_mul_f32 v[10:11], v[26:27], v[82:83] op_sel_hi:[1,0]
	s_waitcnt lgkmcnt(0)
	v_lshlrev_b32_e32 v6, 16, v4
	v_and_b32_e32 v7, 0xffff0000, v4
	v_lshlrev_b32_e32 v9, 16, v5
	v_and_b32_e32 v8, 0xffff0000, v5
	v_pk_mul_f32 v[4:5], v[58:59], v[82:83] op_sel_hi:[1,0]
	v_pk_fma_f32 v[8:9], v[142:143], v[10:11], v[8:9] neg_lo:[1,0,0] neg_hi:[1,0,0]
	v_pk_fma_f32 v[4:5], v[142:143], v[4:5], v[6:7] neg_lo:[1,0,0] neg_hi:[1,0,0]
	v_pk_mul_f32 v[10:11], v[8:9], v[8:9]
	v_pk_mul_f32 v[6:7], v[4:5], v[4:5]
	s_nop 0
	v_add_f32_e32 v3, v6, v7
	v_add_f32_e32 v3, v3, v11
	v_add_f32_e32 v3, v10, v3
	s_waitcnt lgkmcnt(0)
	s_nop 1
	v_add_f32_dpp v3, v3, v3 quad_perm:[1,0,3,2] row_mask:0xf bank_mask:0xf
	s_waitcnt lgkmcnt(0)
	s_nop 1
	v_add_f32_dpp v3, v3, v3 quad_perm:[2,3,0,1] row_mask:0xf bank_mask:0xf
	s_waitcnt lgkmcnt(0)
	s_nop 1
	v_add_f32_dpp v3, v3, v3 row_half_mirror row_mask:0xf bank_mask:0xf
	s_waitcnt lgkmcnt(0)
	s_nop 1
	v_add_f32_dpp v3, v3, v3 row_mirror row_mask:0xf bank_mask:0xf
	ds_bpermute_b32 v6, v170, v3
	s_waitcnt lgkmcnt(0)
	v_add_f32_e32 v3, v3, v6
	v_fmamk_f32 v3, v3, 0x3c000000, v249
	v_mul_f32_e32 v6, 0x4b800000, v3
	v_cmp_gt_f32_e32 vcc, s10, v3
	s_nop 1
	v_cndmask_b32_e32 v3, v3, v6, vcc
	v_rsq_f32_e32 v3, v3
	s_nop 0
	v_mul_f32_e32 v6, 0x45800000, v3
	v_cndmask_b32_e32 v3, v3, v6, vcc
	v_mul_f32_e32 v4, v4, v3
	v_mul_f32_e32 v5, v5, v3
	v_mul_f32_e32 v6, v9, v3
	v_mul_f32_e32 v3, v8, v3
	v_mul_f32_e32 v4, v69, v4
	v_mul_f32_e32 v5, v71, v5
	v_mul_f32_e32 v6, v73, v6
	v_mul_f32_e32 v3, v77, v3
	v_cvt_pk_bf16_f32 v4, v4, s0
	v_cvt_pk_bf16_f32 v5, v5, s0
	v_cvt_pk_bf16_f32 v6, v6, s0
	v_cvt_pk_bf16_f32 v3, v3, s0
	ds_write_b16 v74, v4 offset:4624
	ds_write_b16 v74, v5 offset:4688
	ds_write_b16 v74, v6 offset:4752
	ds_write_b16 v74, v3 offset:4816
	ds_read2st64_b32 v[4:5], v79 offset0:20 offset1:21
	v_mov_b32_e32 v6, v12
	v_mov_b32_e32 v7, v60
	s_waitcnt lgkmcnt(0)
	v_lshlrev_b32_e32 v8, 16, v4
	v_and_b32_e32 v9, 0xffff0000, v4
	v_lshlrev_b32_e32 v11, 16, v5
	v_and_b32_e32 v10, 0xffff0000, v5
	v_pk_mul_f32 v[4:5], v[6:7], v[76:77] op_sel_hi:[1,0]
	s_nop 0
	v_pk_fma_f32 v[4:5], v[142:143], v[4:5], v[8:9] neg_lo:[1,0,0] neg_hi:[1,0,0]
	v_mov_b32_e32 v8, v44
	v_mov_b32_e32 v9, v28
	v_pk_mul_f32 v[8:9], v[8:9], v[76:77] op_sel_hi:[1,0]
	v_pk_mul_f32 v[6:7], v[4:5], v[4:5]
	v_pk_fma_f32 v[8:9], v[142:143], v[8:9], v[10:11] neg_lo:[1,0,0] neg_hi:[1,0,0]
	v_add_f32_e32 v3, v6, v7
	v_pk_mul_f32 v[10:11], v[8:9], v[8:9]
	s_nop 0
	v_add_f32_e32 v3, v3, v11
	v_add_f32_e32 v3, v10, v3
	s_waitcnt lgkmcnt(0)
	s_nop 1
	v_add_f32_dpp v3, v3, v3 quad_perm:[1,0,3,2] row_mask:0xf bank_mask:0xf
	s_waitcnt lgkmcnt(0)
	s_nop 1
	v_add_f32_dpp v3, v3, v3 quad_perm:[2,3,0,1] row_mask:0xf bank_mask:0xf
	s_waitcnt lgkmcnt(0)
	s_nop 1
	v_add_f32_dpp v3, v3, v3 row_half_mirror row_mask:0xf bank_mask:0xf
	s_waitcnt lgkmcnt(0)
	s_nop 1
	v_add_f32_dpp v3, v3, v3 row_mirror row_mask:0xf bank_mask:0xf
	ds_bpermute_b32 v6, v170, v3
	s_waitcnt lgkmcnt(0)
	v_add_f32_e32 v3, v3, v6
	v_fmamk_f32 v3, v3, 0x3c000000, v249
	v_mul_f32_e32 v6, 0x4b800000, v3
	v_cmp_gt_f32_e32 vcc, s10, v3
	s_nop 1
	v_cndmask_b32_e32 v3, v3, v6, vcc
	v_rsq_f32_e32 v3, v3
	s_nop 0
	v_mul_f32_e32 v6, 0x45800000, v3
	v_cndmask_b32_e32 v3, v3, v6, vcc
	v_mul_f32_e32 v4, v4, v3
	v_mul_f32_e32 v5, v5, v3
	v_mul_f32_e32 v6, v9, v3
	v_mul_f32_e32 v3, v8, v3
	v_mul_f32_e32 v4, v69, v4
	v_mul_f32_e32 v5, v71, v5
	v_mul_f32_e32 v6, v73, v6
	v_mul_f32_e32 v3, v77, v3
	v_cvt_pk_bf16_f32 v4, v4, s0
	v_cvt_pk_bf16_f32 v5, v5, s0
	v_cvt_pk_bf16_f32 v6, v6, s0
	v_cvt_pk_bf16_f32 v3, v3, s0
	ds_write_b16 v74, v4 offset:4896
	ds_write_b16 v74, v5 offset:4960
	ds_write_b16 v74, v6 offset:5024
	ds_write_b16 v74, v3 offset:5088
	ds_read2st64_b32 v[4:5], v79 offset0:22 offset1:23
	v_mov_b32_e32 v60, v13
	v_mov_b32_e32 v28, v45
	v_pk_mul_f32 v[10:11], v[28:29], v[72:73] op_sel_hi:[1,0]
	s_waitcnt lgkmcnt(0)
	v_lshlrev_b32_e32 v6, 16, v4
	v_and_b32_e32 v7, 0xffff0000, v4
	v_lshlrev_b32_e32 v9, 16, v5
	v_and_b32_e32 v8, 0xffff0000, v5
	v_pk_mul_f32 v[4:5], v[60:61], v[72:73] op_sel_hi:[1,0]
	v_pk_fma_f32 v[8:9], v[142:143], v[10:11], v[8:9] neg_lo:[1,0,0] neg_hi:[1,0,0]
	v_pk_fma_f32 v[4:5], v[142:143], v[4:5], v[6:7] neg_lo:[1,0,0] neg_hi:[1,0,0]
	v_pk_mul_f32 v[10:11], v[8:9], v[8:9]
	v_pk_mul_f32 v[6:7], v[4:5], v[4:5]
	s_nop 0
	v_add_f32_e32 v3, v6, v7
	v_add_f32_e32 v3, v3, v11
	v_add_f32_e32 v3, v10, v3
	s_waitcnt lgkmcnt(0)
	s_nop 1
	v_add_f32_dpp v3, v3, v3 quad_perm:[1,0,3,2] row_mask:0xf bank_mask:0xf
	s_waitcnt lgkmcnt(0)
	s_nop 1
	v_add_f32_dpp v3, v3, v3 quad_perm:[2,3,0,1] row_mask:0xf bank_mask:0xf
	s_waitcnt lgkmcnt(0)
	s_nop 1
	v_add_f32_dpp v3, v3, v3 row_half_mirror row_mask:0xf bank_mask:0xf
	s_waitcnt lgkmcnt(0)
	s_nop 1
	v_add_f32_dpp v3, v3, v3 row_mirror row_mask:0xf bank_mask:0xf
	ds_bpermute_b32 v6, v170, v3
	s_waitcnt lgkmcnt(0)
	v_add_f32_e32 v3, v3, v6
	v_fmamk_f32 v3, v3, 0x3c000000, v249
	v_mul_f32_e32 v6, 0x4b800000, v3
	v_cmp_gt_f32_e32 vcc, s10, v3
	s_nop 1
	v_cndmask_b32_e32 v3, v3, v6, vcc
	v_rsq_f32_e32 v3, v3
	s_nop 0
	v_mul_f32_e32 v6, 0x45800000, v3
	v_cndmask_b32_e32 v3, v3, v6, vcc
	v_mul_f32_e32 v4, v4, v3
	v_mul_f32_e32 v5, v5, v3
	v_mul_f32_e32 v6, v9, v3
	v_mul_f32_e32 v3, v8, v3
	v_mul_f32_e32 v4, v69, v4
	v_mul_f32_e32 v5, v71, v5
	v_mul_f32_e32 v6, v73, v6
	v_mul_f32_e32 v3, v77, v3
	v_cvt_pk_bf16_f32 v4, v4, s0
	v_cvt_pk_bf16_f32 v5, v5, s0
	v_cvt_pk_bf16_f32 v6, v6, s0
	v_cvt_pk_bf16_f32 v3, v3, s0
	ds_write_b16 v2, v4 offset:4352
	ds_write_b16 v2, v5 offset:4416
	ds_write_b16 v2, v6 offset:4480
	ds_write_b16 v2, v3 offset:4544
	ds_read2st64_b32 v[4:5], v79 offset0:24 offset1:25
	v_mov_b32_e32 v6, v14
	v_mov_b32_e32 v7, v62
	s_waitcnt lgkmcnt(0)
	v_lshlrev_b32_e32 v8, 16, v4
	v_and_b32_e32 v9, 0xffff0000, v4
	v_lshlrev_b32_e32 v11, 16, v5
	v_and_b32_e32 v10, 0xffff0000, v5
	v_pk_mul_f32 v[4:5], v[6:7], v[70:71] op_sel_hi:[1,0]
	s_nop 0
	v_pk_fma_f32 v[4:5], v[142:143], v[4:5], v[8:9] neg_lo:[1,0,0] neg_hi:[1,0,0]
	v_mov_b32_e32 v8, v46
	v_mov_b32_e32 v9, v30
	v_pk_mul_f32 v[8:9], v[8:9], v[70:71] op_sel_hi:[1,0]
	v_pk_mul_f32 v[6:7], v[4:5], v[4:5]
	v_pk_fma_f32 v[8:9], v[142:143], v[8:9], v[10:11] neg_lo:[1,0,0] neg_hi:[1,0,0]
	v_add_f32_e32 v3, v6, v7
	v_pk_mul_f32 v[10:11], v[8:9], v[8:9]
	s_nop 0
	v_add_f32_e32 v3, v3, v11
	v_add_f32_e32 v3, v10, v3
	s_waitcnt lgkmcnt(0)
	s_nop 1
	v_add_f32_dpp v3, v3, v3 quad_perm:[1,0,3,2] row_mask:0xf bank_mask:0xf
	s_waitcnt lgkmcnt(0)
	s_nop 1
	v_add_f32_dpp v3, v3, v3 quad_perm:[2,3,0,1] row_mask:0xf bank_mask:0xf
	s_waitcnt lgkmcnt(0)
	s_nop 1
	v_add_f32_dpp v3, v3, v3 row_half_mirror row_mask:0xf bank_mask:0xf
	s_waitcnt lgkmcnt(0)
	s_nop 1
	v_add_f32_dpp v3, v3, v3 row_mirror row_mask:0xf bank_mask:0xf
	ds_bpermute_b32 v6, v170, v3
	s_waitcnt lgkmcnt(0)
	v_add_f32_e32 v3, v3, v6
	v_fmamk_f32 v3, v3, 0x3c000000, v249
	v_mul_f32_e32 v6, 0x4b800000, v3
	v_cmp_gt_f32_e32 vcc, s10, v3
	s_nop 1
	v_cndmask_b32_e32 v3, v3, v6, vcc
	v_rsq_f32_e32 v3, v3
	s_nop 0
	v_mul_f32_e32 v6, 0x45800000, v3
	v_cndmask_b32_e32 v3, v3, v6, vcc
	v_mul_f32_e32 v4, v4, v3
	v_mul_f32_e32 v5, v5, v3
	v_mul_f32_e32 v6, v9, v3
	v_mul_f32_e32 v3, v8, v3
	v_mul_f32_e32 v4, v69, v4
	v_mul_f32_e32 v5, v71, v5
	v_mul_f32_e32 v6, v73, v6
	v_mul_f32_e32 v3, v77, v3
	v_cvt_pk_bf16_f32 v4, v4, s0
	v_cvt_pk_bf16_f32 v5, v5, s0
	v_cvt_pk_bf16_f32 v6, v6, s0
	v_cvt_pk_bf16_f32 v3, v3, s0
	ds_write_b16 v74, v4 offset:6528
	ds_write_b16 v74, v5 offset:6592
	ds_write_b16 v74, v6 offset:6656
	ds_write_b16 v74, v3 offset:6720
	ds_read2st64_b32 v[4:5], v79 offset0:26 offset1:27
	v_mov_b32_e32 v62, v15
	v_mov_b32_e32 v30, v47
	v_pk_mul_f32 v[10:11], v[30:31], v[68:69] op_sel_hi:[1,0]
	s_waitcnt lgkmcnt(0)
	v_lshlrev_b32_e32 v6, 16, v4
	v_and_b32_e32 v7, 0xffff0000, v4
	v_lshlrev_b32_e32 v9, 16, v5
	v_and_b32_e32 v8, 0xffff0000, v5
	v_pk_mul_f32 v[4:5], v[62:63], v[68:69] op_sel_hi:[1,0]
	v_pk_fma_f32 v[8:9], v[142:143], v[10:11], v[8:9] neg_lo:[1,0,0] neg_hi:[1,0,0]
	v_pk_fma_f32 v[4:5], v[142:143], v[4:5], v[6:7] neg_lo:[1,0,0] neg_hi:[1,0,0]
	v_pk_mul_f32 v[10:11], v[8:9], v[8:9]
	v_pk_mul_f32 v[6:7], v[4:5], v[4:5]
	s_nop 0
	v_add_f32_e32 v3, v6, v7
	v_add_f32_e32 v3, v3, v11
	v_add_f32_e32 v3, v10, v3
	s_waitcnt lgkmcnt(0)
	s_nop 1
	v_add_f32_dpp v3, v3, v3 quad_perm:[1,0,3,2] row_mask:0xf bank_mask:0xf
	s_waitcnt lgkmcnt(0)
	s_nop 1
	v_add_f32_dpp v3, v3, v3 quad_perm:[2,3,0,1] row_mask:0xf bank_mask:0xf
	s_waitcnt lgkmcnt(0)
	s_nop 1
	v_add_f32_dpp v3, v3, v3 row_half_mirror row_mask:0xf bank_mask:0xf
	s_waitcnt lgkmcnt(0)
	s_nop 1
	v_add_f32_dpp v3, v3, v3 row_mirror row_mask:0xf bank_mask:0xf
	ds_bpermute_b32 v6, v170, v3
	s_waitcnt lgkmcnt(0)
	v_add_f32_e32 v3, v3, v6
	v_fmamk_f32 v3, v3, 0x3c000000, v249
	v_mul_f32_e32 v6, 0x4b800000, v3
	v_cmp_gt_f32_e32 vcc, s10, v3
	s_nop 1
	v_cndmask_b32_e32 v3, v3, v6, vcc
	v_rsq_f32_e32 v3, v3
	s_nop 0
	v_mul_f32_e32 v6, 0x45800000, v3
	v_cndmask_b32_e32 v3, v3, v6, vcc
	v_mul_f32_e32 v4, v4, v3
	v_mul_f32_e32 v5, v5, v3
	v_mul_f32_e32 v6, v9, v3
	v_mul_f32_e32 v3, v8, v3
	v_mul_f32_e32 v4, v69, v4
	v_mul_f32_e32 v5, v71, v5
	v_mul_f32_e32 v6, v73, v6
	v_mul_f32_e32 v3, v77, v3
	v_cvt_pk_bf16_f32 v4, v4, s0
	v_cvt_pk_bf16_f32 v5, v5, s0
	v_cvt_pk_bf16_f32 v6, v6, s0
	v_cvt_pk_bf16_f32 v3, v3, s0
	ds_write_b16 v74, v4 offset:6800
	ds_write_b16 v74, v5 offset:6864
	ds_write_b16 v74, v6 offset:6928
	ds_write_b16 v74, v3 offset:6992
	ds_read2st64_b32 v[4:5], v79 offset0:28 offset1:29
	v_mov_b32_e32 v6, v16
	v_mov_b32_e32 v7, v64
	s_waitcnt lgkmcnt(0)
	v_lshlrev_b32_e32 v8, 16, v4
	v_and_b32_e32 v9, 0xffff0000, v4
	v_lshlrev_b32_e32 v11, 16, v5
	v_and_b32_e32 v10, 0xffff0000, v5
	v_pk_mul_f32 v[4:5], v[6:7], v[66:67] op_sel_hi:[1,0]
	s_nop 0
	v_pk_fma_f32 v[4:5], v[142:143], v[4:5], v[8:9] neg_lo:[1,0,0] neg_hi:[1,0,0]
	v_mov_b32_e32 v8, v48
	v_mov_b32_e32 v9, v32
	v_pk_mul_f32 v[8:9], v[8:9], v[66:67] op_sel_hi:[1,0]
	v_pk_mul_f32 v[6:7], v[4:5], v[4:5]
	v_pk_fma_f32 v[8:9], v[142:143], v[8:9], v[10:11] neg_lo:[1,0,0] neg_hi:[1,0,0]
	v_add_f32_e32 v3, v6, v7
	v_pk_mul_f32 v[10:11], v[8:9], v[8:9]
	s_nop 0
	v_add_f32_e32 v3, v3, v11
	v_add_f32_e32 v3, v10, v3
	s_waitcnt lgkmcnt(0)
	s_nop 1
	v_add_f32_dpp v3, v3, v3 quad_perm:[1,0,3,2] row_mask:0xf bank_mask:0xf
	s_waitcnt lgkmcnt(0)
	s_nop 1
	v_add_f32_dpp v3, v3, v3 quad_perm:[2,3,0,1] row_mask:0xf bank_mask:0xf
	s_waitcnt lgkmcnt(0)
	s_nop 1
	v_add_f32_dpp v3, v3, v3 row_half_mirror row_mask:0xf bank_mask:0xf
	s_waitcnt lgkmcnt(0)
	s_nop 1
	v_add_f32_dpp v3, v3, v3 row_mirror row_mask:0xf bank_mask:0xf
	ds_bpermute_b32 v6, v170, v3
	s_waitcnt lgkmcnt(0)
	v_add_f32_e32 v3, v3, v6
	v_fmamk_f32 v3, v3, 0x3c000000, v249
	v_mul_f32_e32 v6, 0x4b800000, v3
	v_cmp_gt_f32_e32 vcc, s10, v3
	s_nop 1
	v_cndmask_b32_e32 v3, v3, v6, vcc
	v_rsq_f32_e32 v3, v3
	s_nop 0
	v_mul_f32_e32 v6, 0x45800000, v3
	v_cndmask_b32_e32 v3, v3, v6, vcc
	v_mul_f32_e32 v4, v4, v3
	v_mul_f32_e32 v5, v5, v3
	v_mul_f32_e32 v6, v9, v3
	v_mul_f32_e32 v3, v8, v3
	v_mul_f32_e32 v4, v69, v4
	v_mul_f32_e32 v5, v71, v5
	v_mul_f32_e32 v6, v73, v6
	v_mul_f32_e32 v3, v77, v3
	v_cvt_pk_bf16_f32 v4, v4, s0
	v_cvt_pk_bf16_f32 v5, v5, s0
	v_cvt_pk_bf16_f32 v6, v6, s0
	v_cvt_pk_bf16_f32 v3, v3, s0
	ds_write_b16 v74, v4 offset:7072
	ds_write_b16 v74, v5 offset:7136
	ds_write_b16 v74, v6 offset:7200
	ds_write_b16 v74, v3 offset:7264
	ds_read2st64_b32 v[4:5], v79 offset0:30 offset1:31
	v_mov_b32_e32 v64, v17
	v_mov_b32_e32 v32, v49
	v_pk_mul_f32 v[10:11], v[32:33], v[0:1] op_sel_hi:[1,0]
	s_waitcnt lgkmcnt(0)
	v_lshlrev_b32_e32 v6, 16, v4
	v_and_b32_e32 v7, 0xffff0000, v4
	v_lshlrev_b32_e32 v9, 16, v5
	v_and_b32_e32 v8, 0xffff0000, v5
	v_pk_mul_f32 v[4:5], v[64:65], v[0:1] op_sel_hi:[1,0]
	v_pk_fma_f32 v[8:9], v[142:143], v[10:11], v[8:9] neg_lo:[1,0,0] neg_hi:[1,0,0]
	v_pk_fma_f32 v[4:5], v[142:143], v[4:5], v[6:7] neg_lo:[1,0,0] neg_hi:[1,0,0]
	v_pk_mul_f32 v[10:11], v[8:9], v[8:9]
	v_pk_mul_f32 v[6:7], v[4:5], v[4:5]
	s_nop 0
	v_add_f32_e32 v0, v6, v7
	v_add_f32_e32 v0, v0, v11
	v_add_f32_e32 v0, v10, v0
	s_waitcnt lgkmcnt(0)
	s_nop 1
	v_add_f32_dpp v0, v0, v0 quad_perm:[1,0,3,2] row_mask:0xf bank_mask:0xf
	s_waitcnt lgkmcnt(0)
	s_nop 1
	v_add_f32_dpp v0, v0, v0 quad_perm:[2,3,0,1] row_mask:0xf bank_mask:0xf
	s_waitcnt lgkmcnt(0)
	s_nop 1
	v_add_f32_dpp v0, v0, v0 row_half_mirror row_mask:0xf bank_mask:0xf
	s_waitcnt lgkmcnt(0)
	s_nop 1
	v_add_f32_dpp v0, v0, v0 row_mirror row_mask:0xf bank_mask:0xf
	ds_bpermute_b32 v3, v170, v0
	s_waitcnt lgkmcnt(0)
	v_add_f32_e32 v0, v0, v3
	v_fmamk_f32 v0, v0, 0x3c000000, v249
	v_mul_f32_e32 v3, 0x4b800000, v0
	v_cmp_gt_f32_e32 vcc, s10, v0
	s_nop 1
	v_cndmask_b32_e32 v0, v0, v3, vcc
	v_rsq_f32_e32 v0, v0
	s_nop 0
	v_mul_f32_e32 v3, 0x45800000, v0
	v_cndmask_b32_e32 v0, v0, v3, vcc
	v_mul_f32_e32 v3, v4, v0
	v_mul_f32_e32 v4, v5, v0
	v_mul_f32_e32 v5, v9, v0
	v_mul_f32_e32 v0, v8, v0
	v_mul_f32_e32 v3, v69, v3
	v_mul_f32_e32 v4, v71, v4
	v_mul_f32_e32 v5, v73, v5
	v_mul_f32_e32 v0, v77, v0
	v_cvt_pk_bf16_f32 v3, v3, s0
	v_cvt_pk_bf16_f32 v4, v4, s0
	v_cvt_pk_bf16_f32 v5, v5, s0
	v_cvt_pk_bf16_f32 v0, v0, s0
	ds_write_b16 v2, v3 offset:6528
	ds_write_b16 v2, v4 offset:6592
	ds_write_b16 v2, v5 offset:6656
	ds_write_b16 v2, v0 offset:6720
	s_add_i32 s4, s1, s60
	s_ashr_i32 s5, s4, 31
	s_lshl_b64 s[4:5], s[4:5], 11
	s_add_u32 s1, s41, s4
	s_addc_u32 s5, s66, s5
	s_add_u32 s4, s1, s61
	v_ashrrev_i32_e32 v6, 4, v172
	v_lshlrev_b32_e32 v0, 4, v172
	s_addc_u32 s5, s5, 0
	v_and_b32_e32 v0, 0xf0, v0
	v_mul_lo_u32 v2, v6, s77
	s_waitcnt lgkmcnt(0)
	v_lshl_add_u64 v[8:9], s[4:5], 0, v[0:1]
	v_add3_u32 v0, v67, v0, v2
	ds_read_b128 v[2:5], v0
	v_ashrrev_i32_e32 v7, 31, v6
	v_lshlrev_b64 v[6:7], 11, v[6:7]
	v_lshl_add_u64 v[6:7], v[8:9], 0, v[6:7]
	v_add_co_u32_e32 v8, vcc, s88, v6
	s_waitcnt lgkmcnt(0)
	global_store_dwordx4 v[6:7], v[2:5], off
	ds_read_b128 v[2:5], v0 offset:1088
	v_addc_co_u32_e32 v9, vcc, 0, v7, vcc
	v_readlane_b32 s1, v253, 61
	s_add_i32 s68, s68, s1
	s_waitcnt lgkmcnt(0)
	global_store_dwordx4 v[8:9], v[2:5], off
	ds_read_b128 v[2:5], v0 offset:2176
	v_add_co_u32_e32 v8, vcc, s14, v6
	v_readlane_b32 s1, v253, 63
	s_nop 0
	v_addc_co_u32_e32 v9, vcc, 0, v7, vcc
	s_waitcnt lgkmcnt(0)
	global_store_dwordx4 v[8:9], v[2:5], off
	ds_read_b128 v[2:5], v0 offset:3264
	v_add_co_u32_e32 v8, vcc, s89, v6
	s_add_i32 s69, s69, s90
	s_nop 0
	v_addc_co_u32_e32 v9, vcc, 0, v7, vcc
	s_waitcnt lgkmcnt(0)
	global_store_dwordx4 v[8:9], v[2:5], off
	ds_read_b128 v[2:5], v0 offset:4352
	v_add_co_u32_e32 v8, vcc, s81, v6
	s_add_i32 s67, s67, s1
	s_nop 0
	v_addc_co_u32_e32 v9, vcc, 0, v7, vcc
	s_waitcnt lgkmcnt(0)
	global_store_dwordx4 v[8:9], v[2:5], off
	ds_read_b128 v[2:5], v0 offset:5440
	v_add_co_u32_e32 v8, vcc, s20, v6
	s_cmpk_gt_i32 s69, 0xff
	s_nop 0
	v_addc_co_u32_e32 v9, vcc, 0, v7, vcc
	s_waitcnt lgkmcnt(0)
	global_store_dwordx4 v[8:9], v[2:5], off
	ds_read_b128 v[2:5], v0 offset:6528
	v_add_co_u32_e32 v8, vcc, s18, v6
	s_nop 1
	v_addc_co_u32_e32 v9, vcc, 0, v7, vcc
	s_waitcnt lgkmcnt(0)
	global_store_dwordx4 v[8:9], v[2:5], off
	ds_read_b128 v[2:5], v0 offset:7616
	v_add_co_u32_e32 v6, vcc, 0xe000, v6
	s_nop 1
	v_addc_co_u32_e32 v7, vcc, 0, v7, vcc
	s_waitcnt lgkmcnt(0)
	global_store_dwordx4 v[6:7], v[2:5], off
	s_barrier
	s_cbranch_scc1 .LBB0_94
.LBB0_34:
	s_lshl_b32 s1, s68, 1
	s_ashr_i32 s70, s69, 6
	s_and_b32 s36, s1, 0x700
	s_mul_i32 s28, s70, 0x1800000
	s_mul_hi_i32 s29, s70, 0x1800000
	s_add_u32 s1, s9, s28
	s_addc_u32 s4, s40, s29
	s_lshl_b32 s5, s69, 4
	s_and_b32 s71, s5, 0x380
	s_lshl_b32 s5, s71, 1
	s_add_u32 s48, s1, s5
	s_addc_u32 s49, s4, 0
	v_mov_b32_e32 v6, v227
	v_mov_b32_e32 v162, v226
	s_add_u32 s30, s48, 0x1000
	s_addc_u32 s31, s49, 0
	v_mov_b64_e32 v[2:3], s[48:49]
	v_ashrrev_i32_e32 v10, 3, v6
	s_movk_i32 s23, 0x1800
	v_lshlrev_b32_e32 v7, 4, v6
	s_lshl_b32 s1, s69, 8
	v_mad_i64_i32 v[4:5], s[4:5], v10, s23, v[2:3]
	v_and_b32_e32 v0, 0x70, v7
	v_and_b32_e32 v144, 0xf0, v7
	v_mov_b32_e32 v145, v1
	v_ashrrev_i32_e32 v11, 4, v6
	v_add_u32_e32 v6, 0x200, v6
	s_and_b32 s11, s1, 0x700
	v_lshl_add_u64 v[150:151], v[4:5], 0, v[0:1]
	v_lshl_add_u64 v[4:5], s[30:31], 0, v[144:145]
	v_ashrrev_i32_e32 v12, 4, v6
	s_xor_b32 s22, s11, 0xf00
	v_readlane_b32 s1, v251, 7
	v_mad_i64_i32 v[152:153], s[4:5], v11, s23, v[4:5]
	v_mad_i64_i32 v[154:155], s[4:5], v12, s23, v[4:5]
	v_and_b32_e32 v145, 31, v162
	v_ashrrev_i32_e32 v5, 5, v162
	s_add_i32 s1, s22, s1
	v_lshlrev_b32_e32 v4, 3, v5
	v_or_b32_e32 v176, s1, v145
	v_lshlrev_b32_e32 v172, 4, v5
	v_lshlrev_b32_e32 v173, 2, v5
	v_ashrrev_i32_e32 v5, 31, v4
	v_mad_u64_u32 v[2:3], s[4:5], v176, s23, v[2:3]
	v_lshl_add_u64 v[156:157], v[4:5], 1, v[2:3]
	global_load_dwordx4 v[114:117], v[150:151], off offset:2048
	global_load_dwordx4 v[118:121], v[152:153], off
	global_load_dwordx4 v[122:125], v[154:155], off
	global_load_dwordx4 v[126:129], v[156:157], off
	global_load_dwordx4 v[130:133], v[156:157], off offset:32
	global_load_dwordx4 v[134:137], v[156:157], off offset:64
	global_load_dwordx4 v[138:141], v[156:157], off offset:96
	v_lshrrev_b32_e32 v14, 2, v162
	v_mad_i64_i32 v[6:7], s[4:5], v10, s23, 0
	v_mad_i64_i32 v[8:9], s[4:5], v11, s23, 0
	v_mul_lo_u32 v163, v10, s96
	s_movk_i32 s78, 0x140
	v_mul_lo_u32 v164, v11, s78
	v_mad_i64_i32 v[10:11], s[4:5], v12, s23, 0
	v_and_or_b32 v2, v14, 3, v173
	s_addk_i32 s22, 0x100
	v_mov_b32_e32 v4, 0x1800000
	s_movk_i32 s78, 0x140
	v_mul_lo_u32 v178, v2, s78
	s_lshr_b32 s4, s22, 6
	v_mad_i64_i32 v[2:3], s[22:23], s70, v4, v[10:11]
	v_or3_b32 v2, v2, s36, v144
	v_lshlrev_b32_e32 v237, 2, v162
	v_and_b32_e32 v13, 16, v162
	v_add_u32_e32 v16, 0, v144
	s_movk_i32 s78, 0x140
	v_mul_lo_u32 v175, v12, s78
	v_lshl_add_u64 v[146:147], s[16:17], 0, v[2:3]
	v_mad_i64_i32 v[2:3], s[22:23], s70, v4, v[8:9]
	v_and_or_b32 v13, v237, 12, v13
	v_add_u32_e32 v15, 0, v163
	v_add_u32_e32 v235, v16, v164
	v_add_u32_e32 v236, v16, v175
	v_or3_b32 v2, v2, s36, v144
	v_mad_i64_i32 v[158:159], s[22:23], s70, v4, v[6:7]
	v_mov_b32_e32 v16, v1
	v_mov_b32_e32 v17, v1
	v_lshlrev_b32_e32 v177, 1, v13
	v_add_u32_e32 v234, v15, v0
	v_lshl_add_u64 v[148:149], s[16:17], 0, v[2:3]
	v_or3_b32 v158, v158, s36, v0
	v_mov_b32_e32 v2, v1
	v_mov_b32_e32 v3, v1
	v_mov_b32_e32 v4, v1
	v_mov_b32_e32 v5, v1
	v_mov_b32_e32 v6, v1
	v_mov_b32_e32 v7, v1
	v_mov_b32_e32 v8, v1
	v_mov_b32_e32 v9, v1
	v_mov_b32_e32 v10, v1
	v_mov_b32_e32 v11, v1
	v_mov_b32_e32 v12, v1
	v_mov_b32_e32 v13, v1
	v_mov_b32_e32 v14, v1
	v_mov_b32_e32 v15, v1
	v_mov_b64_e32 v[64:65], v[16:17]
	v_mov_b64_e32 v[48:49], v[16:17]
	v_mov_b64_e32 v[32:33], v[16:17]
	v_mov_b64_e32 v[80:81], v[16:17]
	s_mov_b32 s10, 1
	v_cmp_gt_u32_e64 s[42:43], 32, v162
	v_mul_u32_u24_e32 v165, 0x90, v145
	v_lshl_add_u32 v174, v145, 2, s91
	s_or_b32 s5, s1, 31
	v_subrev_u32_e32 v179, 32, v176
	v_subrev_u32_e32 v180, 33, v176
	v_subrev_u32_e32 v181, 34, v176
	v_subrev_u32_e32 v182, 35, v176
	v_add_u32_e32 v183, -8, v176
	v_subrev_u32_e32 v184, 40, v176
	v_add_u32_e32 v185, -9, v176
	v_subrev_u32_e32 v186, 41, v176
	v_add_u32_e32 v187, -10, v176
	v_subrev_u32_e32 v188, 42, v176
	v_add_u32_e32 v189, -11, v176
	v_subrev_u32_e32 v195, 43, v176
	v_add_u32_e32 v196, -16, v176
	v_subrev_u32_e32 v197, 48, v176
	v_subrev_u32_e32 v198, 17, v176
	v_subrev_u32_e32 v199, 49, v176
	v_subrev_u32_e32 v200, 18, v176
	v_subrev_u32_e32 v201, 50, v176
	v_subrev_u32_e32 v202, 19, v176
	v_subrev_u32_e32 v203, 51, v176
	v_subrev_u32_e32 v204, 24, v176
	v_subrev_u32_e32 v205, 56, v176
	v_subrev_u32_e32 v228, 25, v176
	v_subrev_u32_e32 v229, 57, v176
	v_subrev_u32_e32 v230, 26, v176
	v_subrev_u32_e32 v231, 58, v176
	v_subrev_u32_e32 v232, 27, v176
	v_subrev_u32_e32 v233, 59, v176
	v_lshl_add_u64 v[160:161], s[44:45], 0, v[158:159]
	v_mov_b32_e32 v239, 0xff800000
	s_mov_b32 s22, 63
	s_mov_b64 s[50:51], 0
	v_mov_b64_e32 v[62:63], v[14:15]
	v_mov_b64_e32 v[60:61], v[12:13]
	v_mov_b64_e32 v[58:59], v[10:11]
	v_mov_b64_e32 v[56:57], v[8:9]
	v_mov_b64_e32 v[54:55], v[6:7]
	v_mov_b64_e32 v[52:53], v[4:5]
	v_mov_b64_e32 v[50:51], v[2:3]
	v_mov_b64_e32 v[46:47], v[14:15]
	v_mov_b64_e32 v[44:45], v[12:13]
	v_mov_b64_e32 v[42:43], v[10:11]
	v_mov_b64_e32 v[40:41], v[8:9]
	v_mov_b64_e32 v[38:39], v[6:7]
	v_mov_b64_e32 v[36:37], v[4:5]
	v_mov_b64_e32 v[34:35], v[2:3]
	v_mov_b64_e32 v[30:31], v[14:15]
	v_mov_b64_e32 v[28:29], v[12:13]
	v_mov_b64_e32 v[26:27], v[10:11]
	v_mov_b64_e32 v[24:25], v[8:9]
	v_mov_b64_e32 v[22:23], v[6:7]
	v_mov_b64_e32 v[20:21], v[4:5]
	v_mov_b64_e32 v[18:19], v[2:3]
	v_mov_b64_e32 v[78:79], v[14:15]
	v_mov_b64_e32 v[76:77], v[12:13]
	v_mov_b64_e32 v[74:75], v[10:11]
	v_mov_b64_e32 v[72:73], v[8:9]
	v_mov_b64_e32 v[70:71], v[6:7]
	v_mov_b64_e32 v[68:69], v[4:5]
	v_mov_b64_e32 v[66:67], v[2:3]
	s_waitcnt vmcnt(6)
	ds_write_b128 v234, v[114:117]
	s_waitcnt vmcnt(5)
	ds_write_b128 v235, v[118:121] offset:9216
	s_waitcnt vmcnt(4)
	ds_write_b128 v236, v[122:125] offset:9216
	s_waitcnt vmcnt(0) lgkmcnt(0)
	s_barrier
	s_cmp_lt_u32 s10, s4
	s_cselect_b64 s[60:61], -1, 0
	s_cmp_ge_u32 s10, s4
	s_cbranch_scc1 .LBB0_36

.LBB0_36:
	s_add_i32 s23, s10, -1
	s_and_b32 s23, s23, 1
	s_sub_i32 s26, s22, 63
	s_cmp_gt_u32 s26, s5
	s_cbranch_scc1 .LBB0_43
	s_mul_i32 s26, s23, 0x7400
	s_add_i32 s26, s26, 0
	s_cmp_le_u32 s22, s1
	v_add3_u32 v190, s26, v165, v172
	ds_read_b128 v[98:101], v190
	ds_read_b128 v[102:105], v190 offset:32
	ds_read_b128 v[106:109], v190 offset:64
	ds_read_b128 v[110:113], v190 offset:96
	ds_read_b128 v[240:243], v190 offset:4608
	ds_read_b128 v[244:247], v190 offset:4640
	ds_read_b128 v[214:217], v190 offset:4672
	ds_read_b128 v[190:193], v190 offset:4704
	s_waitcnt lgkmcnt(7)
	v_mfma_f32_32x32x16_bf16 v[82:97], v[98:101], v[126:129], 0
	s_waitcnt lgkmcnt(6)
	v_mfma_f32_32x32x16_bf16 v[82:97], v[102:105], v[130:133], v[82:97]
	s_waitcnt lgkmcnt(5)
	v_mfma_f32_32x32x16_bf16 v[82:97], v[106:109], v[134:137], v[82:97]
	s_waitcnt lgkmcnt(4)
	v_mfma_f32_32x32x16_bf16 v[82:97], v[110:113], v[138:141], v[82:97]
	s_waitcnt lgkmcnt(3)
	v_mfma_f32_32x32x16_bf16 v[98:113], v[240:243], v[126:129], 0
	s_waitcnt lgkmcnt(2)
	v_mfma_f32_32x32x16_bf16 v[98:113], v[244:247], v[130:133], v[98:113]
	s_waitcnt lgkmcnt(1)
	v_mfma_f32_32x32x16_bf16 v[98:113], v[214:217], v[134:137], v[98:113]
	s_waitcnt lgkmcnt(0)
	v_mfma_f32_32x32x16_bf16 v[98:113], v[190:193], v[138:141], v[98:113]
	s_cbranch_scc1 .LBB0_39
	v_add_u32_e32 v190, s22, v173
	v_subrev_u32_e32 v191, 63, v190
	v_cmp_le_i32_e32 vcc, v191, v179
	v_subrev_u32_e32 v192, 61, v190
	v_subrev_u32_e32 v190, 60, v190
	s_nop 5
	v_cndmask_b32_e32 v98, v220, v98, vcc
	v_cmp_lt_i32_e32 vcc, v191, v176
	s_nop 1
	v_cndmask_b32_e32 v83, v220, v83, vcc
	v_cmp_le_i32_e32 vcc, v191, v176
	s_nop 1
	v_cndmask_b32_e32 v82, v220, v82, vcc
	v_cmp_le_i32_e32 vcc, v191, v180
	s_nop 1
	v_cndmask_b32_e32 v99, v220, v99, vcc
	v_cmp_le_i32_e32 vcc, v192, v176
	s_nop 1
	v_cndmask_b32_e32 v84, v220, v84, vcc
	v_cmp_le_i32_e32 vcc, v191, v181
	s_nop 1
	v_cndmask_b32_e32 v100, v220, v100, vcc
	v_cmp_le_i32_e32 vcc, v190, v176
	s_nop 1
	v_cndmask_b32_e32 v85, v220, v85, vcc
	v_cmp_le_i32_e32 vcc, v191, v182
	s_nop 1
	v_cndmask_b32_e32 v101, v220, v101, vcc
	v_cmp_le_i32_e32 vcc, v191, v183
	s_nop 1
	v_cndmask_b32_e32 v86, v220, v86, vcc
	v_cmp_le_i32_e32 vcc, v191, v184
	s_nop 1
	v_cndmask_b32_e32 v102, v220, v102, vcc
	v_cmp_le_i32_e32 vcc, v191, v185
	s_nop 1
	v_cndmask_b32_e32 v87, v220, v87, vcc
	v_cmp_le_i32_e32 vcc, v191, v186
	s_nop 1
	v_cndmask_b32_e32 v103, v220, v103, vcc
	v_cmp_le_i32_e32 vcc, v191, v187
	s_nop 1
	v_cndmask_b32_e32 v88, v220, v88, vcc
	v_cmp_le_i32_e32 vcc, v191, v188
	s_nop 1
	v_cndmask_b32_e32 v104, v220, v104, vcc
	v_cmp_le_i32_e32 vcc, v191, v189
	s_nop 1
	v_cndmask_b32_e32 v89, v220, v89, vcc
	v_cmp_le_i32_e32 vcc, v191, v195
	s_nop 1
	v_cndmask_b32_e32 v105, v220, v105, vcc
	v_cmp_le_i32_e32 vcc, v191, v196
	s_nop 1
	v_cndmask_b32_e32 v90, v220, v90, vcc
	v_cmp_le_i32_e32 vcc, v191, v197
	s_nop 1
	v_cndmask_b32_e32 v106, v220, v106, vcc
	v_cmp_le_i32_e32 vcc, v191, v198
	s_nop 1
	v_cndmask_b32_e32 v91, v220, v91, vcc
	v_cmp_le_i32_e32 vcc, v191, v199
	s_nop 1
	v_cndmask_b32_e32 v107, v220, v107, vcc
	v_cmp_le_i32_e32 vcc, v191, v200
	s_nop 1
	v_cndmask_b32_e32 v92, v220, v92, vcc
	v_cmp_le_i32_e32 vcc, v191, v201
	s_nop 1
	v_cndmask_b32_e32 v108, v220, v108, vcc
	v_cmp_le_i32_e32 vcc, v191, v202
	s_nop 1
	v_cndmask_b32_e32 v93, v220, v93, vcc
	v_cmp_le_i32_e32 vcc, v191, v203
	s_nop 1
	v_cndmask_b32_e32 v109, v220, v109, vcc
	v_cmp_le_i32_e32 vcc, v191, v204
	s_nop 1
	v_cndmask_b32_e32 v94, v220, v94, vcc
	v_cmp_le_i32_e32 vcc, v191, v205
	s_nop 1
	v_cndmask_b32_e32 v110, v220, v110, vcc
	v_cmp_le_i32_e32 vcc, v191, v228
	s_nop 1
	v_cndmask_b32_e32 v95, v220, v95, vcc
	v_cmp_le_i32_e32 vcc, v191, v229
	s_nop 1
	v_cndmask_b32_e32 v111, v220, v111, vcc
	v_cmp_le_i32_e32 vcc, v191, v230
	s_nop 1
	v_cndmask_b32_e32 v96, v220, v96, vcc
	v_cmp_le_i32_e32 vcc, v191, v231
	s_nop 1
	v_cndmask_b32_e32 v112, v220, v112, vcc
	v_cmp_le_i32_e32 vcc, v191, v232
	s_nop 1
	v_cndmask_b32_e32 v97, v220, v97, vcc
	v_cmp_le_i32_e32 vcc, v191, v233
	s_nop 1
	v_cndmask_b32_e32 v113, v220, v113, vcc
.LBB0_39:
	s_nop 10
	v_max3_f32 v240, v82, v83, v84
	v_max3_f32 v241, v98, v99, v100
	v_max3_f32 v242, v90, v91, v92
	v_max3_f32 v243, v106, v107, v108
	v_max3_f32 v240, v240, v85, v86
	v_max3_f32 v241, v241, v101, v102
	v_max3_f32 v242, v242, v93, v94
	v_max3_f32 v243, v243, v109, v110
	v_max3_f32 v240, v240, v87, v88
	v_max3_f32 v241, v241, v103, v104
	v_max3_f32 v242, v242, v95, v96
	v_max3_f32 v243, v243, v111, v112
	v_max3_f32 v240, v240, v89, v105
	v_max3_f32 v242, v242, v97, v113
	v_max3_f32 v240, v240, v241, v242
	v_max_f32_e32 v240, v240, v243
	v_mov_b32_e32 v241, v240
	s_nop 1
	v_permlane32_swap_b32_e32 v240, v241
	v_max_f32_e32 v238, v240, v241
	v_add_f32_e32 v190, 0x41000000, v239
	v_cmp_gt_f32_e32 vcc, v238, v190
	s_cbranch_vccz .LBB0_44
	v_max_f32_e32 v190, v238, v238
	v_max_f32_e32 v191, v239, v239
	v_max_f32_e32 v238, v191, v190
	s_and_saveexec_b64 s[62:63], s[42:43]
	s_cbranch_execz .LBB0_42
	v_sub_f32_e32 v190, v239, v238
	v_exp_f32_e32 v190, v190
	ds_write_b32 v174, v190 offset:59392
.LBB0_42:
	s_or_b64 exec, exec, s[62:63]
	v_add_u32_e32 v206, s91, v172
	ds_read_b128 v[240:243], v206 offset:59488
	ds_read_b128 v[244:247], v206 offset:59456
	ds_read_b128 v[190:193], v206 offset:59424
	ds_read_b128 v[214:217], v206 offset:59392
	s_waitcnt lgkmcnt(3)
	v_pk_mul_f32 v[14:15], v[14:15], v[240:241]
	s_waitcnt lgkmcnt(2)
	v_pk_mul_f32 v[10:11], v[10:11], v[244:245]
	s_waitcnt lgkmcnt(1)
	v_pk_mul_f32 v[6:7], v[6:7], v[190:191]
	v_pk_mul_f32 v[16:17], v[16:17], v[242:243]
	v_pk_mul_f32 v[12:13], v[12:13], v[246:247]
	v_pk_mul_f32 v[8:9], v[8:9], v[192:193]
	s_waitcnt lgkmcnt(0)
	v_pk_mul_f32 v[4:5], v[4:5], v[216:217]
	v_pk_mul_f32 v[2:3], v[2:3], v[214:215]
	v_pk_mul_f32 v[62:63], v[62:63], v[240:241]
	v_pk_mul_f32 v[58:59], v[58:59], v[244:245]
	v_pk_mul_f32 v[54:55], v[54:55], v[190:191]
	v_pk_mul_f32 v[64:65], v[64:65], v[242:243]
	v_pk_mul_f32 v[60:61], v[60:61], v[246:247]
	v_pk_mul_f32 v[56:57], v[56:57], v[192:193]
	v_pk_mul_f32 v[52:53], v[52:53], v[216:217]
	v_pk_mul_f32 v[50:51], v[50:51], v[214:215]
	v_pk_mul_f32 v[46:47], v[46:47], v[240:241]
	v_pk_mul_f32 v[42:43], v[42:43], v[244:245]
	v_pk_mul_f32 v[38:39], v[38:39], v[190:191]
	v_pk_mul_f32 v[48:49], v[48:49], v[242:243]
	v_pk_mul_f32 v[44:45], v[44:45], v[246:247]
	v_pk_mul_f32 v[40:41], v[40:41], v[192:193]
	v_pk_mul_f32 v[36:37], v[36:37], v[216:217]
	v_pk_mul_f32 v[34:35], v[34:35], v[214:215]
	v_pk_mul_f32 v[30:31], v[30:31], v[240:241]
	v_pk_mul_f32 v[26:27], v[26:27], v[244:245]
	v_pk_mul_f32 v[22:23], v[22:23], v[190:191]
	v_pk_mul_f32 v[32:33], v[32:33], v[242:243]
	v_pk_mul_f32 v[28:29], v[28:29], v[246:247]
	v_pk_mul_f32 v[24:25], v[24:25], v[192:193]
	v_pk_mul_f32 v[20:21], v[20:21], v[216:217]
	v_pk_mul_f32 v[18:19], v[18:19], v[214:215]
	v_pk_mul_f32 v[78:79], v[78:79], v[240:241]
	v_pk_mul_f32 v[74:75], v[74:75], v[244:245]
	v_pk_mul_f32 v[70:71], v[70:71], v[190:191]
	v_pk_mul_f32 v[80:81], v[80:81], v[242:243]
	v_pk_mul_f32 v[76:77], v[76:77], v[246:247]
	v_pk_mul_f32 v[72:73], v[72:73], v[192:193]
	v_pk_mul_f32 v[68:69], v[68:69], v[216:217]
	v_pk_mul_f32 v[66:67], v[66:67], v[214:215]
	s_branch .LBB0_45

.LBB0_45:
	v_add3_u32 v190, s26, v178, v177
	s_mov_b32 s78, s76
	s_mov_b32 s79, s76
	s_mov_b32 s77, s76
	ds_read_b64_tr_b16 v[240:241], v190 offset:9216
	ds_read_b64_tr_b16 v[242:243], v190 offset:11776
	ds_read_b64_tr_b16 v[244:245], v190 offset:9280
	ds_read_b64_tr_b16 v[246:247], v190 offset:11840
	ds_read_b64_tr_b16 v[214:215], v190 offset:9344
	ds_read_b64_tr_b16 v[216:217], v190 offset:11904
	v_sub_f32_e32 v82, v82, v238
	v_sub_f32_e32 v83, v83, v238
	v_sub_f32_e32 v84, v84, v238
	v_sub_f32_e32 v85, v85, v238
	v_sub_f32_e32 v86, v86, v238
	v_sub_f32_e32 v87, v87, v238
	v_sub_f32_e32 v88, v88, v238
	v_sub_f32_e32 v89, v89, v238
	v_exp_f32_e32 v82, v82
	v_exp_f32_e32 v83, v83
	v_exp_f32_e32 v84, v84
	v_exp_f32_e32 v85, v85
	v_exp_f32_e32 v86, v86
	v_exp_f32_e32 v87, v87
	v_exp_f32_e32 v88, v88
	v_exp_f32_e32 v89, v89
	v_cvt_pk_bf16_f32 v82, v82, v83
	v_cvt_pk_bf16_f32 v83, v84, v85
	v_cvt_pk_bf16_f32 v84, v86, v87
	v_cvt_pk_bf16_f32 v85, v88, v89
	v_mov_b64_e32 v[88:89], s[78:79]
	v_mov_b64_e32 v[86:87], s[76:77]
	s_waitcnt lgkmcnt(4)
	v_mfma_f32_32x32x16_bf16 v[2:17], v[82:85], v[240:243], v[2:17]
	v_sub_f32_e32 v90, v90, v238
	v_sub_f32_e32 v91, v91, v238
	v_sub_f32_e32 v92, v92, v238
	v_sub_f32_e32 v93, v93, v238
	ds_read_b64_tr_b16 v[240:241], v190 offset:9408
	ds_read_b64_tr_b16 v[242:243], v190 offset:11968
	s_waitcnt lgkmcnt(4)
	v_mfma_f32_32x32x16_bf16 v[50:65], v[82:85], v[244:247], v[50:65]
	v_sub_f32_e32 v94, v94, v238
	v_sub_f32_e32 v95, v95, v238
	v_sub_f32_e32 v96, v96, v238
	v_sub_f32_e32 v97, v97, v238
	ds_read_b64_tr_b16 v[244:245], v190 offset:14336
	ds_read_b64_tr_b16 v[246:247], v190 offset:16896
	s_waitcnt lgkmcnt(4)
	v_mfma_f32_32x32x16_bf16 v[34:49], v[82:85], v[214:217], v[34:49]
	v_exp_f32_e32 v90, v90
	v_exp_f32_e32 v91, v91
	v_exp_f32_e32 v92, v92
	v_exp_f32_e32 v93, v93
	ds_read_b64_tr_b16 v[214:215], v190 offset:14400
	ds_read_b64_tr_b16 v[216:217], v190 offset:16960
	s_waitcnt lgkmcnt(4)
	v_mfma_f32_32x32x16_bf16 v[18:33], v[82:85], v[240:243], v[18:33]
	v_exp_f32_e32 v94, v94
	v_exp_f32_e32 v95, v95
	v_exp_f32_e32 v96, v96
	v_exp_f32_e32 v97, v97
	ds_read_b64_tr_b16 v[240:241], v190 offset:14464
	ds_read_b64_tr_b16 v[242:243], v190 offset:17024
	v_mfma_f32_32x32x16_bf16 v[66:81], v[82:85], v[86:89], v[66:81]
	v_cvt_pk_bf16_f32 v90, v90, v91
	v_cvt_pk_bf16_f32 v91, v92, v93
	v_cvt_pk_bf16_f32 v92, v94, v95
	v_cvt_pk_bf16_f32 v93, v96, v97
	s_nop 0
	s_waitcnt lgkmcnt(4)
	v_mfma_f32_32x32x16_bf16 v[2:17], v[90:93], v[244:247], v[2:17]
	v_sub_f32_e32 v98, v98, v238
	v_sub_f32_e32 v99, v99, v238
	v_sub_f32_e32 v100, v100, v238
	v_sub_f32_e32 v101, v101, v238
	ds_read_b64_tr_b16 v[244:245], v190 offset:14528
	ds_read_b64_tr_b16 v[246:247], v190 offset:17088
	s_waitcnt lgkmcnt(4)
	v_mfma_f32_32x32x16_bf16 v[50:65], v[90:93], v[214:217], v[50:65]
	v_sub_f32_e32 v102, v102, v238
	v_sub_f32_e32 v103, v103, v238
	v_sub_f32_e32 v104, v104, v238
	v_sub_f32_e32 v105, v105, v238
	ds_read_b64_tr_b16 v[214:215], v190 offset:19456
	ds_read_b64_tr_b16 v[216:217], v190 offset:22016
	s_waitcnt lgkmcnt(4)
	v_mfma_f32_32x32x16_bf16 v[34:49], v[90:93], v[240:243], v[34:49]
	v_exp_f32_e32 v98, v98
	v_exp_f32_e32 v99, v99
	v_exp_f32_e32 v100, v100
	v_exp_f32_e32 v101, v101
	ds_read_b64_tr_b16 v[240:241], v190 offset:19520
	ds_read_b64_tr_b16 v[242:243], v190 offset:22080
	s_waitcnt lgkmcnt(4)
	v_mfma_f32_32x32x16_bf16 v[18:33], v[90:93], v[244:247], v[18:33]
	v_exp_f32_e32 v102, v102
	v_exp_f32_e32 v103, v103
	v_exp_f32_e32 v104, v104
	v_exp_f32_e32 v105, v105
	ds_read_b64_tr_b16 v[244:245], v190 offset:19584
	ds_read_b64_tr_b16 v[246:247], v190 offset:22144
	v_mfma_f32_32x32x16_bf16 v[66:81], v[90:93], v[86:89], v[66:81]
	v_cvt_pk_bf16_f32 v98, v98, v99
	v_cvt_pk_bf16_f32 v99, v100, v101
	v_cvt_pk_bf16_f32 v100, v102, v103
	v_cvt_pk_bf16_f32 v101, v104, v105
	s_nop 0
	s_waitcnt lgkmcnt(4)
	v_mfma_f32_32x32x16_bf16 v[2:17], v[98:101], v[214:217], v[2:17]
	v_sub_f32_e32 v106, v106, v238
	v_sub_f32_e32 v107, v107, v238
	v_sub_f32_e32 v108, v108, v238
	v_sub_f32_e32 v109, v109, v238
	ds_read_b64_tr_b16 v[214:215], v190 offset:19648
	ds_read_b64_tr_b16 v[216:217], v190 offset:22208
	s_waitcnt lgkmcnt(4)
	v_mfma_f32_32x32x16_bf16 v[50:65], v[98:101], v[240:243], v[50:65]
	v_sub_f32_e32 v110, v110, v238
	v_sub_f32_e32 v111, v111, v238
	v_sub_f32_e32 v112, v112, v238
	v_sub_f32_e32 v113, v113, v238
	ds_read_b64_tr_b16 v[240:241], v190 offset:24576
	ds_read_b64_tr_b16 v[242:243], v190 offset:27136
	s_waitcnt lgkmcnt(4)
	v_mfma_f32_32x32x16_bf16 v[34:49], v[98:101], v[244:247], v[34:49]
	v_exp_f32_e32 v106, v106
	v_exp_f32_e32 v107, v107
	v_exp_f32_e32 v108, v108
	v_exp_f32_e32 v109, v109
	ds_read_b64_tr_b16 v[244:245], v190 offset:24640
	ds_read_b64_tr_b16 v[246:247], v190 offset:27200
	s_waitcnt lgkmcnt(4)
	v_mfma_f32_32x32x16_bf16 v[18:33], v[98:101], v[214:217], v[18:33]
	v_exp_f32_e32 v110, v110
	v_exp_f32_e32 v111, v111
	v_exp_f32_e32 v112, v112
	v_exp_f32_e32 v113, v113
	ds_read_b64_tr_b16 v[214:215], v190 offset:24704
	ds_read_b64_tr_b16 v[216:217], v190 offset:27264
	v_mfma_f32_32x32x16_bf16 v[66:81], v[98:101], v[86:89], v[66:81]
	v_cvt_pk_bf16_f32 v106, v106, v107
	v_cvt_pk_bf16_f32 v107, v108, v109
	v_cvt_pk_bf16_f32 v108, v110, v111
	v_cvt_pk_bf16_f32 v109, v112, v113
	s_nop 0
	s_waitcnt lgkmcnt(4)
	v_mfma_f32_32x32x16_bf16 v[2:17], v[106:109], v[240:243], v[2:17]
	ds_read_b64_tr_b16 v[240:241], v190 offset:24768
	ds_read_b64_tr_b16 v[242:243], v190 offset:27328
	s_waitcnt lgkmcnt(4)
	v_mfma_f32_32x32x16_bf16 v[50:65], v[106:109], v[244:247], v[50:65]
	s_waitcnt lgkmcnt(2)
	v_mfma_f32_32x32x16_bf16 v[34:49], v[106:109], v[214:217], v[34:49]
	s_waitcnt lgkmcnt(0)
	v_mfma_f32_32x32x16_bf16 v[18:33], v[106:109], v[240:243], v[18:33]
	v_mfma_f32_32x32x16_bf16 v[66:81], v[106:109], v[86:89], v[66:81]
	s_movk_i32 s77, 0x110
	s_andn2_b64 vcc, exec, s[60:61]
	s_cbranch_vccnz .LBB0_47
.LBB0_46:
	s_xor_b32 s23, s23, 1
	s_mulk_i32 s23, 0x7400
	s_add_i32 s23, s23, 0
	v_add3_u32 v82, s23, v163, v0
	v_add_u32_e32 v83, s23, v144
	v_add_u32_e32 v84, v83, v164
	v_add_u32_e32 v83, v83, v175
	s_waitcnt vmcnt(2)
	ds_write_b128 v82, v[114:117]
	s_waitcnt vmcnt(1)
	ds_write_b128 v84, v[118:121] offset:9216
	s_waitcnt vmcnt(0)
	ds_write_b128 v83, v[122:125] offset:9216

.LBB0_51:
	s_add_i32 s23, s22, -1
	s_and_b32 s23, s23, 1
	s_sub_i32 s26, s10, 63
	s_cmp_gt_u32 s26, s5
	s_cbranch_scc1 .LBB0_58
	s_mul_i32 s26, s23, 0x7400
	s_add_i32 s26, s26, 0
	s_cmp_le_u32 s10, s1
	v_add3_u32 v152, s26, v165, v172
	ds_read_b128 v[98:101], v152
	ds_read_b128 v[102:105], v152 offset:32
	ds_read_b128 v[106:109], v152 offset:64
	ds_read_b128 v[110:113], v152 offset:96
	ds_read_b128 v[154:157], v152 offset:4608
	ds_read_b128 v[190:193], v152 offset:4640
	ds_read_b128 v[214:217], v152 offset:4672
	ds_read_b128 v[234:237], v152 offset:4704
	s_waitcnt lgkmcnt(7)
	v_mfma_f32_32x32x16_bf16 v[82:97], v[98:101], v[114:117], 0
	s_waitcnt lgkmcnt(6)
	v_mfma_f32_32x32x16_bf16 v[82:97], v[102:105], v[118:121], v[82:97]
	s_waitcnt lgkmcnt(5)
	v_mfma_f32_32x32x16_bf16 v[82:97], v[106:109], v[126:129], v[82:97]
	s_waitcnt lgkmcnt(4)
	v_mfma_f32_32x32x16_bf16 v[82:97], v[110:113], v[130:133], v[82:97]
	s_waitcnt lgkmcnt(3)
	v_mfma_f32_32x32x16_bf16 v[98:113], v[154:157], v[114:117], 0
	s_waitcnt lgkmcnt(2)
	v_mfma_f32_32x32x16_bf16 v[98:113], v[190:193], v[118:121], v[98:113]
	s_waitcnt lgkmcnt(1)
	v_mfma_f32_32x32x16_bf16 v[98:113], v[214:217], v[126:129], v[98:113]
	s_waitcnt lgkmcnt(0)
	v_mfma_f32_32x32x16_bf16 v[98:113], v[234:237], v[130:133], v[98:113]
	s_cbranch_scc1 .LBB0_54
	v_add_u32_e32 v152, s10, v173
	v_subrev_u32_e32 v154, 63, v152
	v_cmp_le_i32_e32 vcc, v154, v179
	v_subrev_u32_e32 v155, 61, v152
	v_subrev_u32_e32 v152, 60, v152
	s_nop 5
	v_cndmask_b32_e32 v98, v220, v98, vcc
	v_cmp_lt_i32_e32 vcc, v154, v176
	s_nop 1
	v_cndmask_b32_e32 v83, v220, v83, vcc
	v_cmp_le_i32_e32 vcc, v154, v176
	s_nop 1
	v_cndmask_b32_e32 v82, v220, v82, vcc
	v_cmp_le_i32_e32 vcc, v154, v180
	s_nop 1
	v_cndmask_b32_e32 v99, v220, v99, vcc
	v_cmp_le_i32_e32 vcc, v155, v176
	s_nop 1
	v_cndmask_b32_e32 v84, v220, v84, vcc
	v_cmp_le_i32_e32 vcc, v154, v181
	s_nop 1
	v_cndmask_b32_e32 v100, v220, v100, vcc
	v_cmp_le_i32_e32 vcc, v152, v176
	s_nop 1
	v_cndmask_b32_e32 v85, v220, v85, vcc
	v_cmp_le_i32_e32 vcc, v154, v182
	s_nop 1
	v_cndmask_b32_e32 v101, v220, v101, vcc
	v_cmp_le_i32_e32 vcc, v154, v183
	s_nop 1
	v_cndmask_b32_e32 v86, v220, v86, vcc
	v_cmp_le_i32_e32 vcc, v154, v184
	s_nop 1
	v_cndmask_b32_e32 v102, v220, v102, vcc
	v_cmp_le_i32_e32 vcc, v154, v185
	s_nop 1
	v_cndmask_b32_e32 v87, v220, v87, vcc
	v_cmp_le_i32_e32 vcc, v154, v186
	s_nop 1
	v_cndmask_b32_e32 v103, v220, v103, vcc
	v_cmp_le_i32_e32 vcc, v154, v187
	s_nop 1
	v_cndmask_b32_e32 v88, v220, v88, vcc
	v_cmp_le_i32_e32 vcc, v154, v188
	s_nop 1
	v_cndmask_b32_e32 v104, v220, v104, vcc
	v_cmp_le_i32_e32 vcc, v154, v189
	s_nop 1
	v_cndmask_b32_e32 v89, v220, v89, vcc
	v_cmp_le_i32_e32 vcc, v154, v195
	s_nop 1
	v_cndmask_b32_e32 v105, v220, v105, vcc
	v_cmp_le_i32_e32 vcc, v154, v196
	s_nop 1
	v_cndmask_b32_e32 v90, v220, v90, vcc
	v_cmp_le_i32_e32 vcc, v154, v197
	s_nop 1
	v_cndmask_b32_e32 v106, v220, v106, vcc
	v_cmp_le_i32_e32 vcc, v154, v198
	s_nop 1
	v_cndmask_b32_e32 v91, v220, v91, vcc
	v_cmp_le_i32_e32 vcc, v154, v199
	s_nop 1
	v_cndmask_b32_e32 v107, v220, v107, vcc
	v_cmp_le_i32_e32 vcc, v154, v200
	s_nop 1
	v_cndmask_b32_e32 v92, v220, v92, vcc
	v_cmp_le_i32_e32 vcc, v154, v201
	s_nop 1
	v_cndmask_b32_e32 v108, v220, v108, vcc
	v_cmp_le_i32_e32 vcc, v154, v202
	s_nop 1
	v_cndmask_b32_e32 v93, v220, v93, vcc
	v_cmp_le_i32_e32 vcc, v154, v203
	s_nop 1
	v_cndmask_b32_e32 v109, v220, v109, vcc
	v_cmp_le_i32_e32 vcc, v154, v204
	s_nop 1
	v_cndmask_b32_e32 v94, v220, v94, vcc
	v_cmp_le_i32_e32 vcc, v154, v205
	s_nop 1
	v_cndmask_b32_e32 v110, v220, v110, vcc
	v_cmp_le_i32_e32 vcc, v154, v228
	s_nop 1
	v_cndmask_b32_e32 v95, v220, v95, vcc
	v_cmp_le_i32_e32 vcc, v154, v229
	s_nop 1
	v_cndmask_b32_e32 v111, v220, v111, vcc
	v_cmp_le_i32_e32 vcc, v154, v230
	s_nop 1
	v_cndmask_b32_e32 v96, v220, v96, vcc
	v_cmp_le_i32_e32 vcc, v154, v231
	s_nop 1
	v_cndmask_b32_e32 v112, v220, v112, vcc
	v_cmp_le_i32_e32 vcc, v154, v232
	s_nop 1
	v_cndmask_b32_e32 v97, v220, v97, vcc
	v_cmp_le_i32_e32 vcc, v154, v233
	s_nop 1
	v_cndmask_b32_e32 v113, v220, v113, vcc
.LBB0_54:
	s_nop 10
	v_max3_f32 v154, v82, v83, v84
	v_max3_f32 v155, v98, v99, v100
	v_max3_f32 v156, v90, v91, v92
	v_max3_f32 v157, v106, v107, v108
	v_max3_f32 v154, v154, v85, v86
	v_max3_f32 v155, v155, v101, v102
	v_max3_f32 v156, v156, v93, v94
	v_max3_f32 v157, v157, v109, v110
	v_max3_f32 v154, v154, v87, v88
	v_max3_f32 v155, v155, v103, v104
	v_max3_f32 v156, v156, v95, v96
	v_max3_f32 v157, v157, v111, v112
	v_max3_f32 v154, v154, v89, v105
	v_max3_f32 v156, v156, v97, v113
	v_max3_f32 v154, v154, v155, v156
	v_max_f32_e32 v154, v154, v157
	v_mov_b32_e32 v155, v154
	s_nop 1
	v_permlane32_swap_b32_e32 v154, v155
	v_max_f32_e32 v152, v154, v155
	v_add_f32_e32 v154, 0x41000000, v153
	v_cmp_gt_f32_e32 vcc, v152, v154
	s_cbranch_vccz .LBB0_59
	v_max_f32_e32 v152, v152, v152
	v_max_f32_e32 v154, v153, v153
	v_max_f32_e32 v152, v154, v152
	s_and_saveexec_b64 s[64:65], s[42:43]
	s_cbranch_execz .LBB0_57
	v_sub_f32_e32 v153, v153, v152
	v_exp_f32_e32 v153, v153
	ds_write_b32 v174, v153 offset:59392
.LBB0_57:
	s_or_b64 exec, exec, s[64:65]
	v_add_u32_e32 v153, s91, v172
	ds_read_b128 v[154:157], v153 offset:59488
	ds_read_b128 v[190:193], v153 offset:59456
	ds_read_b128 v[214:217], v153 offset:59424
	ds_read_b128 v[234:237], v153 offset:59392
	s_waitcnt lgkmcnt(3)
	v_pk_mul_f32 v[14:15], v[14:15], v[154:155]
	s_waitcnt lgkmcnt(2)
	v_pk_mul_f32 v[10:11], v[10:11], v[190:191]
	s_waitcnt lgkmcnt(1)
	v_pk_mul_f32 v[6:7], v[6:7], v[214:215]
	v_pk_mul_f32 v[16:17], v[16:17], v[156:157]
	v_pk_mul_f32 v[12:13], v[12:13], v[192:193]
	v_pk_mul_f32 v[8:9], v[8:9], v[216:217]
	s_waitcnt lgkmcnt(0)
	v_pk_mul_f32 v[4:5], v[4:5], v[236:237]
	v_pk_mul_f32 v[2:3], v[2:3], v[234:235]
	v_pk_mul_f32 v[62:63], v[62:63], v[154:155]
	v_pk_mul_f32 v[58:59], v[58:59], v[190:191]
	v_pk_mul_f32 v[54:55], v[54:55], v[214:215]
	v_pk_mul_f32 v[64:65], v[64:65], v[156:157]
	v_pk_mul_f32 v[60:61], v[60:61], v[192:193]
	v_pk_mul_f32 v[56:57], v[56:57], v[216:217]
	v_pk_mul_f32 v[52:53], v[52:53], v[236:237]
	v_pk_mul_f32 v[50:51], v[50:51], v[234:235]
	v_pk_mul_f32 v[30:31], v[30:31], v[154:155]
	v_pk_mul_f32 v[26:27], v[26:27], v[190:191]
	v_pk_mul_f32 v[22:23], v[22:23], v[214:215]
	v_pk_mul_f32 v[32:33], v[32:33], v[156:157]
	v_pk_mul_f32 v[28:29], v[28:29], v[192:193]
	v_pk_mul_f32 v[24:25], v[24:25], v[216:217]
	v_pk_mul_f32 v[20:21], v[20:21], v[236:237]
	v_pk_mul_f32 v[18:19], v[18:19], v[234:235]
	v_pk_mul_f32 v[46:47], v[46:47], v[154:155]
	v_pk_mul_f32 v[42:43], v[42:43], v[190:191]
	v_pk_mul_f32 v[38:39], v[38:39], v[214:215]
	v_pk_mul_f32 v[48:49], v[48:49], v[156:157]
	v_pk_mul_f32 v[44:45], v[44:45], v[192:193]
	v_pk_mul_f32 v[40:41], v[40:41], v[216:217]
	v_pk_mul_f32 v[36:37], v[36:37], v[236:237]
	v_pk_mul_f32 v[34:35], v[34:35], v[234:235]
	v_pk_mul_f32 v[78:79], v[78:79], v[154:155]
	v_pk_mul_f32 v[74:75], v[74:75], v[190:191]
	v_pk_mul_f32 v[70:71], v[70:71], v[214:215]
	v_pk_mul_f32 v[80:81], v[80:81], v[156:157]
	v_pk_mul_f32 v[76:77], v[76:77], v[192:193]
	v_pk_mul_f32 v[72:73], v[72:73], v[216:217]
	v_pk_mul_f32 v[68:69], v[68:69], v[236:237]
	v_pk_mul_f32 v[66:67], v[66:67], v[234:235]
	s_branch .LBB0_60

.LBB0_60:
	v_add3_u32 v153, s26, v178, v177
	s_mov_b32 s78, s76
	s_mov_b32 s79, s76
	s_mov_b32 s77, s76
	ds_read_b64_tr_b16 v[154:155], v153 offset:9216
	ds_read_b64_tr_b16 v[156:157], v153 offset:11776
	ds_read_b64_tr_b16 v[190:191], v153 offset:9280
	ds_read_b64_tr_b16 v[192:193], v153 offset:11840
	ds_read_b64_tr_b16 v[214:215], v153 offset:9344
	ds_read_b64_tr_b16 v[216:217], v153 offset:11904
	ds_read_b64_tr_b16 v[234:235], v153 offset:9408
	ds_read_b64_tr_b16 v[236:237], v153 offset:11968
	v_sub_f32_e32 v82, v82, v152
	v_sub_f32_e32 v83, v83, v152
	v_sub_f32_e32 v84, v84, v152
	v_sub_f32_e32 v85, v85, v152
	v_sub_f32_e32 v86, v86, v152
	v_sub_f32_e32 v87, v87, v152
	v_sub_f32_e32 v88, v88, v152
	v_sub_f32_e32 v89, v89, v152
	v_exp_f32_e32 v82, v82
	v_exp_f32_e32 v83, v83
	v_exp_f32_e32 v84, v84
	v_exp_f32_e32 v85, v85
	v_exp_f32_e32 v86, v86
	v_exp_f32_e32 v87, v87
	v_exp_f32_e32 v88, v88
	v_exp_f32_e32 v89, v89
	v_cvt_pk_bf16_f32 v82, v82, v83
	v_cvt_pk_bf16_f32 v83, v84, v85
	v_cvt_pk_bf16_f32 v84, v86, v87
	v_cvt_pk_bf16_f32 v85, v88, v89
	v_mov_b64_e32 v[88:89], s[78:79]
	v_mov_b64_e32 v[86:87], s[76:77]
	s_waitcnt lgkmcnt(6)
	v_mfma_f32_32x32x16_bf16 v[2:17], v[82:85], v[154:157], v[2:17]
	v_sub_f32_e32 v90, v90, v152
	v_sub_f32_e32 v91, v91, v152
	v_sub_f32_e32 v92, v92, v152
	v_sub_f32_e32 v93, v93, v152
	ds_read_b64_tr_b16 v[154:155], v153 offset:14336
	ds_read_b64_tr_b16 v[156:157], v153 offset:16896
	s_waitcnt lgkmcnt(6)
	v_mfma_f32_32x32x16_bf16 v[50:65], v[82:85], v[190:193], v[50:65]
	v_sub_f32_e32 v94, v94, v152
	v_sub_f32_e32 v95, v95, v152
	v_sub_f32_e32 v96, v96, v152
	v_sub_f32_e32 v97, v97, v152
	ds_read_b64_tr_b16 v[190:191], v153 offset:14400
	ds_read_b64_tr_b16 v[192:193], v153 offset:16960
	s_waitcnt lgkmcnt(6)
	v_mfma_f32_32x32x16_bf16 v[18:33], v[82:85], v[214:217], v[18:33]
	v_exp_f32_e32 v90, v90
	v_exp_f32_e32 v91, v91
	v_exp_f32_e32 v92, v92
	v_exp_f32_e32 v93, v93
	ds_read_b64_tr_b16 v[214:215], v153 offset:14464
	ds_read_b64_tr_b16 v[216:217], v153 offset:17024
	s_waitcnt lgkmcnt(6)
	v_mfma_f32_32x32x16_bf16 v[34:49], v[82:85], v[234:237], v[34:49]
	v_exp_f32_e32 v94, v94
	v_exp_f32_e32 v95, v95
	v_exp_f32_e32 v96, v96
	v_exp_f32_e32 v97, v97
	ds_read_b64_tr_b16 v[234:235], v153 offset:14528
	ds_read_b64_tr_b16 v[236:237], v153 offset:17088
	v_mfma_f32_32x32x16_bf16 v[66:81], v[82:85], v[86:89], v[66:81]
	v_cvt_pk_bf16_f32 v90, v90, v91
	v_cvt_pk_bf16_f32 v91, v92, v93
	v_cvt_pk_bf16_f32 v92, v94, v95
	v_cvt_pk_bf16_f32 v93, v96, v97
	s_nop 0
	s_waitcnt lgkmcnt(6)
	v_mfma_f32_32x32x16_bf16 v[2:17], v[90:93], v[154:157], v[2:17]
	v_sub_f32_e32 v98, v98, v152
	v_sub_f32_e32 v99, v99, v152
	v_sub_f32_e32 v100, v100, v152
	v_sub_f32_e32 v101, v101, v152
	ds_read_b64_tr_b16 v[154:155], v153 offset:19456
	ds_read_b64_tr_b16 v[156:157], v153 offset:22016
	s_waitcnt lgkmcnt(6)
	v_mfma_f32_32x32x16_bf16 v[50:65], v[90:93], v[190:193], v[50:65]
	v_sub_f32_e32 v102, v102, v152
	v_sub_f32_e32 v103, v103, v152
	v_sub_f32_e32 v104, v104, v152
	v_sub_f32_e32 v105, v105, v152
	ds_read_b64_tr_b16 v[190:191], v153 offset:19520
	ds_read_b64_tr_b16 v[192:193], v153 offset:22080
	s_waitcnt lgkmcnt(6)
	v_mfma_f32_32x32x16_bf16 v[18:33], v[90:93], v[214:217], v[18:33]
	v_exp_f32_e32 v98, v98
	v_exp_f32_e32 v99, v99
	v_exp_f32_e32 v100, v100
	v_exp_f32_e32 v101, v101
	ds_read_b64_tr_b16 v[214:215], v153 offset:19584
	ds_read_b64_tr_b16 v[216:217], v153 offset:22144
	s_waitcnt lgkmcnt(6)
	v_mfma_f32_32x32x16_bf16 v[34:49], v[90:93], v[234:237], v[34:49]
	v_exp_f32_e32 v102, v102
	v_exp_f32_e32 v103, v103
	v_exp_f32_e32 v104, v104
	v_exp_f32_e32 v105, v105
	ds_read_b64_tr_b16 v[234:235], v153 offset:19648
	ds_read_b64_tr_b16 v[236:237], v153 offset:22208
	v_mfma_f32_32x32x16_bf16 v[66:81], v[90:93], v[86:89], v[66:81]
	v_cvt_pk_bf16_f32 v98, v98, v99
	v_cvt_pk_bf16_f32 v99, v100, v101
	v_cvt_pk_bf16_f32 v100, v102, v103
	v_cvt_pk_bf16_f32 v101, v104, v105
	s_nop 0
	s_waitcnt lgkmcnt(6)
	v_mfma_f32_32x32x16_bf16 v[2:17], v[98:101], v[154:157], v[2:17]
	v_sub_f32_e32 v106, v106, v152
	v_sub_f32_e32 v107, v107, v152
	v_sub_f32_e32 v108, v108, v152
	v_sub_f32_e32 v109, v109, v152
	ds_read_b64_tr_b16 v[154:155], v153 offset:24576
	ds_read_b64_tr_b16 v[156:157], v153 offset:27136
	s_waitcnt lgkmcnt(6)
	v_mfma_f32_32x32x16_bf16 v[50:65], v[98:101], v[190:193], v[50:65]
	v_sub_f32_e32 v110, v110, v152
	v_sub_f32_e32 v111, v111, v152
	v_sub_f32_e32 v112, v112, v152
	v_sub_f32_e32 v113, v113, v152
	ds_read_b64_tr_b16 v[190:191], v153 offset:24640
	ds_read_b64_tr_b16 v[192:193], v153 offset:27200
	s_waitcnt lgkmcnt(6)
	v_mfma_f32_32x32x16_bf16 v[18:33], v[98:101], v[214:217], v[18:33]
	v_exp_f32_e32 v106, v106
	v_exp_f32_e32 v107, v107
	v_exp_f32_e32 v108, v108
	v_exp_f32_e32 v109, v109
	ds_read_b64_tr_b16 v[214:215], v153 offset:24704
	ds_read_b64_tr_b16 v[216:217], v153 offset:27264
	s_waitcnt lgkmcnt(6)
	v_mfma_f32_32x32x16_bf16 v[34:49], v[98:101], v[234:237], v[34:49]
	v_exp_f32_e32 v110, v110
	v_exp_f32_e32 v111, v111
	v_exp_f32_e32 v112, v112
	v_exp_f32_e32 v113, v113
	ds_read_b64_tr_b16 v[234:235], v153 offset:24768
	ds_read_b64_tr_b16 v[236:237], v153 offset:27328
	v_mfma_f32_32x32x16_bf16 v[66:81], v[98:101], v[86:89], v[66:81]
	v_cvt_pk_bf16_f32 v106, v106, v107
	v_cvt_pk_bf16_f32 v107, v108, v109
	v_cvt_pk_bf16_f32 v108, v110, v111
	v_cvt_pk_bf16_f32 v109, v112, v113
	s_nop 0
	s_waitcnt lgkmcnt(6)
	v_mfma_f32_32x32x16_bf16 v[2:17], v[106:109], v[154:157], v[2:17]
	s_waitcnt lgkmcnt(4)
	v_mfma_f32_32x32x16_bf16 v[50:65], v[106:109], v[190:193], v[50:65]
	s_waitcnt lgkmcnt(2)
	v_mfma_f32_32x32x16_bf16 v[18:33], v[106:109], v[214:217], v[18:33]
	s_waitcnt lgkmcnt(0)
	v_mfma_f32_32x32x16_bf16 v[34:49], v[106:109], v[234:237], v[34:49]
	v_mfma_f32_32x32x16_bf16 v[66:81], v[106:109], v[86:89], v[66:81]
	s_movk_i32 s77, 0x110
	s_andn2_b64 vcc, exec, s[62:63]
	s_cbranch_vccnz .LBB0_62
.LBB0_61:
	s_xor_b32 s23, s23, 1
	s_mulk_i32 s23, 0x7400
	s_add_i32 s23, s23, 0
	v_add3_u32 v82, s23, v163, v0
	v_add_u32_e32 v83, s23, v144
	v_add_u32_e32 v84, v83, v164
	v_add_u32_e32 v83, v83, v175
	s_waitcnt vmcnt(2)
	ds_write_b128 v82, v[122:125]
	s_waitcnt vmcnt(1)
	ds_write_b128 v84, v[134:137] offset:9216
	s_waitcnt vmcnt(0)
	ds_write_b128 v83, v[138:141] offset:9216

.LBB0_64:
	v_readlane_b32 s4, v255, 34
	v_readlane_b32 s5, v255, 35
	s_load_dwordx2 s[50:51], s[4:5], 0xb0
	v_rcp_f32_e32 v94, v69
	v_lshlrev_b32_e32 v69, 2, v145
	v_rcp_f32_e32 v98, v67
	v_rcp_f32_e32 v90, v71
	v_rcp_f32_e32 v86, v73
	s_waitcnt lgkmcnt(0)
	global_load_dword v67, v69, s[50:51]
	global_load_dword v71, v69, s[50:51] offset:128
	global_load_dword v73, v69, s[50:51] offset:256
	v_readlane_b32 s4, v251, 48
	global_load_dword v69, v69, s[50:51] offset:384
	v_rcp_f32_e32 v82, v75
	v_rcp_f32_e32 v96, v68
	v_rcp_f32_e32 v68, v79
	v_rcp_f32_e32 v88, v72
	v_rcp_f32_e32 v84, v74
	v_rcp_f32_e32 v74, v76
	v_rcp_f32_e32 v72, v77
	v_rcp_f32_e32 v100, v66
	v_mov_b32_e32 v106, v34
	v_mov_b32_e32 v107, v18
	s_mov_b32 s5, 0x800000
	v_rcp_f32_e32 v66, v80
	v_ashrrev_i32_e32 v80, 3, v162
	v_rcp_f32_e32 v92, v70
	v_rcp_f32_e32 v70, v78
	v_rcp_f32_e32 v0, v81
	v_and_b32_e32 v81, 0xffffffc, v80
	s_and_b32 s10, s67, 0x700
	s_addk_i32 s10, 0x100
	s_waitcnt vmcnt(3)
	v_mul_f32_e32 v67, 0x3f24fd5c, v67
	s_waitcnt vmcnt(2)
	v_mul_f32_e32 v71, 0x3f24fd5c, v71
	s_waitcnt vmcnt(1)
	v_mul_f32_e32 v73, 0x3f24fd5c, v73
	s_waitcnt vmcnt(0)
	v_mul_f32_e32 v75, 0x3f24fd5c, v69
	v_mov_b32_e32 v69, s4
	s_mov_b32 s4, 1
	v_add_u32_e32 v79, 0, v160
	ds_read2st64_b32 v[76:77], v79 offset1:1
	v_add_u32_e32 v69, 0, v69
	v_lshl_add_u32 v78, v145, 1, v69
	s_waitcnt lgkmcnt(0)
	v_lshlrev_b32_e32 v102, 16, v76
	v_and_b32_e32 v103, 0xffff0000, v76
	v_lshlrev_b32_e32 v105, 16, v77
	v_and_b32_e32 v104, 0xffff0000, v77
	v_mov_b32_e32 v76, v2
	v_mov_b32_e32 v77, v50
	v_pk_mul_f32 v[76:77], v[76:77], v[100:101] op_sel_hi:[1,0]
	v_pk_mul_f32 v[100:101], v[106:107], v[100:101] op_sel_hi:[1,0]
	v_pk_fma_f32 v[102:103], v[142:143], v[76:77], v[102:103] neg_lo:[1,0,0] neg_hi:[1,0,0]
	v_pk_fma_f32 v[100:101], v[142:143], v[100:101], v[104:105] neg_lo:[1,0,0] neg_hi:[1,0,0]
	v_pk_mul_f32 v[76:77], v[102:103], v[102:103]
	v_pk_mul_f32 v[104:105], v[100:101], v[100:101]
	v_add_f32_e32 v2, v76, v77
	v_add_f32_e32 v2, v2, v105
	v_add_f32_e32 v2, v104, v2
	v_mad_u64_u32 v[76:77], s[22:23], v81, s77, v[78:79]
	s_waitcnt lgkmcnt(0)
	s_nop 1
	v_add_f32_dpp v2, v2, v2 quad_perm:[1,0,3,2] row_mask:0xf bank_mask:0xf
	s_waitcnt lgkmcnt(0)
	s_nop 1
	v_add_f32_dpp v2, v2, v2 quad_perm:[2,3,0,1] row_mask:0xf bank_mask:0xf
	s_waitcnt lgkmcnt(0)
	s_nop 1
	v_add_f32_dpp v2, v2, v2 row_half_mirror row_mask:0xf bank_mask:0xf
	s_waitcnt lgkmcnt(0)
	s_nop 1
	v_add_f32_dpp v2, v2, v2 row_mirror row_mask:0xf bank_mask:0xf
	ds_bpermute_b32 v18, v170, v2
	s_waitcnt lgkmcnt(0)
	v_add_f32_e32 v2, v2, v18
	v_fmamk_f32 v2, v2, 0x3c000000, v249
	v_cmp_gt_f32_e32 vcc, s5, v2
	v_mul_f32_e32 v18, 0x4b800000, v2
	s_nop 0
	v_cndmask_b32_e32 v2, v2, v18, vcc
	v_rsq_f32_e32 v2, v2
	s_nop 0
	v_mul_f32_e32 v18, 0x45800000, v2
	v_cndmask_b32_e32 v2, v2, v18, vcc
	v_mul_f32_e32 v18, v102, v2
	v_mul_f32_e32 v18, v67, v18
	v_cvt_pk_bf16_f32 v18, v18, s0
	ds_write_b16 v76, v18
	v_mul_f32_e32 v18, v103, v2
	v_mul_f32_e32 v18, v71, v18
	v_cvt_pk_bf16_f32 v18, v18, s0
	ds_write_b16 v76, v18 offset:64
	v_mul_f32_e32 v18, v101, v2
	v_mul_f32_e32 v2, v100, v2
	v_mul_f32_e32 v18, v73, v18
	v_mul_f32_e32 v2, v75, v2
	v_cvt_pk_bf16_f32 v18, v18, s0
	v_cvt_pk_bf16_f32 v2, v2, s0
	ds_write_b16 v76, v18 offset:128
	ds_write_b16 v76, v2 offset:192
	ds_read2st64_b32 v[100:101], v79 offset0:2 offset1:3
	v_mov_b32_e32 v50, v3
	v_pk_mul_f32 v[50:51], v[50:51], v[98:99] op_sel_hi:[1,0]
	v_mov_b32_e32 v18, v35
	v_pk_mul_f32 v[18:19], v[18:19], v[98:99] op_sel_hi:[1,0]
	s_waitcnt lgkmcnt(0)
	v_lshlrev_b32_e32 v2, 16, v100
	v_and_b32_e32 v3, 0xffff0000, v100
	v_lshlrev_b32_e32 v103, 16, v101
	v_and_b32_e32 v102, 0xffff0000, v101
	v_pk_fma_f32 v[2:3], v[142:143], v[50:51], v[2:3] neg_lo:[1,0,0] neg_hi:[1,0,0]
	v_pk_fma_f32 v[18:19], v[142:143], v[18:19], v[102:103] neg_lo:[1,0,0] neg_hi:[1,0,0]
	v_pk_mul_f32 v[50:51], v[2:3], v[2:3]
	v_pk_mul_f32 v[34:35], v[18:19], v[18:19]
	v_add_f32_e32 v50, v50, v51
	v_add_f32_e32 v35, v50, v35
	v_add_f32_e32 v34, v34, v35
	s_waitcnt lgkmcnt(0)
	s_nop 1
	v_add_f32_dpp v34, v34, v34 quad_perm:[1,0,3,2] row_mask:0xf bank_mask:0xf
	s_waitcnt lgkmcnt(0)
	s_nop 1
	v_add_f32_dpp v34, v34, v34 quad_perm:[2,3,0,1] row_mask:0xf bank_mask:0xf
	s_waitcnt lgkmcnt(0)
	s_nop 1
	v_add_f32_dpp v34, v34, v34 row_half_mirror row_mask:0xf bank_mask:0xf
	s_waitcnt lgkmcnt(0)
	s_nop 1
	v_add_f32_dpp v34, v34, v34 row_mirror row_mask:0xf bank_mask:0xf
	ds_bpermute_b32 v35, v170, v34
	s_waitcnt lgkmcnt(0)
	v_add_f32_e32 v34, v34, v35
	v_fmamk_f32 v34, v34, 0x3c000000, v249
	v_mul_f32_e32 v35, 0x4b800000, v34
	v_cmp_gt_f32_e32 vcc, s5, v34
	s_nop 1
	v_cndmask_b32_e32 v34, v34, v35, vcc
	v_rsq_f32_e32 v34, v34
	s_nop 0
	v_mul_f32_e32 v35, 0x45800000, v34
	v_cndmask_b32_e32 v34, v34, v35, vcc
	v_mul_f32_e32 v2, v2, v34
	v_mul_f32_e32 v3, v3, v34
	v_mul_f32_e32 v19, v19, v34
	v_mul_f32_e32 v18, v18, v34
	v_mul_f32_e32 v2, v67, v2
	v_mul_f32_e32 v3, v71, v3
	v_mul_f32_e32 v19, v73, v19
	v_mul_f32_e32 v18, v75, v18
	v_cvt_pk_bf16_f32 v2, v2, s0
	v_cvt_pk_bf16_f32 v3, v3, s0
	v_cvt_pk_bf16_f32 v19, v19, s0
	v_cvt_pk_bf16_f32 v18, v18, s0
	ds_write_b16 v76, v2 offset:272
	ds_write_b16 v76, v3 offset:336
	ds_write_b16 v76, v19 offset:400
	ds_write_b16 v76, v18 offset:464
	ds_read2st64_b32 v[2:3], v79 offset0:4 offset1:5
	v_mov_b32_e32 v18, v4
	v_mov_b32_e32 v19, v52
	s_waitcnt lgkmcnt(0)
	v_lshlrev_b32_e32 v34, 16, v2
	v_and_b32_e32 v35, 0xffff0000, v2
	v_lshlrev_b32_e32 v51, 16, v3
	v_and_b32_e32 v50, 0xffff0000, v3
	v_pk_mul_f32 v[2:3], v[18:19], v[96:97] op_sel_hi:[1,0]
	s_nop 0
	v_pk_fma_f32 v[2:3], v[142:143], v[2:3], v[34:35] neg_lo:[1,0,0] neg_hi:[1,0,0]
	v_mov_b32_e32 v34, v36
	v_mov_b32_e32 v35, v20
	v_pk_mul_f32 v[34:35], v[34:35], v[96:97] op_sel_hi:[1,0]
	v_pk_mul_f32 v[18:19], v[2:3], v[2:3]
	v_pk_fma_f32 v[34:35], v[142:143], v[34:35], v[50:51] neg_lo:[1,0,0] neg_hi:[1,0,0]
	v_add_f32_e32 v4, v18, v19
	v_pk_mul_f32 v[50:51], v[34:35], v[34:35]
	s_nop 0
	v_add_f32_e32 v4, v4, v51
	v_add_f32_e32 v4, v50, v4
	s_waitcnt lgkmcnt(0)
	s_nop 1
	v_add_f32_dpp v4, v4, v4 quad_perm:[1,0,3,2] row_mask:0xf bank_mask:0xf
	s_waitcnt lgkmcnt(0)
	s_nop 1
	v_add_f32_dpp v4, v4, v4 quad_perm:[2,3,0,1] row_mask:0xf bank_mask:0xf
	s_waitcnt lgkmcnt(0)
	s_nop 1
	v_add_f32_dpp v4, v4, v4 row_half_mirror row_mask:0xf bank_mask:0xf
	s_waitcnt lgkmcnt(0)
	s_nop 1
	v_add_f32_dpp v4, v4, v4 row_mirror row_mask:0xf bank_mask:0xf
	ds_bpermute_b32 v18, v170, v4
	s_waitcnt lgkmcnt(0)
	v_add_f32_e32 v4, v4, v18
	v_fmamk_f32 v4, v4, 0x3c000000, v249
	v_mul_f32_e32 v18, 0x4b800000, v4
	v_cmp_gt_f32_e32 vcc, s5, v4
	s_nop 1
	v_cndmask_b32_e32 v4, v4, v18, vcc
	v_rsq_f32_e32 v4, v4
	s_nop 0
	v_mul_f32_e32 v18, 0x45800000, v4
	v_cndmask_b32_e32 v4, v4, v18, vcc
	v_mul_f32_e32 v2, v2, v4
	v_mul_f32_e32 v3, v3, v4
	v_mul_f32_e32 v18, v35, v4
	v_mul_f32_e32 v4, v34, v4
	v_mul_f32_e32 v2, v67, v2
	v_mul_f32_e32 v3, v71, v3
	v_mul_f32_e32 v18, v73, v18
	v_mul_f32_e32 v4, v75, v4
	v_cvt_pk_bf16_f32 v2, v2, s0
	v_cvt_pk_bf16_f32 v3, v3, s0
	v_cvt_pk_bf16_f32 v18, v18, s0
	v_cvt_pk_bf16_f32 v4, v4, s0
	ds_write_b16 v76, v2 offset:544
	ds_write_b16 v76, v3 offset:608
	ds_write_b16 v76, v18 offset:672
	ds_write_b16 v76, v4 offset:736
	ds_read2st64_b32 v[2:3], v79 offset0:6 offset1:7
	v_mov_b32_e32 v52, v5
	v_mov_b32_e32 v20, v37
	s_waitcnt lgkmcnt(0)
	v_lshlrev_b32_e32 v18, 16, v2
	v_and_b32_e32 v19, 0xffff0000, v2
	v_lshlrev_b32_e32 v35, 16, v3
	v_and_b32_e32 v34, 0xffff0000, v3
	v_pk_mul_f32 v[2:3], v[52:53], v[94:95] op_sel_hi:[1,0]
	s_nop 0
	v_pk_fma_f32 v[4:5], v[142:143], v[2:3], v[18:19] neg_lo:[1,0,0] neg_hi:[1,0,0]
	v_pk_mul_f32 v[18:19], v[20:21], v[94:95] op_sel_hi:[1,0]
	v_pk_mul_f32 v[2:3], v[4:5], v[4:5]
	v_pk_fma_f32 v[18:19], v[142:143], v[18:19], v[34:35] neg_lo:[1,0,0] neg_hi:[1,0,0]
	v_add_f32_e32 v2, v2, v3
	v_pk_mul_f32 v[20:21], v[18:19], v[18:19]
	s_nop 0
	v_add_f32_e32 v2, v2, v21
	v_add_f32_e32 v2, v20, v2
	s_waitcnt lgkmcnt(0)
	s_nop 1
	v_add_f32_dpp v2, v2, v2 quad_perm:[1,0,3,2] row_mask:0xf bank_mask:0xf
	s_waitcnt lgkmcnt(0)
	s_nop 1
	v_add_f32_dpp v2, v2, v2 quad_perm:[2,3,0,1] row_mask:0xf bank_mask:0xf
	s_waitcnt lgkmcnt(0)
	s_nop 1
	v_add_f32_dpp v2, v2, v2 row_half_mirror row_mask:0xf bank_mask:0xf
	s_waitcnt lgkmcnt(0)
	s_nop 1
	v_add_f32_dpp v2, v2, v2 row_mirror row_mask:0xf bank_mask:0xf
	ds_bpermute_b32 v3, v170, v2
	s_waitcnt lgkmcnt(0)
	v_add_f32_e32 v2, v2, v3
	v_fmamk_f32 v2, v2, 0x3c000000, v249
	v_cmp_gt_f32_e32 vcc, s5, v2
	v_mul_f32_e32 v3, 0x4b800000, v2
	s_nop 0
	v_cndmask_b32_e32 v2, v2, v3, vcc
	v_rsq_f32_e32 v2, v2
	s_nop 0
	v_mul_f32_e32 v3, 0x45800000, v2
	v_cndmask_b32_e32 v20, v2, v3, vcc
	v_or_b32_e32 v2, 3, v80
	v_mad_u64_u32 v[2:3], s[22:23], v2, s77, v[78:79]
	v_mul_f32_e32 v3, v4, v20
	v_mul_f32_e32 v3, v67, v3
	v_cvt_pk_bf16_f32 v3, v3, s0
	ds_write_b16 v2, v3
	v_mul_f32_e32 v3, v5, v20
	v_mul_f32_e32 v3, v71, v3
	v_cvt_pk_bf16_f32 v3, v3, s0
	ds_write_b16 v2, v3 offset:64
	v_mul_f32_e32 v3, v19, v20
	v_mul_f32_e32 v3, v73, v3
	v_cvt_pk_bf16_f32 v3, v3, s0
	ds_write_b16 v2, v3 offset:128
	v_mul_f32_e32 v3, v18, v20
	v_mul_f32_e32 v3, v75, v3
	v_cvt_pk_bf16_f32 v3, v3, s0
	ds_write_b16 v2, v3 offset:192
	ds_read2st64_b32 v[4:5], v79 offset0:8 offset1:9
	v_mov_b32_e32 v18, v6
	v_mov_b32_e32 v19, v54
	s_waitcnt lgkmcnt(0)
	v_lshlrev_b32_e32 v20, 16, v4
	v_and_b32_e32 v21, 0xffff0000, v4
	v_lshlrev_b32_e32 v35, 16, v5
	v_and_b32_e32 v34, 0xffff0000, v5
	v_pk_mul_f32 v[4:5], v[18:19], v[92:93] op_sel_hi:[1,0]
	s_nop 0
	v_pk_fma_f32 v[4:5], v[142:143], v[4:5], v[20:21] neg_lo:[1,0,0] neg_hi:[1,0,0]
	v_mov_b32_e32 v20, v38
	v_mov_b32_e32 v21, v22
	v_pk_mul_f32 v[20:21], v[20:21], v[92:93] op_sel_hi:[1,0]
	v_pk_mul_f32 v[18:19], v[4:5], v[4:5]
	v_pk_fma_f32 v[20:21], v[142:143], v[20:21], v[34:35] neg_lo:[1,0,0] neg_hi:[1,0,0]
	v_add_f32_e32 v3, v18, v19
	v_pk_mul_f32 v[34:35], v[20:21], v[20:21]
	s_nop 0
	v_add_f32_e32 v3, v3, v35
	v_add_f32_e32 v3, v34, v3
	s_waitcnt lgkmcnt(0)
	s_nop 1
	v_add_f32_dpp v3, v3, v3 quad_perm:[1,0,3,2] row_mask:0xf bank_mask:0xf
	s_waitcnt lgkmcnt(0)
	s_nop 1
	v_add_f32_dpp v3, v3, v3 quad_perm:[2,3,0,1] row_mask:0xf bank_mask:0xf
	s_waitcnt lgkmcnt(0)
	s_nop 1
	v_add_f32_dpp v3, v3, v3 row_half_mirror row_mask:0xf bank_mask:0xf
	s_waitcnt lgkmcnt(0)
	s_nop 1
	v_add_f32_dpp v3, v3, v3 row_mirror row_mask:0xf bank_mask:0xf
	ds_bpermute_b32 v6, v170, v3
	s_waitcnt lgkmcnt(0)
	v_add_f32_e32 v3, v3, v6
	v_fmamk_f32 v3, v3, 0x3c000000, v249
	v_mul_f32_e32 v6, 0x4b800000, v3
	v_cmp_gt_f32_e32 vcc, s5, v3
	s_nop 1
	v_cndmask_b32_e32 v3, v3, v6, vcc
	v_rsq_f32_e32 v3, v3
	s_nop 0
	v_mul_f32_e32 v6, 0x45800000, v3
	v_cndmask_b32_e32 v3, v3, v6, vcc
	v_mul_f32_e32 v4, v4, v3
	v_mul_f32_e32 v5, v5, v3
	v_mul_f32_e32 v6, v21, v3
	v_mul_f32_e32 v3, v20, v3
	v_mul_f32_e32 v4, v67, v4
	v_mul_f32_e32 v5, v71, v5
	v_mul_f32_e32 v6, v73, v6
	v_mul_f32_e32 v3, v75, v3
	v_cvt_pk_bf16_f32 v4, v4, s0
	v_cvt_pk_bf16_f32 v5, v5, s0
	v_cvt_pk_bf16_f32 v6, v6, s0
	v_cvt_pk_bf16_f32 v3, v3, s0
	ds_write_b16 v76, v4 offset:2176
	ds_write_b16 v76, v5 offset:2240
	ds_write_b16 v76, v6 offset:2304
	ds_write_b16 v76, v3 offset:2368
	ds_read2st64_b32 v[4:5], v79 offset0:10 offset1:11
	v_mov_b32_e32 v54, v7
	v_mov_b32_e32 v22, v39
	v_pk_mul_f32 v[20:21], v[22:23], v[90:91] op_sel_hi:[1,0]
	s_waitcnt lgkmcnt(0)
	v_lshlrev_b32_e32 v6, 16, v4
	v_and_b32_e32 v7, 0xffff0000, v4
	v_lshlrev_b32_e32 v19, 16, v5
	v_and_b32_e32 v18, 0xffff0000, v5
	v_pk_mul_f32 v[4:5], v[54:55], v[90:91] op_sel_hi:[1,0]
	v_pk_fma_f32 v[18:19], v[142:143], v[20:21], v[18:19] neg_lo:[1,0,0] neg_hi:[1,0,0]
	v_pk_fma_f32 v[4:5], v[142:143], v[4:5], v[6:7] neg_lo:[1,0,0] neg_hi:[1,0,0]
	v_pk_mul_f32 v[20:21], v[18:19], v[18:19]
	v_pk_mul_f32 v[6:7], v[4:5], v[4:5]
	s_nop 0
	v_add_f32_e32 v3, v6, v7
	v_add_f32_e32 v3, v3, v21
	v_add_f32_e32 v3, v20, v3
	s_waitcnt lgkmcnt(0)
	s_nop 1
	v_add_f32_dpp v3, v3, v3 quad_perm:[1,0,3,2] row_mask:0xf bank_mask:0xf
	s_waitcnt lgkmcnt(0)
	s_nop 1
	v_add_f32_dpp v3, v3, v3 quad_perm:[2,3,0,1] row_mask:0xf bank_mask:0xf
	s_waitcnt lgkmcnt(0)
	s_nop 1
	v_add_f32_dpp v3, v3, v3 row_half_mirror row_mask:0xf bank_mask:0xf
	s_waitcnt lgkmcnt(0)
	s_nop 1
	v_add_f32_dpp v3, v3, v3 row_mirror row_mask:0xf bank_mask:0xf
	ds_bpermute_b32 v6, v170, v3
	s_waitcnt lgkmcnt(0)
	v_add_f32_e32 v3, v3, v6
	v_fmamk_f32 v3, v3, 0x3c000000, v249
	v_mul_f32_e32 v6, 0x4b800000, v3
	v_cmp_gt_f32_e32 vcc, s5, v3
	s_nop 1
	v_cndmask_b32_e32 v3, v3, v6, vcc
	v_rsq_f32_e32 v3, v3
	s_nop 0
	v_mul_f32_e32 v6, 0x45800000, v3
	v_cndmask_b32_e32 v3, v3, v6, vcc
	v_mul_f32_e32 v4, v4, v3
	v_mul_f32_e32 v5, v5, v3
	v_mul_f32_e32 v6, v19, v3
	v_mul_f32_e32 v3, v18, v3
	v_mul_f32_e32 v4, v67, v4
	v_mul_f32_e32 v5, v71, v5
	v_mul_f32_e32 v6, v73, v6
	v_mul_f32_e32 v3, v75, v3
	v_cvt_pk_bf16_f32 v4, v4, s0
	v_cvt_pk_bf16_f32 v5, v5, s0
	v_cvt_pk_bf16_f32 v6, v6, s0
	v_cvt_pk_bf16_f32 v3, v3, s0
	ds_write_b16 v76, v4 offset:2448
	ds_write_b16 v76, v5 offset:2512
	ds_write_b16 v76, v6 offset:2576
	ds_write_b16 v76, v3 offset:2640
	ds_read2st64_b32 v[4:5], v79 offset0:12 offset1:13
	v_mov_b32_e32 v6, v8
	v_mov_b32_e32 v7, v56
	s_waitcnt lgkmcnt(0)
	v_lshlrev_b32_e32 v18, 16, v4
	v_and_b32_e32 v19, 0xffff0000, v4
	v_lshlrev_b32_e32 v21, 16, v5
	v_and_b32_e32 v20, 0xffff0000, v5
	v_pk_mul_f32 v[4:5], v[6:7], v[88:89] op_sel_hi:[1,0]
	s_nop 0
	v_pk_fma_f32 v[4:5], v[142:143], v[4:5], v[18:19] neg_lo:[1,0,0] neg_hi:[1,0,0]
	v_mov_b32_e32 v18, v40
	v_mov_b32_e32 v19, v24
	v_pk_mul_f32 v[18:19], v[18:19], v[88:89] op_sel_hi:[1,0]
	v_pk_mul_f32 v[6:7], v[4:5], v[4:5]
	v_pk_fma_f32 v[18:19], v[142:143], v[18:19], v[20:21] neg_lo:[1,0,0] neg_hi:[1,0,0]
	v_add_f32_e32 v3, v6, v7
	v_pk_mul_f32 v[20:21], v[18:19], v[18:19]
	s_nop 0
	v_add_f32_e32 v3, v3, v21
	v_add_f32_e32 v3, v20, v3
	s_waitcnt lgkmcnt(0)
	s_nop 1
	v_add_f32_dpp v3, v3, v3 quad_perm:[1,0,3,2] row_mask:0xf bank_mask:0xf
	s_waitcnt lgkmcnt(0)
	s_nop 1
	v_add_f32_dpp v3, v3, v3 quad_perm:[2,3,0,1] row_mask:0xf bank_mask:0xf
	s_waitcnt lgkmcnt(0)
	s_nop 1
	v_add_f32_dpp v3, v3, v3 row_half_mirror row_mask:0xf bank_mask:0xf
	s_waitcnt lgkmcnt(0)
	s_nop 1
	v_add_f32_dpp v3, v3, v3 row_mirror row_mask:0xf bank_mask:0xf
	ds_bpermute_b32 v6, v170, v3
	s_waitcnt lgkmcnt(0)
	v_add_f32_e32 v3, v3, v6
	v_fmamk_f32 v3, v3, 0x3c000000, v249
	v_mul_f32_e32 v6, 0x4b800000, v3
	v_cmp_gt_f32_e32 vcc, s5, v3
	s_nop 1
	v_cndmask_b32_e32 v3, v3, v6, vcc
	v_rsq_f32_e32 v3, v3
	s_nop 0
	v_mul_f32_e32 v6, 0x45800000, v3
	v_cndmask_b32_e32 v3, v3, v6, vcc
	v_mul_f32_e32 v4, v4, v3
	v_mul_f32_e32 v5, v5, v3
	v_mul_f32_e32 v6, v19, v3
	v_mul_f32_e32 v3, v18, v3
	v_mul_f32_e32 v4, v67, v4
	v_mul_f32_e32 v5, v71, v5
	v_mul_f32_e32 v6, v73, v6
	v_mul_f32_e32 v3, v75, v3
	v_cvt_pk_bf16_f32 v4, v4, s0
	v_cvt_pk_bf16_f32 v5, v5, s0
	v_cvt_pk_bf16_f32 v6, v6, s0
	v_cvt_pk_bf16_f32 v3, v3, s0
	ds_write_b16 v76, v4 offset:2720
	ds_write_b16 v76, v5 offset:2784
	ds_write_b16 v76, v6 offset:2848
	ds_write_b16 v76, v3 offset:2912
	ds_read2st64_b32 v[4:5], v79 offset0:14 offset1:15
	v_mov_b32_e32 v56, v9
	v_mov_b32_e32 v24, v41
	v_pk_mul_f32 v[18:19], v[24:25], v[86:87] op_sel_hi:[1,0]
	s_waitcnt lgkmcnt(0)
	v_lshlrev_b32_e32 v6, 16, v4
	v_and_b32_e32 v7, 0xffff0000, v4
	v_lshlrev_b32_e32 v9, 16, v5
	v_and_b32_e32 v8, 0xffff0000, v5
	v_pk_mul_f32 v[4:5], v[56:57], v[86:87] op_sel_hi:[1,0]
	v_pk_fma_f32 v[8:9], v[142:143], v[18:19], v[8:9] neg_lo:[1,0,0] neg_hi:[1,0,0]
	v_pk_fma_f32 v[4:5], v[142:143], v[4:5], v[6:7] neg_lo:[1,0,0] neg_hi:[1,0,0]
	v_pk_mul_f32 v[18:19], v[8:9], v[8:9]
	v_pk_mul_f32 v[6:7], v[4:5], v[4:5]
	s_nop 0
	v_add_f32_e32 v3, v6, v7
	v_add_f32_e32 v3, v3, v19
	v_add_f32_e32 v3, v18, v3
	s_waitcnt lgkmcnt(0)
	s_nop 1
	v_add_f32_dpp v3, v3, v3 quad_perm:[1,0,3,2] row_mask:0xf bank_mask:0xf
	s_waitcnt lgkmcnt(0)
	s_nop 1
	v_add_f32_dpp v3, v3, v3 quad_perm:[2,3,0,1] row_mask:0xf bank_mask:0xf
	s_waitcnt lgkmcnt(0)
	s_nop 1
	v_add_f32_dpp v3, v3, v3 row_half_mirror row_mask:0xf bank_mask:0xf
	s_waitcnt lgkmcnt(0)
	s_nop 1
	v_add_f32_dpp v3, v3, v3 row_mirror row_mask:0xf bank_mask:0xf
	ds_bpermute_b32 v6, v170, v3
	s_waitcnt lgkmcnt(0)
	v_add_f32_e32 v3, v3, v6
	v_fmamk_f32 v3, v3, 0x3c000000, v249
	v_mul_f32_e32 v6, 0x4b800000, v3
	v_cmp_gt_f32_e32 vcc, s5, v3
	s_nop 1
	v_cndmask_b32_e32 v3, v3, v6, vcc
	v_rsq_f32_e32 v3, v3
	s_nop 0
	v_mul_f32_e32 v6, 0x45800000, v3
	v_cndmask_b32_e32 v3, v3, v6, vcc
	v_mul_f32_e32 v4, v4, v3
	v_mul_f32_e32 v5, v5, v3
	v_mul_f32_e32 v6, v9, v3
	v_mul_f32_e32 v3, v8, v3
	v_mul_f32_e32 v4, v67, v4
	v_mul_f32_e32 v5, v71, v5
	v_mul_f32_e32 v6, v73, v6
	v_mul_f32_e32 v3, v75, v3
	v_cvt_pk_bf16_f32 v4, v4, s0
	v_cvt_pk_bf16_f32 v5, v5, s0
	v_cvt_pk_bf16_f32 v6, v6, s0
	v_cvt_pk_bf16_f32 v3, v3, s0
	ds_write_b16 v2, v4 offset:2176
	ds_write_b16 v2, v5 offset:2240
	ds_write_b16 v2, v6 offset:2304
	ds_write_b16 v2, v3 offset:2368
	ds_read2st64_b32 v[4:5], v79 offset0:16 offset1:17
	v_mov_b32_e32 v6, v10
	v_mov_b32_e32 v7, v58
	s_waitcnt lgkmcnt(0)
	v_lshlrev_b32_e32 v8, 16, v4
	v_and_b32_e32 v9, 0xffff0000, v4
	v_lshlrev_b32_e32 v19, 16, v5
	v_and_b32_e32 v18, 0xffff0000, v5
	v_pk_mul_f32 v[4:5], v[6:7], v[84:85] op_sel_hi:[1,0]
	s_nop 0
	v_pk_fma_f32 v[4:5], v[142:143], v[4:5], v[8:9] neg_lo:[1,0,0] neg_hi:[1,0,0]
	v_mov_b32_e32 v8, v42
	v_mov_b32_e32 v9, v26
	v_pk_mul_f32 v[8:9], v[8:9], v[84:85] op_sel_hi:[1,0]
	v_pk_mul_f32 v[6:7], v[4:5], v[4:5]
	v_pk_fma_f32 v[8:9], v[142:143], v[8:9], v[18:19] neg_lo:[1,0,0] neg_hi:[1,0,0]
	v_add_f32_e32 v3, v6, v7
	v_pk_mul_f32 v[18:19], v[8:9], v[8:9]
	s_nop 0
	v_add_f32_e32 v3, v3, v19
	v_add_f32_e32 v3, v18, v3
	s_waitcnt lgkmcnt(0)
	s_nop 1
	v_add_f32_dpp v3, v3, v3 quad_perm:[1,0,3,2] row_mask:0xf bank_mask:0xf
	s_waitcnt lgkmcnt(0)
	s_nop 1
	v_add_f32_dpp v3, v3, v3 quad_perm:[2,3,0,1] row_mask:0xf bank_mask:0xf
	s_waitcnt lgkmcnt(0)
	s_nop 1
	v_add_f32_dpp v3, v3, v3 row_half_mirror row_mask:0xf bank_mask:0xf
	s_waitcnt lgkmcnt(0)
	s_nop 1
	v_add_f32_dpp v3, v3, v3 row_mirror row_mask:0xf bank_mask:0xf
	ds_bpermute_b32 v6, v170, v3
	s_waitcnt lgkmcnt(0)
	v_add_f32_e32 v3, v3, v6
	v_fmamk_f32 v3, v3, 0x3c000000, v249
	v_mul_f32_e32 v6, 0x4b800000, v3
	v_cmp_gt_f32_e32 vcc, s5, v3
	s_nop 1
	v_cndmask_b32_e32 v3, v3, v6, vcc
	v_rsq_f32_e32 v3, v3
	s_nop 0
	v_mul_f32_e32 v6, 0x45800000, v3
	v_cndmask_b32_e32 v3, v3, v6, vcc
	v_mul_f32_e32 v4, v4, v3
	v_mul_f32_e32 v5, v5, v3
	v_mul_f32_e32 v6, v9, v3
	v_mul_f32_e32 v3, v8, v3
	v_mul_f32_e32 v4, v67, v4
	v_mul_f32_e32 v5, v71, v5
	v_mul_f32_e32 v6, v73, v6
	v_mul_f32_e32 v3, v75, v3
	v_cvt_pk_bf16_f32 v4, v4, s0
	v_cvt_pk_bf16_f32 v5, v5, s0
	v_cvt_pk_bf16_f32 v6, v6, s0
	v_cvt_pk_bf16_f32 v3, v3, s0
	ds_write_b16 v76, v4 offset:4352
	ds_write_b16 v76, v5 offset:4416
	ds_write_b16 v76, v6 offset:4480
	ds_write_b16 v76, v3 offset:4544
	ds_read2st64_b32 v[4:5], v79 offset0:18 offset1:19
	v_mov_b32_e32 v58, v11
	v_mov_b32_e32 v26, v43
	v_pk_mul_f32 v[10:11], v[26:27], v[82:83] op_sel_hi:[1,0]
	s_waitcnt lgkmcnt(0)
	v_lshlrev_b32_e32 v6, 16, v4
	v_and_b32_e32 v7, 0xffff0000, v4
	v_lshlrev_b32_e32 v9, 16, v5
	v_and_b32_e32 v8, 0xffff0000, v5
	v_pk_mul_f32 v[4:5], v[58:59], v[82:83] op_sel_hi:[1,0]
	v_pk_fma_f32 v[8:9], v[142:143], v[10:11], v[8:9] neg_lo:[1,0,0] neg_hi:[1,0,0]
	v_pk_fma_f32 v[4:5], v[142:143], v[4:5], v[6:7] neg_lo:[1,0,0] neg_hi:[1,0,0]
	v_pk_mul_f32 v[10:11], v[8:9], v[8:9]
	v_pk_mul_f32 v[6:7], v[4:5], v[4:5]
	s_nop 0
	v_add_f32_e32 v3, v6, v7
	v_add_f32_e32 v3, v3, v11
	v_add_f32_e32 v3, v10, v3
	s_waitcnt lgkmcnt(0)
	s_nop 1
	v_add_f32_dpp v3, v3, v3 quad_perm:[1,0,3,2] row_mask:0xf bank_mask:0xf
	s_waitcnt lgkmcnt(0)
	s_nop 1
	v_add_f32_dpp v3, v3, v3 quad_perm:[2,3,0,1] row_mask:0xf bank_mask:0xf
	s_waitcnt lgkmcnt(0)
	s_nop 1
	v_add_f32_dpp v3, v3, v3 row_half_mirror row_mask:0xf bank_mask:0xf
	s_waitcnt lgkmcnt(0)
	s_nop 1
	v_add_f32_dpp v3, v3, v3 row_mirror row_mask:0xf bank_mask:0xf
	ds_bpermute_b32 v6, v170, v3
	s_waitcnt lgkmcnt(0)
	v_add_f32_e32 v3, v3, v6
	v_fmamk_f32 v3, v3, 0x3c000000, v249
	v_mul_f32_e32 v6, 0x4b800000, v3
	v_cmp_gt_f32_e32 vcc, s5, v3
	s_nop 1
	v_cndmask_b32_e32 v3, v3, v6, vcc
	v_rsq_f32_e32 v3, v3
	s_nop 0
	v_mul_f32_e32 v6, 0x45800000, v3
	v_cndmask_b32_e32 v3, v3, v6, vcc
	v_mul_f32_e32 v4, v4, v3
	v_mul_f32_e32 v5, v5, v3
	v_mul_f32_e32 v6, v9, v3
	v_mul_f32_e32 v3, v8, v3
	v_mul_f32_e32 v4, v67, v4
	v_mul_f32_e32 v5, v71, v5
	v_mul_f32_e32 v6, v73, v6
	v_mul_f32_e32 v3, v75, v3
	v_cvt_pk_bf16_f32 v4, v4, s0
	v_cvt_pk_bf16_f32 v5, v5, s0
	v_cvt_pk_bf16_f32 v6, v6, s0
	v_cvt_pk_bf16_f32 v3, v3, s0
	ds_write_b16 v76, v4 offset:4624
	ds_write_b16 v76, v5 offset:4688
	ds_write_b16 v76, v6 offset:4752
	ds_write_b16 v76, v3 offset:4816
	ds_read2st64_b32 v[4:5], v79 offset0:20 offset1:21
	v_mov_b32_e32 v6, v12
	v_mov_b32_e32 v7, v60
	s_waitcnt lgkmcnt(0)
	v_lshlrev_b32_e32 v8, 16, v4
	v_and_b32_e32 v9, 0xffff0000, v4
	v_lshlrev_b32_e32 v11, 16, v5
	v_and_b32_e32 v10, 0xffff0000, v5
	v_pk_mul_f32 v[4:5], v[6:7], v[74:75] op_sel_hi:[1,0]
	s_nop 0
	v_pk_fma_f32 v[4:5], v[142:143], v[4:5], v[8:9] neg_lo:[1,0,0] neg_hi:[1,0,0]
	v_mov_b32_e32 v8, v44
	v_mov_b32_e32 v9, v28
	v_pk_mul_f32 v[8:9], v[8:9], v[74:75] op_sel_hi:[1,0]
	v_pk_mul_f32 v[6:7], v[4:5], v[4:5]
	v_pk_fma_f32 v[8:9], v[142:143], v[8:9], v[10:11] neg_lo:[1,0,0] neg_hi:[1,0,0]
	v_add_f32_e32 v3, v6, v7
	v_pk_mul_f32 v[10:11], v[8:9], v[8:9]
	s_nop 0
	v_add_f32_e32 v3, v3, v11
	v_add_f32_e32 v3, v10, v3
	s_waitcnt lgkmcnt(0)
	s_nop 1
	v_add_f32_dpp v3, v3, v3 quad_perm:[1,0,3,2] row_mask:0xf bank_mask:0xf
	s_waitcnt lgkmcnt(0)
	s_nop 1
	v_add_f32_dpp v3, v3, v3 quad_perm:[2,3,0,1] row_mask:0xf bank_mask:0xf
	s_waitcnt lgkmcnt(0)
	s_nop 1
	v_add_f32_dpp v3, v3, v3 row_half_mirror row_mask:0xf bank_mask:0xf
	s_waitcnt lgkmcnt(0)
	s_nop 1
	v_add_f32_dpp v3, v3, v3 row_mirror row_mask:0xf bank_mask:0xf
	ds_bpermute_b32 v6, v170, v3
	s_waitcnt lgkmcnt(0)
	v_add_f32_e32 v3, v3, v6
	v_fmamk_f32 v3, v3, 0x3c000000, v249
	v_mul_f32_e32 v6, 0x4b800000, v3
	v_cmp_gt_f32_e32 vcc, s5, v3
	s_nop 1
	v_cndmask_b32_e32 v3, v3, v6, vcc
	v_rsq_f32_e32 v3, v3
	s_nop 0
	v_mul_f32_e32 v6, 0x45800000, v3
	v_cndmask_b32_e32 v3, v3, v6, vcc
	v_mul_f32_e32 v4, v4, v3
	v_mul_f32_e32 v5, v5, v3
	v_mul_f32_e32 v6, v9, v3
	v_mul_f32_e32 v3, v8, v3
	v_mul_f32_e32 v4, v67, v4
	v_mul_f32_e32 v5, v71, v5
	v_mul_f32_e32 v6, v73, v6
	v_mul_f32_e32 v3, v75, v3
	v_cvt_pk_bf16_f32 v4, v4, s0
	v_cvt_pk_bf16_f32 v5, v5, s0
	v_cvt_pk_bf16_f32 v6, v6, s0
	v_cvt_pk_bf16_f32 v3, v3, s0
	ds_write_b16 v76, v4 offset:4896
	ds_write_b16 v76, v5 offset:4960
	ds_write_b16 v76, v6 offset:5024
	ds_write_b16 v76, v3 offset:5088
	ds_read2st64_b32 v[4:5], v79 offset0:22 offset1:23
	v_mov_b32_e32 v60, v13
	v_mov_b32_e32 v28, v45
	v_pk_mul_f32 v[10:11], v[28:29], v[72:73] op_sel_hi:[1,0]
	s_waitcnt lgkmcnt(0)
	v_lshlrev_b32_e32 v6, 16, v4
	v_and_b32_e32 v7, 0xffff0000, v4
	v_lshlrev_b32_e32 v9, 16, v5
	v_and_b32_e32 v8, 0xffff0000, v5
	v_pk_mul_f32 v[4:5], v[60:61], v[72:73] op_sel_hi:[1,0]
	v_pk_fma_f32 v[8:9], v[142:143], v[10:11], v[8:9] neg_lo:[1,0,0] neg_hi:[1,0,0]
	v_pk_fma_f32 v[4:5], v[142:143], v[4:5], v[6:7] neg_lo:[1,0,0] neg_hi:[1,0,0]
	v_pk_mul_f32 v[10:11], v[8:9], v[8:9]
	v_pk_mul_f32 v[6:7], v[4:5], v[4:5]
	s_nop 0
	v_add_f32_e32 v3, v6, v7
	v_add_f32_e32 v3, v3, v11
	v_add_f32_e32 v3, v10, v3
	s_waitcnt lgkmcnt(0)
	s_nop 1
	v_add_f32_dpp v3, v3, v3 quad_perm:[1,0,3,2] row_mask:0xf bank_mask:0xf
	s_waitcnt lgkmcnt(0)
	s_nop 1
	v_add_f32_dpp v3, v3, v3 quad_perm:[2,3,0,1] row_mask:0xf bank_mask:0xf
	s_waitcnt lgkmcnt(0)
	s_nop 1
	v_add_f32_dpp v3, v3, v3 row_half_mirror row_mask:0xf bank_mask:0xf
	s_waitcnt lgkmcnt(0)
	s_nop 1
	v_add_f32_dpp v3, v3, v3 row_mirror row_mask:0xf bank_mask:0xf
	ds_bpermute_b32 v6, v170, v3
	s_waitcnt lgkmcnt(0)
	v_add_f32_e32 v3, v3, v6
	v_fmamk_f32 v3, v3, 0x3c000000, v249
	v_mul_f32_e32 v6, 0x4b800000, v3
	v_cmp_gt_f32_e32 vcc, s5, v3
	s_nop 1
	v_cndmask_b32_e32 v3, v3, v6, vcc
	v_rsq_f32_e32 v3, v3
	s_nop 0
	v_mul_f32_e32 v6, 0x45800000, v3
	v_cndmask_b32_e32 v3, v3, v6, vcc
	v_mul_f32_e32 v4, v4, v3
	v_mul_f32_e32 v5, v5, v3
	v_mul_f32_e32 v6, v9, v3
	v_mul_f32_e32 v3, v8, v3
	v_mul_f32_e32 v4, v67, v4
	v_mul_f32_e32 v5, v71, v5
	v_mul_f32_e32 v6, v73, v6
	v_mul_f32_e32 v3, v75, v3
	v_cvt_pk_bf16_f32 v4, v4, s0
	v_cvt_pk_bf16_f32 v5, v5, s0
	v_cvt_pk_bf16_f32 v6, v6, s0
	v_cvt_pk_bf16_f32 v3, v3, s0
	ds_write_b16 v2, v4 offset:4352
	ds_write_b16 v2, v5 offset:4416
	ds_write_b16 v2, v6 offset:4480
	ds_write_b16 v2, v3 offset:4544
	ds_read2st64_b32 v[4:5], v79 offset0:24 offset1:25
	v_mov_b32_e32 v6, v14
	v_mov_b32_e32 v7, v62
	s_waitcnt lgkmcnt(0)
	v_lshlrev_b32_e32 v8, 16, v4
	v_and_b32_e32 v9, 0xffff0000, v4
	v_lshlrev_b32_e32 v11, 16, v5
	v_and_b32_e32 v10, 0xffff0000, v5
	v_pk_mul_f32 v[4:5], v[6:7], v[70:71] op_sel_hi:[1,0]
	s_nop 0
	v_pk_fma_f32 v[4:5], v[142:143], v[4:5], v[8:9] neg_lo:[1,0,0] neg_hi:[1,0,0]
	v_mov_b32_e32 v8, v46
	v_mov_b32_e32 v9, v30
	v_pk_mul_f32 v[8:9], v[8:9], v[70:71] op_sel_hi:[1,0]
	v_pk_mul_f32 v[6:7], v[4:5], v[4:5]
	v_pk_fma_f32 v[8:9], v[142:143], v[8:9], v[10:11] neg_lo:[1,0,0] neg_hi:[1,0,0]
	v_add_f32_e32 v3, v6, v7
	v_pk_mul_f32 v[10:11], v[8:9], v[8:9]
	s_nop 0
	v_add_f32_e32 v3, v3, v11
	v_add_f32_e32 v3, v10, v3
	s_waitcnt lgkmcnt(0)
	s_nop 1
	v_add_f32_dpp v3, v3, v3 quad_perm:[1,0,3,2] row_mask:0xf bank_mask:0xf
	s_waitcnt lgkmcnt(0)
	s_nop 1
	v_add_f32_dpp v3, v3, v3 quad_perm:[2,3,0,1] row_mask:0xf bank_mask:0xf
	s_waitcnt lgkmcnt(0)
	s_nop 1
	v_add_f32_dpp v3, v3, v3 row_half_mirror row_mask:0xf bank_mask:0xf
	s_waitcnt lgkmcnt(0)
	s_nop 1
	v_add_f32_dpp v3, v3, v3 row_mirror row_mask:0xf bank_mask:0xf
	ds_bpermute_b32 v6, v170, v3
	s_waitcnt lgkmcnt(0)
	v_add_f32_e32 v3, v3, v6
	v_fmamk_f32 v3, v3, 0x3c000000, v249
	v_mul_f32_e32 v6, 0x4b800000, v3
	v_cmp_gt_f32_e32 vcc, s5, v3
	s_nop 1
	v_cndmask_b32_e32 v3, v3, v6, vcc
	v_rsq_f32_e32 v3, v3
	s_nop 0
	v_mul_f32_e32 v6, 0x45800000, v3
	v_cndmask_b32_e32 v3, v3, v6, vcc
	v_mul_f32_e32 v4, v4, v3
	v_mul_f32_e32 v5, v5, v3
	v_mul_f32_e32 v6, v9, v3
	v_mul_f32_e32 v3, v8, v3
	v_mul_f32_e32 v4, v67, v4
	v_mul_f32_e32 v5, v71, v5
	v_mul_f32_e32 v6, v73, v6
	v_mul_f32_e32 v3, v75, v3
	v_cvt_pk_bf16_f32 v4, v4, s0
	v_cvt_pk_bf16_f32 v5, v5, s0
	v_cvt_pk_bf16_f32 v6, v6, s0
	v_cvt_pk_bf16_f32 v3, v3, s0
	ds_write_b16 v76, v4 offset:6528
	ds_write_b16 v76, v5 offset:6592
	ds_write_b16 v76, v6 offset:6656
	ds_write_b16 v76, v3 offset:6720
	ds_read2st64_b32 v[4:5], v79 offset0:26 offset1:27
	v_mov_b32_e32 v62, v15
	v_mov_b32_e32 v30, v47
	v_pk_mul_f32 v[10:11], v[30:31], v[68:69] op_sel_hi:[1,0]
	s_waitcnt lgkmcnt(0)
	v_lshlrev_b32_e32 v6, 16, v4
	v_and_b32_e32 v7, 0xffff0000, v4
	v_lshlrev_b32_e32 v9, 16, v5
	v_and_b32_e32 v8, 0xffff0000, v5
	v_pk_mul_f32 v[4:5], v[62:63], v[68:69] op_sel_hi:[1,0]
	v_pk_fma_f32 v[8:9], v[142:143], v[10:11], v[8:9] neg_lo:[1,0,0] neg_hi:[1,0,0]
	v_pk_fma_f32 v[4:5], v[142:143], v[4:5], v[6:7] neg_lo:[1,0,0] neg_hi:[1,0,0]
	v_pk_mul_f32 v[10:11], v[8:9], v[8:9]
	v_pk_mul_f32 v[6:7], v[4:5], v[4:5]
	s_nop 0
	v_add_f32_e32 v3, v6, v7
	v_add_f32_e32 v3, v3, v11
	v_add_f32_e32 v3, v10, v3
	s_waitcnt lgkmcnt(0)
	s_nop 1
	v_add_f32_dpp v3, v3, v3 quad_perm:[1,0,3,2] row_mask:0xf bank_mask:0xf
	s_waitcnt lgkmcnt(0)
	s_nop 1
	v_add_f32_dpp v3, v3, v3 quad_perm:[2,3,0,1] row_mask:0xf bank_mask:0xf
	s_waitcnt lgkmcnt(0)
	s_nop 1
	v_add_f32_dpp v3, v3, v3 row_half_mirror row_mask:0xf bank_mask:0xf
	s_waitcnt lgkmcnt(0)
	s_nop 1
	v_add_f32_dpp v3, v3, v3 row_mirror row_mask:0xf bank_mask:0xf
	ds_bpermute_b32 v6, v170, v3
	s_waitcnt lgkmcnt(0)
	v_add_f32_e32 v3, v3, v6
	v_fmamk_f32 v3, v3, 0x3c000000, v249
	v_mul_f32_e32 v6, 0x4b800000, v3
	v_cmp_gt_f32_e32 vcc, s5, v3
	s_nop 1
	v_cndmask_b32_e32 v3, v3, v6, vcc
	v_rsq_f32_e32 v3, v3
	s_nop 0
	v_mul_f32_e32 v6, 0x45800000, v3
	v_cndmask_b32_e32 v3, v3, v6, vcc
	v_mul_f32_e32 v4, v4, v3
	v_mul_f32_e32 v5, v5, v3
	v_mul_f32_e32 v6, v9, v3
	v_mul_f32_e32 v3, v8, v3
	v_mul_f32_e32 v4, v67, v4
	v_mul_f32_e32 v5, v71, v5
	v_mul_f32_e32 v6, v73, v6
	v_mul_f32_e32 v3, v75, v3
	v_cvt_pk_bf16_f32 v4, v4, s0
	v_cvt_pk_bf16_f32 v5, v5, s0
	v_cvt_pk_bf16_f32 v6, v6, s0
	v_cvt_pk_bf16_f32 v3, v3, s0
	ds_write_b16 v76, v4 offset:6800
	ds_write_b16 v76, v5 offset:6864
	ds_write_b16 v76, v6 offset:6928
	ds_write_b16 v76, v3 offset:6992
	ds_read2st64_b32 v[4:5], v79 offset0:28 offset1:29
	v_mov_b32_e32 v6, v16
	v_mov_b32_e32 v7, v64
	s_waitcnt lgkmcnt(0)
	v_lshlrev_b32_e32 v8, 16, v4
	v_and_b32_e32 v9, 0xffff0000, v4
	v_lshlrev_b32_e32 v11, 16, v5
	v_and_b32_e32 v10, 0xffff0000, v5
	v_pk_mul_f32 v[4:5], v[6:7], v[66:67] op_sel_hi:[1,0]
	s_nop 0
	v_pk_fma_f32 v[4:5], v[142:143], v[4:5], v[8:9] neg_lo:[1,0,0] neg_hi:[1,0,0]
	v_mov_b32_e32 v8, v48
	v_mov_b32_e32 v9, v32
	v_pk_mul_f32 v[8:9], v[8:9], v[66:67] op_sel_hi:[1,0]
	v_pk_mul_f32 v[6:7], v[4:5], v[4:5]
	v_pk_fma_f32 v[8:9], v[142:143], v[8:9], v[10:11] neg_lo:[1,0,0] neg_hi:[1,0,0]
	v_add_f32_e32 v3, v6, v7
	v_pk_mul_f32 v[10:11], v[8:9], v[8:9]
	s_nop 0
	v_add_f32_e32 v3, v3, v11
	v_add_f32_e32 v3, v10, v3
	s_waitcnt lgkmcnt(0)
	s_nop 1
	v_add_f32_dpp v3, v3, v3 quad_perm:[1,0,3,2] row_mask:0xf bank_mask:0xf
	s_waitcnt lgkmcnt(0)
	s_nop 1
	v_add_f32_dpp v3, v3, v3 quad_perm:[2,3,0,1] row_mask:0xf bank_mask:0xf
	s_waitcnt lgkmcnt(0)
	s_nop 1
	v_add_f32_dpp v3, v3, v3 row_half_mirror row_mask:0xf bank_mask:0xf
	s_waitcnt lgkmcnt(0)
	s_nop 1
	v_add_f32_dpp v3, v3, v3 row_mirror row_mask:0xf bank_mask:0xf
	ds_bpermute_b32 v6, v170, v3
	s_waitcnt lgkmcnt(0)
	v_add_f32_e32 v3, v3, v6
	v_fmamk_f32 v3, v3, 0x3c000000, v249
	v_mul_f32_e32 v6, 0x4b800000, v3
	v_cmp_gt_f32_e32 vcc, s5, v3
	s_nop 1
	v_cndmask_b32_e32 v3, v3, v6, vcc
	v_rsq_f32_e32 v3, v3
	s_nop 0
	v_mul_f32_e32 v6, 0x45800000, v3
	v_cndmask_b32_e32 v3, v3, v6, vcc
	v_mul_f32_e32 v4, v4, v3
	v_mul_f32_e32 v5, v5, v3
	v_mul_f32_e32 v6, v9, v3
	v_mul_f32_e32 v3, v8, v3
	v_mul_f32_e32 v4, v67, v4
	v_mul_f32_e32 v5, v71, v5
	v_mul_f32_e32 v6, v73, v6
	v_mul_f32_e32 v3, v75, v3
	v_cvt_pk_bf16_f32 v4, v4, s0
	v_cvt_pk_bf16_f32 v5, v5, s0
	v_cvt_pk_bf16_f32 v6, v6, s0
	v_cvt_pk_bf16_f32 v3, v3, s0
	ds_write_b16 v76, v4 offset:7072
	ds_write_b16 v76, v5 offset:7136
	ds_write_b16 v76, v6 offset:7200
	ds_write_b16 v76, v3 offset:7264
	ds_read2st64_b32 v[4:5], v79 offset0:30 offset1:31
	v_mov_b32_e32 v64, v17
	v_mov_b32_e32 v32, v49
	v_pk_mul_f32 v[10:11], v[32:33], v[0:1] op_sel_hi:[1,0]
	s_waitcnt lgkmcnt(0)
	v_lshlrev_b32_e32 v6, 16, v4
	v_and_b32_e32 v7, 0xffff0000, v4
	v_lshlrev_b32_e32 v9, 16, v5
	v_and_b32_e32 v8, 0xffff0000, v5
	v_pk_mul_f32 v[4:5], v[64:65], v[0:1] op_sel_hi:[1,0]
	v_pk_fma_f32 v[8:9], v[142:143], v[10:11], v[8:9] neg_lo:[1,0,0] neg_hi:[1,0,0]
	v_pk_fma_f32 v[4:5], v[142:143], v[4:5], v[6:7] neg_lo:[1,0,0] neg_hi:[1,0,0]
	v_pk_mul_f32 v[10:11], v[8:9], v[8:9]
	v_pk_mul_f32 v[6:7], v[4:5], v[4:5]
	s_nop 0
	v_add_f32_e32 v0, v6, v7
	v_add_f32_e32 v0, v0, v11
	v_add_f32_e32 v0, v10, v0
	s_waitcnt lgkmcnt(0)
	s_nop 1
	v_add_f32_dpp v0, v0, v0 quad_perm:[1,0,3,2] row_mask:0xf bank_mask:0xf
	s_waitcnt lgkmcnt(0)
	s_nop 1
	v_add_f32_dpp v0, v0, v0 quad_perm:[2,3,0,1] row_mask:0xf bank_mask:0xf
	s_waitcnt lgkmcnt(0)
	s_nop 1
	v_add_f32_dpp v0, v0, v0 row_half_mirror row_mask:0xf bank_mask:0xf
	s_waitcnt lgkmcnt(0)
	s_nop 1
	v_add_f32_dpp v0, v0, v0 row_mirror row_mask:0xf bank_mask:0xf
	ds_bpermute_b32 v3, v170, v0
	s_waitcnt lgkmcnt(0)
	v_add_f32_e32 v0, v0, v3
	v_fmamk_f32 v0, v0, 0x3c000000, v249
	v_mul_f32_e32 v3, 0x4b800000, v0
	v_cmp_gt_f32_e32 vcc, s5, v0
	s_nop 1
	v_cndmask_b32_e32 v0, v0, v3, vcc
	v_rsq_f32_e32 v0, v0
	s_nop 0
	v_mul_f32_e32 v3, 0x45800000, v0
	v_cndmask_b32_e32 v0, v0, v3, vcc
	v_mul_f32_e32 v3, v4, v0
	v_mul_f32_e32 v4, v5, v0
	v_mul_f32_e32 v5, v9, v0
	v_mul_f32_e32 v0, v8, v0
	v_mul_f32_e32 v3, v67, v3
	v_mul_f32_e32 v4, v71, v4
	v_mul_f32_e32 v5, v73, v5
	v_mul_f32_e32 v0, v75, v0
	v_cvt_pk_bf16_f32 v3, v3, s0
	v_cvt_pk_bf16_f32 v4, v4, s0
	v_cvt_pk_bf16_f32 v5, v5, s0
	v_cvt_pk_bf16_f32 v0, v0, s0
	ds_write_b16 v2, v3 offset:6528
	ds_write_b16 v2, v4 offset:6592
	ds_write_b16 v2, v5 offset:6656
	ds_write_b16 v2, v0 offset:6720
	s_lshl_b32 s60, s70, 12
	s_add_i32 s22, s1, s60
	s_ashr_i32 s23, s22, 31
	s_lshl_b64 s[22:23], s[22:23], 11
	s_add_u32 s1, s41, s22
	s_addc_u32 s5, s66, s23
	s_lshl_b32 s61, s71, 1
	s_add_u32 s22, s1, s61
	v_ashrrev_i32_e32 v6, 4, v162
	v_lshlrev_b32_e32 v0, 4, v162
	s_addc_u32 s23, s5, 0
	v_and_b32_e32 v0, 0xf0, v0
	v_mul_lo_u32 v2, v6, s77
	s_waitcnt lgkmcnt(0)
	v_lshl_add_u64 v[8:9], s[22:23], 0, v[0:1]
	v_add3_u32 v0, v69, v0, v2
	ds_read_b128 v[2:5], v0
	v_ashrrev_i32_e32 v7, 31, v6
	v_lshlrev_b64 v[6:7], 11, v[6:7]
	v_lshl_add_u64 v[10:11], v[8:9], 0, v[6:7]
	ds_read_b128 v[6:9], v0 offset:1088
	s_waitcnt lgkmcnt(1)
	global_store_dwordx4 v[10:11], v[2:5], off
	v_mov_b32_e32 v172, v226
	s_movk_i32 s26, 0x1800
	v_add_co_u32_e32 v2, vcc, s88, v10
	v_mov_b32_e32 v145, v1
	s_nop 0
	v_addc_co_u32_e32 v3, vcc, 0, v11, vcc
	s_waitcnt lgkmcnt(0)
	global_store_dwordx4 v[2:3], v[6:9], off
	ds_read_b128 v[2:5], v0 offset:2176
	ds_read_b128 v[6:9], v0 offset:3264
	v_add_co_u32_e32 v12, vcc, s14, v10
	v_readlane_b32 s1, v251, 7
	s_nop 0
	v_addc_co_u32_e32 v13, vcc, 0, v11, vcc
	s_waitcnt lgkmcnt(1)
	global_store_dwordx4 v[12:13], v[2:5], off
	s_add_i32 s1, s11, s1
	v_mov_b32_e32 v16, v1
	v_add_co_u32_e32 v2, vcc, s89, v10
	v_mov_b32_e32 v17, v1
	s_nop 0
	v_addc_co_u32_e32 v3, vcc, 0, v11, vcc
	s_waitcnt lgkmcnt(0)
	global_store_dwordx4 v[2:3], v[6:9], off
	ds_read_b128 v[2:5], v0 offset:4352
	ds_read_b128 v[6:9], v0 offset:5440
	v_add_co_u32_e32 v12, vcc, s81, v10
	s_add_i32 s5, s11, 0x100
	s_nop 0
	v_addc_co_u32_e32 v13, vcc, 0, v11, vcc
	s_waitcnt lgkmcnt(1)
	global_store_dwordx4 v[12:13], v[2:5], off
	v_mov_b32_e32 v14, v1
	v_mov_b32_e32 v15, v1
	v_add_co_u32_e32 v2, vcc, s20, v10
	s_lshr_b32 s5, s5, 6
	s_nop 0
	v_addc_co_u32_e32 v3, vcc, 0, v11, vcc
	s_waitcnt lgkmcnt(0)
	global_store_dwordx4 v[2:3], v[6:9], off
	ds_read_b128 v[2:5], v0 offset:6528
	ds_read_b128 v[6:9], v0 offset:7616
	v_add_co_u32_e32 v12, vcc, s18, v10
	s_or_b32 s11, s1, 31
	s_nop 0
	v_addc_co_u32_e32 v13, vcc, 0, v11, vcc
	s_waitcnt lgkmcnt(1)
	global_store_dwordx4 v[12:13], v[2:5], off
	v_mov_b32_e32 v12, v1
	v_mov_b32_e32 v13, v1
	v_add_co_u32_e32 v2, vcc, s3, v10
	v_mov_b32_e32 v243, 0xff800000
	s_nop 0
	v_addc_co_u32_e32 v3, vcc, 0, v11, vcc
	s_waitcnt lgkmcnt(0)
	global_store_dwordx4 v[2:3], v[6:9], off
	s_barrier
	s_nop 0
	v_mov_b32_e32 v6, v227
	v_mov_b64_e32 v[2:3], s[48:49]
	v_ashrrev_i32_e32 v8, 3, v6
	v_lshlrev_b32_e32 v7, 4, v6
	v_mad_i64_i32 v[4:5], s[22:23], v8, s26, v[2:3]
	v_and_b32_e32 v0, 0x70, v7
	v_and_b32_e32 v144, 0xf0, v7
	v_add_u32_e32 v7, 0x200, v6
	v_lshl_add_u64 v[150:151], v[4:5], 0, v[0:1]
	v_lshl_add_u64 v[4:5], s[30:31], 0, v[144:145]
	v_ashrrev_i32_e32 v9, 4, v6
	v_ashrrev_i32_e32 v7, 4, v7
	v_and_b32_e32 v145, 31, v172
	v_ashrrev_i32_e32 v10, 5, v172
	v_mad_i64_i32 v[152:153], s[22:23], v9, s26, v[4:5]
	v_mad_i64_i32 v[154:155], s[22:23], v7, s26, v[4:5]
	v_or_b32_e32 v173, s1, v145
	v_lshlrev_b32_e32 v4, 3, v10
	v_mad_u64_u32 v[2:3], s[30:31], v173, s26, v[2:3]
	v_ashrrev_i32_e32 v5, 31, v4
	v_lshl_add_u64 v[156:157], v[4:5], 1, v[2:3]
	global_load_dwordx4 v[114:117], v[150:151], off offset:2048
	global_load_dwordx4 v[118:121], v[152:153], off
	global_load_dwordx4 v[122:125], v[154:155], off
	global_load_dwordx4 v[126:129], v[156:157], off
	global_load_dwordx4 v[130:133], v[156:157], off offset:32
	global_load_dwordx4 v[134:137], v[156:157], off offset:64
	global_load_dwordx4 v[138:141], v[156:157], off offset:96
	v_mul_lo_u32 v174, v8, s96
	v_add_u32_e32 v2, 0, v174
	v_add_u32_e32 v238, v2, v0
	v_add_u32_e32 v2, 0, v144
	s_movk_i32 s78, 0x140
	v_mul_lo_u32 v175, v9, s78
	s_movk_i32 s78, 0x140
	v_mul_lo_u32 v176, v7, s78
	v_lshlrev_b32_e32 v241, 2, v172
	v_add_u32_e32 v239, v2, v175
	v_add_u32_e32 v240, v2, v176
	v_and_b32_e32 v2, 16, v172
	v_lshrrev_b32_e32 v3, 2, v172
	v_lshlrev_b32_e32 v179, 2, v10
	v_and_or_b32 v3, v3, 3, v179
	v_and_or_b32 v2, v241, 12, v2
	v_lshlrev_b32_e32 v181, 1, v2
	s_movk_i32 s78, 0x140
	v_mul_lo_u32 v182, v3, s78
	v_mov_b64_e32 v[2:3], s[28:29]
	v_and_b32_e32 v6, 15, v6
	v_mad_i64_i32 v[4:5], s[28:29], v7, s26, v[2:3]
	v_lshlrev_b32_e32 v6, 4, v6
	v_mov_b32_e32 v7, v1
	v_lshl_add_u64 v[4:5], v[4:5], 0, v[6:7]
	v_lshl_add_u64 v[146:147], s[16:17], 0, v[4:5]
	v_mad_i64_i32 v[4:5], s[28:29], v9, s26, v[2:3]
	v_lshl_add_u64 v[4:5], v[4:5], 0, v[6:7]
	v_mad_i64_i32 v[2:3], s[28:29], v8, s26, v[2:3]
	v_lshlrev_b32_e32 v178, 4, v10
	v_lshl_add_u64 v[148:149], s[16:17], 0, v[4:5]
	v_lshl_add_u64 v[158:159], v[2:3], 0, v[0:1]
	v_mov_b32_e32 v2, v1
	v_mov_b32_e32 v3, v1
	v_mov_b32_e32 v4, v1
	v_mov_b32_e32 v5, v1
	v_mov_b32_e32 v6, v1
	v_mov_b32_e32 v8, v1
	v_mov_b32_e32 v9, v1
	v_mov_b32_e32 v10, v1
	v_mov_b32_e32 v11, v1
	v_mov_b64_e32 v[64:65], v[16:17]
	v_mov_b64_e32 v[48:49], v[16:17]
	v_mov_b64_e32 v[32:33], v[16:17]
	v_mov_b64_e32 v[80:81], v[16:17]
	s_mov_b32 s22, 0
	v_mul_u32_u24_e32 v177, 0x90, v145
	v_cmp_gt_u32_e64 s[42:43], 32, v172
	v_lshl_add_u32 v180, v145, 2, s91
	v_subrev_u32_e32 v183, 32, v173
	v_subrev_u32_e32 v184, 33, v173
	v_subrev_u32_e32 v185, 34, v173
	v_subrev_u32_e32 v186, 35, v173
	v_add_u32_e32 v187, -8, v173
	v_subrev_u32_e32 v188, 40, v173
	v_add_u32_e32 v189, -9, v173
	v_subrev_u32_e32 v195, 41, v173
	v_add_u32_e32 v196, -10, v173
	v_subrev_u32_e32 v197, 42, v173
	v_add_u32_e32 v198, -11, v173
	v_subrev_u32_e32 v199, 43, v173
	v_add_u32_e32 v200, -16, v173
	v_subrev_u32_e32 v201, 48, v173
	v_subrev_u32_e32 v202, 17, v173
	v_subrev_u32_e32 v203, 49, v173
	v_subrev_u32_e32 v204, 18, v173
	v_subrev_u32_e32 v205, 50, v173
	v_subrev_u32_e32 v228, 19, v173
	v_subrev_u32_e32 v229, 51, v173
	v_subrev_u32_e32 v230, 24, v173
	v_subrev_u32_e32 v231, 56, v173
	v_subrev_u32_e32 v232, 25, v173
	v_subrev_u32_e32 v233, 57, v173
	v_subrev_u32_e32 v234, 26, v173
	v_subrev_u32_e32 v235, 58, v173
	v_subrev_u32_e32 v236, 27, v173
	v_subrev_u32_e32 v237, 59, v173
	v_lshl_add_u64 v[160:161], s[44:45], 0, v[158:159]
	v_mov_b64_e32 v[162:163], v[148:149]
	v_mov_b64_e32 v[164:165], v[146:147]
	v_mov_b64_e32 v[62:63], v[14:15]
	v_mov_b64_e32 v[60:61], v[12:13]
	v_mov_b64_e32 v[58:59], v[10:11]
	v_mov_b64_e32 v[56:57], v[8:9]
	v_mov_b64_e32 v[54:55], v[6:7]
	v_mov_b64_e32 v[52:53], v[4:5]
	v_mov_b64_e32 v[50:51], v[2:3]
	v_mov_b64_e32 v[46:47], v[14:15]
	v_mov_b64_e32 v[44:45], v[12:13]
	v_mov_b64_e32 v[42:43], v[10:11]
	v_mov_b64_e32 v[40:41], v[8:9]
	v_mov_b64_e32 v[38:39], v[6:7]
	v_mov_b64_e32 v[36:37], v[4:5]
	v_mov_b64_e32 v[34:35], v[2:3]
	v_mov_b64_e32 v[30:31], v[14:15]
	v_mov_b64_e32 v[28:29], v[12:13]
	v_mov_b64_e32 v[26:27], v[10:11]
	v_mov_b64_e32 v[24:25], v[8:9]
	v_mov_b64_e32 v[22:23], v[6:7]
	v_mov_b64_e32 v[20:21], v[4:5]
	v_mov_b64_e32 v[18:19], v[2:3]
	v_mov_b64_e32 v[78:79], v[14:15]
	v_mov_b64_e32 v[76:77], v[12:13]
	v_mov_b64_e32 v[74:75], v[10:11]
	v_mov_b64_e32 v[72:73], v[8:9]
	v_mov_b64_e32 v[70:71], v[6:7]
	v_mov_b64_e32 v[68:69], v[4:5]
	v_mov_b64_e32 v[66:67], v[2:3]
	s_waitcnt vmcnt(6)
	ds_write_b128 v238, v[114:117]
	s_waitcnt vmcnt(5)
	ds_write_b128 v239, v[118:121] offset:9216
	s_waitcnt vmcnt(4)
	ds_write_b128 v240, v[122:125] offset:9216
	s_waitcnt vmcnt(0) lgkmcnt(0)
	s_barrier
	s_cmp_lt_u32 s4, s5
	s_cselect_b64 s[28:29], -1, 0
	s_cmp_ge_u32 s4, s5
	s_cbranch_scc1 .LBB0_66

.LBB0_66:
	s_add_i32 s23, s4, -1
	s_and_b32 s23, s23, 1
	s_cmp_gt_u32 s22, s11
	s_cbranch_scc1 .LBB0_73
	s_mul_i32 s26, s23, 0x7400
	s_add_i32 s26, s26, 0
	s_add_i32 s30, s22, 63
	s_cmp_le_u32 s30, s1
	v_add3_u32 v206, s26, v177, v178
	ds_read_b128 v[98:101], v206
	ds_read_b128 v[102:105], v206 offset:32
	ds_read_b128 v[106:109], v206 offset:64
	ds_read_b128 v[110:113], v206 offset:96
	ds_read_b128 v[190:193], v206 offset:4608
	ds_read_b128 v[214:217], v206 offset:4640
	ds_read_b128 v[244:247], v206 offset:4672
	ds_read_b128 v[206:209], v206 offset:4704
	s_waitcnt lgkmcnt(7)
	v_mfma_f32_32x32x16_bf16 v[82:97], v[98:101], v[126:129], 0
	s_waitcnt lgkmcnt(6)
	v_mfma_f32_32x32x16_bf16 v[82:97], v[102:105], v[130:133], v[82:97]
	s_waitcnt lgkmcnt(5)
	v_mfma_f32_32x32x16_bf16 v[82:97], v[106:109], v[134:137], v[82:97]
	s_waitcnt lgkmcnt(4)
	v_mfma_f32_32x32x16_bf16 v[82:97], v[110:113], v[138:141], v[82:97]
	s_waitcnt lgkmcnt(3)
	v_mfma_f32_32x32x16_bf16 v[98:113], v[190:193], v[126:129], 0
	s_waitcnt lgkmcnt(2)
	v_mfma_f32_32x32x16_bf16 v[98:113], v[214:217], v[130:133], v[98:113]
	s_waitcnt lgkmcnt(1)
	v_mfma_f32_32x32x16_bf16 v[98:113], v[244:247], v[134:137], v[98:113]
	s_waitcnt lgkmcnt(0)
	v_mfma_f32_32x32x16_bf16 v[98:113], v[206:209], v[138:141], v[98:113]
	s_cbranch_scc1 .LBB0_69
	v_add_u32_e32 v190, s22, v179
	v_cmp_le_i32_e32 vcc, v190, v183
	v_add_u32_e32 v191, 2, v190
	s_nop 7
	v_cndmask_b32_e32 v98, v220, v98, vcc
	v_cmp_lt_i32_e32 vcc, v190, v173
	s_nop 1
	v_cndmask_b32_e32 v83, v220, v83, vcc
	v_cmp_le_i32_e32 vcc, v190, v173
	s_nop 1
	v_cndmask_b32_e32 v82, v220, v82, vcc
	v_cmp_le_i32_e32 vcc, v190, v184
	s_nop 1
	v_cndmask_b32_e32 v99, v220, v99, vcc
	v_cmp_le_i32_e32 vcc, v191, v173
	v_add_u32_e32 v191, 3, v190
	s_nop 0
	v_cndmask_b32_e32 v84, v220, v84, vcc
	v_cmp_le_i32_e32 vcc, v190, v185
	s_nop 1
	v_cndmask_b32_e32 v100, v220, v100, vcc
	v_cmp_le_i32_e32 vcc, v191, v173
	s_nop 1
	v_cndmask_b32_e32 v85, v220, v85, vcc
	v_cmp_le_i32_e32 vcc, v190, v186
	s_nop 1
	v_cndmask_b32_e32 v101, v220, v101, vcc
	v_cmp_le_i32_e32 vcc, v190, v187
	s_nop 1
	v_cndmask_b32_e32 v86, v220, v86, vcc
	v_cmp_le_i32_e32 vcc, v190, v188
	s_nop 1
	v_cndmask_b32_e32 v102, v220, v102, vcc
	v_cmp_le_i32_e32 vcc, v190, v189
	s_nop 1
	v_cndmask_b32_e32 v87, v220, v87, vcc
	v_cmp_le_i32_e32 vcc, v190, v195
	s_nop 1
	v_cndmask_b32_e32 v103, v220, v103, vcc
	v_cmp_le_i32_e32 vcc, v190, v196
	s_nop 1
	v_cndmask_b32_e32 v88, v220, v88, vcc
	v_cmp_le_i32_e32 vcc, v190, v197
	s_nop 1
	v_cndmask_b32_e32 v104, v220, v104, vcc
	v_cmp_le_i32_e32 vcc, v190, v198
	s_nop 1
	v_cndmask_b32_e32 v89, v220, v89, vcc
	v_cmp_le_i32_e32 vcc, v190, v199
	s_nop 1
	v_cndmask_b32_e32 v105, v220, v105, vcc
	v_cmp_le_i32_e32 vcc, v190, v200
	s_nop 1
	v_cndmask_b32_e32 v90, v220, v90, vcc
	v_cmp_le_i32_e32 vcc, v190, v201
	s_nop 1
	v_cndmask_b32_e32 v106, v220, v106, vcc
	v_cmp_le_i32_e32 vcc, v190, v202
	s_nop 1
	v_cndmask_b32_e32 v91, v220, v91, vcc
	v_cmp_le_i32_e32 vcc, v190, v203
	s_nop 1
	v_cndmask_b32_e32 v107, v220, v107, vcc
	v_cmp_le_i32_e32 vcc, v190, v204
	s_nop 1
	v_cndmask_b32_e32 v92, v220, v92, vcc
	v_cmp_le_i32_e32 vcc, v190, v205
	s_nop 1
	v_cndmask_b32_e32 v108, v220, v108, vcc
	v_cmp_le_i32_e32 vcc, v190, v228
	s_nop 1
	v_cndmask_b32_e32 v93, v220, v93, vcc
	v_cmp_le_i32_e32 vcc, v190, v229
	s_nop 1
	v_cndmask_b32_e32 v109, v220, v109, vcc
	v_cmp_le_i32_e32 vcc, v190, v230
	s_nop 1
	v_cndmask_b32_e32 v94, v220, v94, vcc
	v_cmp_le_i32_e32 vcc, v190, v231
	s_nop 1
	v_cndmask_b32_e32 v110, v220, v110, vcc
	v_cmp_le_i32_e32 vcc, v190, v232
	s_nop 1
	v_cndmask_b32_e32 v95, v220, v95, vcc
	v_cmp_le_i32_e32 vcc, v190, v233
	s_nop 1
	v_cndmask_b32_e32 v111, v220, v111, vcc
	v_cmp_le_i32_e32 vcc, v190, v234
	s_nop 1
	v_cndmask_b32_e32 v96, v220, v96, vcc
	v_cmp_le_i32_e32 vcc, v190, v235
	s_nop 1
	v_cndmask_b32_e32 v112, v220, v112, vcc
	v_cmp_le_i32_e32 vcc, v190, v236
	s_nop 1
	v_cndmask_b32_e32 v97, v220, v97, vcc
	v_cmp_le_i32_e32 vcc, v190, v237
	s_nop 1
	v_cndmask_b32_e32 v113, v220, v113, vcc
.LBB0_69:
	s_nop 10
	v_max3_f32 v190, v82, v83, v84
	v_max3_f32 v191, v98, v99, v100
	v_max3_f32 v192, v90, v91, v92
	v_max3_f32 v193, v106, v107, v108
	v_max3_f32 v190, v190, v85, v86
	v_max3_f32 v191, v191, v101, v102
	v_max3_f32 v192, v192, v93, v94
	v_max3_f32 v193, v193, v109, v110
	v_max3_f32 v190, v190, v87, v88
	v_max3_f32 v191, v191, v103, v104
	v_max3_f32 v192, v192, v95, v96
	v_max3_f32 v193, v193, v111, v112
	v_max3_f32 v190, v190, v89, v105
	v_max3_f32 v192, v192, v97, v113
	v_max3_f32 v190, v190, v191, v192
	v_max_f32_e32 v190, v190, v193
	v_mov_b32_e32 v191, v190
	s_nop 1
	v_permlane32_swap_b32_e32 v190, v191
	v_max_f32_e32 v242, v190, v191
	v_add_f32_e32 v190, 0x41000000, v243
	v_cmp_gt_f32_e32 vcc, v242, v190
	s_cbranch_vccz .LBB0_74
	v_max_f32_e32 v190, v242, v242
	v_max_f32_e32 v191, v243, v243
	v_max_f32_e32 v242, v191, v190
	s_and_saveexec_b64 s[30:31], s[42:43]
	s_cbranch_execz .LBB0_72
	v_sub_f32_e32 v190, v243, v242
	v_exp_f32_e32 v190, v190
	ds_write_b32 v180, v190 offset:59392
.LBB0_72:
	s_or_b64 exec, exec, s[30:31]
	v_add_u32_e32 v206, s91, v178
	ds_read_b128 v[190:193], v206 offset:59488
	ds_read_b128 v[214:217], v206 offset:59456
	ds_read_b128 v[244:247], v206 offset:59424
	ds_read_b128 v[206:209], v206 offset:59392
	s_waitcnt lgkmcnt(3)
	v_pk_mul_f32 v[14:15], v[14:15], v[190:191]
	s_waitcnt lgkmcnt(2)
	v_pk_mul_f32 v[10:11], v[10:11], v[214:215]
	s_waitcnt lgkmcnt(1)
	v_pk_mul_f32 v[6:7], v[6:7], v[244:245]
	v_pk_mul_f32 v[16:17], v[16:17], v[192:193]
	v_pk_mul_f32 v[12:13], v[12:13], v[216:217]
	v_pk_mul_f32 v[8:9], v[8:9], v[246:247]
	s_waitcnt lgkmcnt(0)
	v_pk_mul_f32 v[4:5], v[4:5], v[208:209]
	v_pk_mul_f32 v[2:3], v[2:3], v[206:207]
	v_pk_mul_f32 v[62:63], v[62:63], v[190:191]
	v_pk_mul_f32 v[58:59], v[58:59], v[214:215]
	v_pk_mul_f32 v[54:55], v[54:55], v[244:245]
	v_pk_mul_f32 v[64:65], v[64:65], v[192:193]
	v_pk_mul_f32 v[60:61], v[60:61], v[216:217]
	v_pk_mul_f32 v[56:57], v[56:57], v[246:247]
	v_pk_mul_f32 v[52:53], v[52:53], v[208:209]
	v_pk_mul_f32 v[50:51], v[50:51], v[206:207]
	v_pk_mul_f32 v[46:47], v[46:47], v[190:191]
	v_pk_mul_f32 v[42:43], v[42:43], v[214:215]
	v_pk_mul_f32 v[38:39], v[38:39], v[244:245]
	v_pk_mul_f32 v[48:49], v[48:49], v[192:193]
	v_pk_mul_f32 v[44:45], v[44:45], v[216:217]
	v_pk_mul_f32 v[40:41], v[40:41], v[246:247]
	v_pk_mul_f32 v[36:37], v[36:37], v[208:209]
	v_pk_mul_f32 v[34:35], v[34:35], v[206:207]
	v_pk_mul_f32 v[30:31], v[30:31], v[190:191]
	v_pk_mul_f32 v[26:27], v[26:27], v[214:215]
	v_pk_mul_f32 v[22:23], v[22:23], v[244:245]
	v_pk_mul_f32 v[32:33], v[32:33], v[192:193]
	v_pk_mul_f32 v[28:29], v[28:29], v[216:217]
	v_pk_mul_f32 v[24:25], v[24:25], v[246:247]
	v_pk_mul_f32 v[20:21], v[20:21], v[208:209]
	v_pk_mul_f32 v[18:19], v[18:19], v[206:207]
	v_pk_mul_f32 v[78:79], v[78:79], v[190:191]
	v_pk_mul_f32 v[74:75], v[74:75], v[214:215]
	v_pk_mul_f32 v[70:71], v[70:71], v[244:245]
	v_pk_mul_f32 v[80:81], v[80:81], v[192:193]
	v_pk_mul_f32 v[76:77], v[76:77], v[216:217]
	v_pk_mul_f32 v[72:73], v[72:73], v[246:247]
	v_pk_mul_f32 v[68:69], v[68:69], v[208:209]
	v_pk_mul_f32 v[66:67], v[66:67], v[206:207]
	s_branch .LBB0_75

.LBB0_75:
	v_add3_u32 v190, s26, v182, v181
	s_mov_b32 s78, s76
	s_mov_b32 s79, s76
	s_mov_b32 s77, s76
	ds_read_b64_tr_b16 v[214:215], v190 offset:9216
	ds_read_b64_tr_b16 v[216:217], v190 offset:11776
	ds_read_b64_tr_b16 v[244:245], v190 offset:9280
	ds_read_b64_tr_b16 v[246:247], v190 offset:11840
	ds_read_b64_tr_b16 v[206:207], v190 offset:9344
	ds_read_b64_tr_b16 v[208:209], v190 offset:11904
	v_sub_f32_e32 v82, v82, v242
	v_sub_f32_e32 v83, v83, v242
	v_sub_f32_e32 v84, v84, v242
	v_sub_f32_e32 v85, v85, v242
	v_sub_f32_e32 v86, v86, v242
	v_sub_f32_e32 v87, v87, v242
	v_sub_f32_e32 v88, v88, v242
	v_sub_f32_e32 v89, v89, v242
	v_exp_f32_e32 v82, v82
	v_exp_f32_e32 v83, v83
	v_exp_f32_e32 v84, v84
	v_exp_f32_e32 v85, v85
	v_exp_f32_e32 v86, v86
	v_exp_f32_e32 v87, v87
	v_exp_f32_e32 v88, v88
	v_exp_f32_e32 v89, v89
	v_cvt_pk_bf16_f32 v82, v82, v83
	v_cvt_pk_bf16_f32 v83, v84, v85
	v_cvt_pk_bf16_f32 v84, v86, v87
	v_cvt_pk_bf16_f32 v85, v88, v89
	v_mov_b64_e32 v[88:89], s[78:79]
	v_mov_b64_e32 v[86:87], s[76:77]
	s_waitcnt lgkmcnt(4)
	v_mfma_f32_32x32x16_bf16 v[2:17], v[82:85], v[214:217], v[2:17]
	v_sub_f32_e32 v90, v90, v242
	v_sub_f32_e32 v91, v91, v242
	v_sub_f32_e32 v92, v92, v242
	v_sub_f32_e32 v93, v93, v242
	ds_read_b64_tr_b16 v[214:215], v190 offset:9408
	ds_read_b64_tr_b16 v[216:217], v190 offset:11968
	s_waitcnt lgkmcnt(4)
	v_mfma_f32_32x32x16_bf16 v[50:65], v[82:85], v[244:247], v[50:65]
	v_sub_f32_e32 v94, v94, v242
	v_sub_f32_e32 v95, v95, v242
	v_sub_f32_e32 v96, v96, v242
	v_sub_f32_e32 v97, v97, v242
	ds_read_b64_tr_b16 v[244:245], v190 offset:14336
	ds_read_b64_tr_b16 v[246:247], v190 offset:16896
	s_waitcnt lgkmcnt(4)
	v_mfma_f32_32x32x16_bf16 v[34:49], v[82:85], v[206:209], v[34:49]
	v_exp_f32_e32 v90, v90
	v_exp_f32_e32 v91, v91
	v_exp_f32_e32 v92, v92
	v_exp_f32_e32 v93, v93
	ds_read_b64_tr_b16 v[206:207], v190 offset:14400
	ds_read_b64_tr_b16 v[208:209], v190 offset:16960
	s_waitcnt lgkmcnt(4)
	v_mfma_f32_32x32x16_bf16 v[18:33], v[82:85], v[214:217], v[18:33]
	v_exp_f32_e32 v94, v94
	v_exp_f32_e32 v95, v95
	v_exp_f32_e32 v96, v96
	v_exp_f32_e32 v97, v97
	ds_read_b64_tr_b16 v[214:215], v190 offset:14464
	ds_read_b64_tr_b16 v[216:217], v190 offset:17024
	v_mfma_f32_32x32x16_bf16 v[66:81], v[82:85], v[86:89], v[66:81]
	v_cvt_pk_bf16_f32 v90, v90, v91
	v_cvt_pk_bf16_f32 v91, v92, v93
	v_cvt_pk_bf16_f32 v92, v94, v95
	v_cvt_pk_bf16_f32 v93, v96, v97
	s_nop 0
	s_waitcnt lgkmcnt(4)
	v_mfma_f32_32x32x16_bf16 v[2:17], v[90:93], v[244:247], v[2:17]
	v_sub_f32_e32 v98, v98, v242
	v_sub_f32_e32 v99, v99, v242
	v_sub_f32_e32 v100, v100, v242
	v_sub_f32_e32 v101, v101, v242
	ds_read_b64_tr_b16 v[244:245], v190 offset:14528
	ds_read_b64_tr_b16 v[246:247], v190 offset:17088
	s_waitcnt lgkmcnt(4)
	v_mfma_f32_32x32x16_bf16 v[50:65], v[90:93], v[206:209], v[50:65]
	v_sub_f32_e32 v102, v102, v242
	v_sub_f32_e32 v103, v103, v242
	v_sub_f32_e32 v104, v104, v242
	v_sub_f32_e32 v105, v105, v242
	ds_read_b64_tr_b16 v[206:207], v190 offset:19456
	ds_read_b64_tr_b16 v[208:209], v190 offset:22016
	s_waitcnt lgkmcnt(4)
	v_mfma_f32_32x32x16_bf16 v[34:49], v[90:93], v[214:217], v[34:49]
	v_exp_f32_e32 v98, v98
	v_exp_f32_e32 v99, v99
	v_exp_f32_e32 v100, v100
	v_exp_f32_e32 v101, v101
	ds_read_b64_tr_b16 v[214:215], v190 offset:19520
	ds_read_b64_tr_b16 v[216:217], v190 offset:22080
	s_waitcnt lgkmcnt(4)
	v_mfma_f32_32x32x16_bf16 v[18:33], v[90:93], v[244:247], v[18:33]
	v_exp_f32_e32 v102, v102
	v_exp_f32_e32 v103, v103
	v_exp_f32_e32 v104, v104
	v_exp_f32_e32 v105, v105
	ds_read_b64_tr_b16 v[244:245], v190 offset:19584
	ds_read_b64_tr_b16 v[246:247], v190 offset:22144
	v_mfma_f32_32x32x16_bf16 v[66:81], v[90:93], v[86:89], v[66:81]
	v_cvt_pk_bf16_f32 v98, v98, v99
	v_cvt_pk_bf16_f32 v99, v100, v101
	v_cvt_pk_bf16_f32 v100, v102, v103
	v_cvt_pk_bf16_f32 v101, v104, v105
	s_nop 0
	s_waitcnt lgkmcnt(4)
	v_mfma_f32_32x32x16_bf16 v[2:17], v[98:101], v[206:209], v[2:17]
	v_sub_f32_e32 v106, v106, v242
	v_sub_f32_e32 v107, v107, v242
	v_sub_f32_e32 v108, v108, v242
	v_sub_f32_e32 v109, v109, v242
	ds_read_b64_tr_b16 v[206:207], v190 offset:19648
	ds_read_b64_tr_b16 v[208:209], v190 offset:22208
	s_waitcnt lgkmcnt(4)
	v_mfma_f32_32x32x16_bf16 v[50:65], v[98:101], v[214:217], v[50:65]
	v_sub_f32_e32 v110, v110, v242
	v_sub_f32_e32 v111, v111, v242
	v_sub_f32_e32 v112, v112, v242
	v_sub_f32_e32 v113, v113, v242
	ds_read_b64_tr_b16 v[214:215], v190 offset:24576
	ds_read_b64_tr_b16 v[216:217], v190 offset:27136
	s_waitcnt lgkmcnt(4)
	v_mfma_f32_32x32x16_bf16 v[34:49], v[98:101], v[244:247], v[34:49]
	v_exp_f32_e32 v106, v106
	v_exp_f32_e32 v107, v107
	v_exp_f32_e32 v108, v108
	v_exp_f32_e32 v109, v109
	ds_read_b64_tr_b16 v[244:245], v190 offset:24640
	ds_read_b64_tr_b16 v[246:247], v190 offset:27200
	s_waitcnt lgkmcnt(4)
	v_mfma_f32_32x32x16_bf16 v[18:33], v[98:101], v[206:209], v[18:33]
	v_exp_f32_e32 v110, v110
	v_exp_f32_e32 v111, v111
	v_exp_f32_e32 v112, v112
	v_exp_f32_e32 v113, v113
	ds_read_b64_tr_b16 v[206:207], v190 offset:24704
	ds_read_b64_tr_b16 v[208:209], v190 offset:27264
	v_mfma_f32_32x32x16_bf16 v[66:81], v[98:101], v[86:89], v[66:81]
	v_cvt_pk_bf16_f32 v106, v106, v107
	v_cvt_pk_bf16_f32 v107, v108, v109
	v_cvt_pk_bf16_f32 v108, v110, v111
	v_cvt_pk_bf16_f32 v109, v112, v113
	s_nop 0
	s_waitcnt lgkmcnt(4)
	v_mfma_f32_32x32x16_bf16 v[2:17], v[106:109], v[214:217], v[2:17]
	ds_read_b64_tr_b16 v[214:215], v190 offset:24768
	ds_read_b64_tr_b16 v[216:217], v190 offset:27328
	s_waitcnt lgkmcnt(4)
	v_mfma_f32_32x32x16_bf16 v[50:65], v[106:109], v[244:247], v[50:65]
	s_waitcnt lgkmcnt(2)
	v_mfma_f32_32x32x16_bf16 v[34:49], v[106:109], v[206:209], v[34:49]
	s_waitcnt lgkmcnt(0)
	v_mfma_f32_32x32x16_bf16 v[18:33], v[106:109], v[214:217], v[18:33]
	v_mfma_f32_32x32x16_bf16 v[66:81], v[106:109], v[86:89], v[66:81]
	s_movk_i32 s77, 0x110
	s_andn2_b64 vcc, exec, s[28:29]
	s_cbranch_vccnz .LBB0_77
.LBB0_76:
	s_xor_b32 s23, s23, 1
	s_mulk_i32 s23, 0x7400
	s_add_i32 s23, s23, 0
	v_add3_u32 v82, s23, v174, v0
	v_add_u32_e32 v83, s23, v144
	v_add_u32_e32 v84, v83, v175
	v_add_u32_e32 v83, v83, v176
	s_waitcnt vmcnt(2)
	ds_write_b128 v82, v[114:117]
	s_waitcnt vmcnt(1)
	ds_write_b128 v84, v[118:121] offset:9216
	s_waitcnt vmcnt(0)
	ds_write_b128 v83, v[122:125] offset:9216

.LBB0_81:
	s_add_i32 s23, s22, -1
	s_and_b32 s23, s23, 1
	s_cmp_gt_u32 s4, s11
	s_cbranch_scc1 .LBB0_88
	s_mul_i32 s26, s23, 0x7400
	s_add_i32 s26, s26, 0
	s_add_i32 s30, s4, 63
	s_cmp_le_u32 s30, s1
	v_add3_u32 v152, s26, v177, v178
	ds_read_b128 v[98:101], v152
	ds_read_b128 v[102:105], v152 offset:32
	ds_read_b128 v[106:109], v152 offset:64
	ds_read_b128 v[110:113], v152 offset:96
	ds_read_b128 v[154:157], v152 offset:4608
	ds_read_b128 v[162:165], v152 offset:4640
	ds_read_b128 v[190:193], v152 offset:4672
	ds_read_b128 v[206:209], v152 offset:4704
	s_waitcnt lgkmcnt(7)
	v_mfma_f32_32x32x16_bf16 v[82:97], v[98:101], v[118:121], 0
	s_waitcnt lgkmcnt(6)
	v_mfma_f32_32x32x16_bf16 v[82:97], v[102:105], v[122:125], v[82:97]
	s_waitcnt lgkmcnt(5)
	v_mfma_f32_32x32x16_bf16 v[82:97], v[106:109], v[126:129], v[82:97]
	s_waitcnt lgkmcnt(4)
	v_mfma_f32_32x32x16_bf16 v[82:97], v[110:113], v[134:137], v[82:97]
	s_waitcnt lgkmcnt(3)
	v_mfma_f32_32x32x16_bf16 v[98:113], v[154:157], v[118:121], 0
	s_waitcnt lgkmcnt(2)
	v_mfma_f32_32x32x16_bf16 v[98:113], v[162:165], v[122:125], v[98:113]
	s_waitcnt lgkmcnt(1)
	v_mfma_f32_32x32x16_bf16 v[98:113], v[190:193], v[126:129], v[98:113]
	s_waitcnt lgkmcnt(0)
	v_mfma_f32_32x32x16_bf16 v[98:113], v[206:209], v[134:137], v[98:113]
	s_cbranch_scc1 .LBB0_84
	v_add_u32_e32 v152, s4, v179
	v_cmp_le_i32_e32 vcc, v152, v183
	v_add_u32_e32 v154, 2, v152
	s_nop 7
	v_cndmask_b32_e32 v98, v220, v98, vcc
	v_cmp_lt_i32_e32 vcc, v152, v173
	s_nop 1
	v_cndmask_b32_e32 v83, v220, v83, vcc
	v_cmp_le_i32_e32 vcc, v152, v173
	s_nop 1
	v_cndmask_b32_e32 v82, v220, v82, vcc
	v_cmp_le_i32_e32 vcc, v152, v184
	s_nop 1
	v_cndmask_b32_e32 v99, v220, v99, vcc
	v_cmp_le_i32_e32 vcc, v154, v173
	v_add_u32_e32 v154, 3, v152
	s_nop 0
	v_cndmask_b32_e32 v84, v220, v84, vcc
	v_cmp_le_i32_e32 vcc, v152, v185
	s_nop 1
	v_cndmask_b32_e32 v100, v220, v100, vcc
	v_cmp_le_i32_e32 vcc, v154, v173
	s_nop 1
	v_cndmask_b32_e32 v85, v220, v85, vcc
	v_cmp_le_i32_e32 vcc, v152, v186
	s_nop 1
	v_cndmask_b32_e32 v101, v220, v101, vcc
	v_cmp_le_i32_e32 vcc, v152, v187
	s_nop 1
	v_cndmask_b32_e32 v86, v220, v86, vcc
	v_cmp_le_i32_e32 vcc, v152, v188
	s_nop 1
	v_cndmask_b32_e32 v102, v220, v102, vcc
	v_cmp_le_i32_e32 vcc, v152, v189
	s_nop 1
	v_cndmask_b32_e32 v87, v220, v87, vcc
	v_cmp_le_i32_e32 vcc, v152, v195
	s_nop 1
	v_cndmask_b32_e32 v103, v220, v103, vcc
	v_cmp_le_i32_e32 vcc, v152, v196
	s_nop 1
	v_cndmask_b32_e32 v88, v220, v88, vcc
	v_cmp_le_i32_e32 vcc, v152, v197
	s_nop 1
	v_cndmask_b32_e32 v104, v220, v104, vcc
	v_cmp_le_i32_e32 vcc, v152, v198
	s_nop 1
	v_cndmask_b32_e32 v89, v220, v89, vcc
	v_cmp_le_i32_e32 vcc, v152, v199
	s_nop 1
	v_cndmask_b32_e32 v105, v220, v105, vcc
	v_cmp_le_i32_e32 vcc, v152, v200
	s_nop 1
	v_cndmask_b32_e32 v90, v220, v90, vcc
	v_cmp_le_i32_e32 vcc, v152, v201
	s_nop 1
	v_cndmask_b32_e32 v106, v220, v106, vcc
	v_cmp_le_i32_e32 vcc, v152, v202
	s_nop 1
	v_cndmask_b32_e32 v91, v220, v91, vcc
	v_cmp_le_i32_e32 vcc, v152, v203
	s_nop 1
	v_cndmask_b32_e32 v107, v220, v107, vcc
	v_cmp_le_i32_e32 vcc, v152, v204
	s_nop 1
	v_cndmask_b32_e32 v92, v220, v92, vcc
	v_cmp_le_i32_e32 vcc, v152, v205
	s_nop 1
	v_cndmask_b32_e32 v108, v220, v108, vcc
	v_cmp_le_i32_e32 vcc, v152, v228
	s_nop 1
	v_cndmask_b32_e32 v93, v220, v93, vcc
	v_cmp_le_i32_e32 vcc, v152, v229
	s_nop 1
	v_cndmask_b32_e32 v109, v220, v109, vcc
	v_cmp_le_i32_e32 vcc, v152, v230
	s_nop 1
	v_cndmask_b32_e32 v94, v220, v94, vcc
	v_cmp_le_i32_e32 vcc, v152, v231
	s_nop 1
	v_cndmask_b32_e32 v110, v220, v110, vcc
	v_cmp_le_i32_e32 vcc, v152, v232
	s_nop 1
	v_cndmask_b32_e32 v95, v220, v95, vcc
	v_cmp_le_i32_e32 vcc, v152, v233
	s_nop 1
	v_cndmask_b32_e32 v111, v220, v111, vcc
	v_cmp_le_i32_e32 vcc, v152, v234
	s_nop 1
	v_cndmask_b32_e32 v96, v220, v96, vcc
	v_cmp_le_i32_e32 vcc, v152, v235
	s_nop 1
	v_cndmask_b32_e32 v112, v220, v112, vcc
	v_cmp_le_i32_e32 vcc, v152, v236
	s_nop 1
	v_cndmask_b32_e32 v97, v220, v97, vcc
	v_cmp_le_i32_e32 vcc, v152, v237
	s_nop 1
	v_cndmask_b32_e32 v113, v220, v113, vcc
.LBB0_84:
	s_nop 10
	v_max3_f32 v154, v82, v83, v84
	v_max3_f32 v155, v98, v99, v100
	v_max3_f32 v156, v90, v91, v92
	v_max3_f32 v157, v106, v107, v108
	v_max3_f32 v154, v154, v85, v86
	v_max3_f32 v155, v155, v101, v102
	v_max3_f32 v156, v156, v93, v94
	v_max3_f32 v157, v157, v109, v110
	v_max3_f32 v154, v154, v87, v88
	v_max3_f32 v155, v155, v103, v104
	v_max3_f32 v156, v156, v95, v96
	v_max3_f32 v157, v157, v111, v112
	v_max3_f32 v154, v154, v89, v105
	v_max3_f32 v156, v156, v97, v113
	v_max3_f32 v154, v154, v155, v156
	v_max_f32_e32 v154, v154, v157
	v_mov_b32_e32 v155, v154
	s_nop 1
	v_permlane32_swap_b32_e32 v154, v155
	v_max_f32_e32 v152, v154, v155
	v_add_f32_e32 v154, 0x41000000, v153
	v_cmp_gt_f32_e32 vcc, v152, v154
	s_cbranch_vccz .LBB0_89
	v_max_f32_e32 v152, v152, v152
	v_max_f32_e32 v154, v153, v153
	v_max_f32_e32 v152, v154, v152
	s_and_saveexec_b64 s[30:31], s[42:43]
	s_cbranch_execz .LBB0_87
	v_sub_f32_e32 v153, v153, v152
	v_exp_f32_e32 v153, v153
	ds_write_b32 v180, v153 offset:59392
.LBB0_87:
	s_or_b64 exec, exec, s[30:31]
	v_add_u32_e32 v153, s91, v178
	ds_read_b128 v[154:157], v153 offset:59488
	ds_read_b128 v[162:165], v153 offset:59456
	ds_read_b128 v[190:193], v153 offset:59424
	ds_read_b128 v[206:209], v153 offset:59392
	s_waitcnt lgkmcnt(3)
	v_pk_mul_f32 v[14:15], v[14:15], v[154:155]
	s_waitcnt lgkmcnt(2)
	v_pk_mul_f32 v[10:11], v[10:11], v[162:163]
	s_waitcnt lgkmcnt(1)
	v_pk_mul_f32 v[6:7], v[6:7], v[190:191]
	v_pk_mul_f32 v[16:17], v[16:17], v[156:157]
	v_pk_mul_f32 v[12:13], v[12:13], v[164:165]
	v_pk_mul_f32 v[8:9], v[8:9], v[192:193]
	s_waitcnt lgkmcnt(0)
	v_pk_mul_f32 v[4:5], v[4:5], v[208:209]
	v_pk_mul_f32 v[2:3], v[2:3], v[206:207]
	v_pk_mul_f32 v[62:63], v[62:63], v[154:155]
	v_pk_mul_f32 v[58:59], v[58:59], v[162:163]
	v_pk_mul_f32 v[54:55], v[54:55], v[190:191]
	v_pk_mul_f32 v[64:65], v[64:65], v[156:157]
	v_pk_mul_f32 v[60:61], v[60:61], v[164:165]
	v_pk_mul_f32 v[56:57], v[56:57], v[192:193]
	v_pk_mul_f32 v[52:53], v[52:53], v[208:209]
	v_pk_mul_f32 v[50:51], v[50:51], v[206:207]
	v_pk_mul_f32 v[30:31], v[30:31], v[154:155]
	v_pk_mul_f32 v[26:27], v[26:27], v[162:163]
	v_pk_mul_f32 v[22:23], v[22:23], v[190:191]
	v_pk_mul_f32 v[32:33], v[32:33], v[156:157]
	v_pk_mul_f32 v[28:29], v[28:29], v[164:165]
	v_pk_mul_f32 v[24:25], v[24:25], v[192:193]
	v_pk_mul_f32 v[20:21], v[20:21], v[208:209]
	v_pk_mul_f32 v[18:19], v[18:19], v[206:207]
	v_pk_mul_f32 v[46:47], v[46:47], v[154:155]
	v_pk_mul_f32 v[42:43], v[42:43], v[162:163]
	v_pk_mul_f32 v[38:39], v[38:39], v[190:191]
	v_pk_mul_f32 v[48:49], v[48:49], v[156:157]
	v_pk_mul_f32 v[44:45], v[44:45], v[164:165]
	v_pk_mul_f32 v[40:41], v[40:41], v[192:193]
	v_pk_mul_f32 v[36:37], v[36:37], v[208:209]
	v_pk_mul_f32 v[34:35], v[34:35], v[206:207]
	v_pk_mul_f32 v[78:79], v[78:79], v[154:155]
	v_pk_mul_f32 v[74:75], v[74:75], v[162:163]
	v_pk_mul_f32 v[70:71], v[70:71], v[190:191]
	v_pk_mul_f32 v[80:81], v[80:81], v[156:157]
	v_pk_mul_f32 v[76:77], v[76:77], v[164:165]
	v_pk_mul_f32 v[72:73], v[72:73], v[192:193]
	v_pk_mul_f32 v[68:69], v[68:69], v[208:209]
	v_pk_mul_f32 v[66:67], v[66:67], v[206:207]
	s_branch .LBB0_90

.LBB0_90:
	v_add3_u32 v153, s26, v182, v181
	s_mov_b32 s78, s76
	s_mov_b32 s79, s76
	s_mov_b32 s77, s76
	ds_read_b64_tr_b16 v[154:155], v153 offset:9216
	ds_read_b64_tr_b16 v[156:157], v153 offset:11776
	ds_read_b64_tr_b16 v[162:163], v153 offset:9280
	ds_read_b64_tr_b16 v[164:165], v153 offset:11840
	ds_read_b64_tr_b16 v[190:191], v153 offset:9344
	ds_read_b64_tr_b16 v[192:193], v153 offset:11904
	ds_read_b64_tr_b16 v[206:207], v153 offset:9408
	ds_read_b64_tr_b16 v[208:209], v153 offset:11968
	v_sub_f32_e32 v82, v82, v152
	v_sub_f32_e32 v83, v83, v152
	v_sub_f32_e32 v84, v84, v152
	v_sub_f32_e32 v85, v85, v152
	v_sub_f32_e32 v86, v86, v152
	v_sub_f32_e32 v87, v87, v152
	v_sub_f32_e32 v88, v88, v152
	v_sub_f32_e32 v89, v89, v152
	v_exp_f32_e32 v82, v82
	v_exp_f32_e32 v83, v83
	v_exp_f32_e32 v84, v84
	v_exp_f32_e32 v85, v85
	v_exp_f32_e32 v86, v86
	v_exp_f32_e32 v87, v87
	v_exp_f32_e32 v88, v88
	v_exp_f32_e32 v89, v89
	v_cvt_pk_bf16_f32 v82, v82, v83
	v_cvt_pk_bf16_f32 v83, v84, v85
	v_cvt_pk_bf16_f32 v84, v86, v87
	v_cvt_pk_bf16_f32 v85, v88, v89
	v_mov_b64_e32 v[88:89], s[78:79]
	v_mov_b64_e32 v[86:87], s[76:77]
	s_waitcnt lgkmcnt(6)
	v_mfma_f32_32x32x16_bf16 v[2:17], v[82:85], v[154:157], v[2:17]
	v_sub_f32_e32 v90, v90, v152
	v_sub_f32_e32 v91, v91, v152
	v_sub_f32_e32 v92, v92, v152
	v_sub_f32_e32 v93, v93, v152
	ds_read_b64_tr_b16 v[154:155], v153 offset:14336
	ds_read_b64_tr_b16 v[156:157], v153 offset:16896
	s_waitcnt lgkmcnt(6)
	v_mfma_f32_32x32x16_bf16 v[50:65], v[82:85], v[162:165], v[50:65]
	v_sub_f32_e32 v94, v94, v152
	v_sub_f32_e32 v95, v95, v152
	v_sub_f32_e32 v96, v96, v152
	v_sub_f32_e32 v97, v97, v152
	ds_read_b64_tr_b16 v[162:163], v153 offset:14400
	ds_read_b64_tr_b16 v[164:165], v153 offset:16960
	s_waitcnt lgkmcnt(6)
	v_mfma_f32_32x32x16_bf16 v[18:33], v[82:85], v[190:193], v[18:33]
	v_exp_f32_e32 v90, v90
	v_exp_f32_e32 v91, v91
	v_exp_f32_e32 v92, v92
	v_exp_f32_e32 v93, v93
	ds_read_b64_tr_b16 v[190:191], v153 offset:14464
	ds_read_b64_tr_b16 v[192:193], v153 offset:17024
	s_waitcnt lgkmcnt(6)
	v_mfma_f32_32x32x16_bf16 v[34:49], v[82:85], v[206:209], v[34:49]
	v_exp_f32_e32 v94, v94
	v_exp_f32_e32 v95, v95
	v_exp_f32_e32 v96, v96
	v_exp_f32_e32 v97, v97
	ds_read_b64_tr_b16 v[206:207], v153 offset:14528
	ds_read_b64_tr_b16 v[208:209], v153 offset:17088
	v_mfma_f32_32x32x16_bf16 v[66:81], v[82:85], v[86:89], v[66:81]
	v_cvt_pk_bf16_f32 v90, v90, v91
	v_cvt_pk_bf16_f32 v91, v92, v93
	v_cvt_pk_bf16_f32 v92, v94, v95
	v_cvt_pk_bf16_f32 v93, v96, v97
	s_nop 0
	s_waitcnt lgkmcnt(6)
	v_mfma_f32_32x32x16_bf16 v[2:17], v[90:93], v[154:157], v[2:17]
	v_sub_f32_e32 v98, v98, v152
	v_sub_f32_e32 v99, v99, v152
	v_sub_f32_e32 v100, v100, v152
	v_sub_f32_e32 v101, v101, v152
	ds_read_b64_tr_b16 v[154:155], v153 offset:19456
	ds_read_b64_tr_b16 v[156:157], v153 offset:22016
	s_waitcnt lgkmcnt(6)
	v_mfma_f32_32x32x16_bf16 v[50:65], v[90:93], v[162:165], v[50:65]
	v_sub_f32_e32 v102, v102, v152
	v_sub_f32_e32 v103, v103, v152
	v_sub_f32_e32 v104, v104, v152
	v_sub_f32_e32 v105, v105, v152
	ds_read_b64_tr_b16 v[162:163], v153 offset:19520
	ds_read_b64_tr_b16 v[164:165], v153 offset:22080
	s_waitcnt lgkmcnt(6)
	v_mfma_f32_32x32x16_bf16 v[18:33], v[90:93], v[190:193], v[18:33]
	v_exp_f32_e32 v98, v98
	v_exp_f32_e32 v99, v99
	v_exp_f32_e32 v100, v100
	v_exp_f32_e32 v101, v101
	ds_read_b64_tr_b16 v[190:191], v153 offset:19584
	ds_read_b64_tr_b16 v[192:193], v153 offset:22144
	s_waitcnt lgkmcnt(6)
	v_mfma_f32_32x32x16_bf16 v[34:49], v[90:93], v[206:209], v[34:49]
	v_exp_f32_e32 v102, v102
	v_exp_f32_e32 v103, v103
	v_exp_f32_e32 v104, v104
	v_exp_f32_e32 v105, v105
	ds_read_b64_tr_b16 v[206:207], v153 offset:19648
	ds_read_b64_tr_b16 v[208:209], v153 offset:22208
	v_mfma_f32_32x32x16_bf16 v[66:81], v[90:93], v[86:89], v[66:81]
	v_cvt_pk_bf16_f32 v98, v98, v99
	v_cvt_pk_bf16_f32 v99, v100, v101
	v_cvt_pk_bf16_f32 v100, v102, v103
	v_cvt_pk_bf16_f32 v101, v104, v105
	s_nop 0
	s_waitcnt lgkmcnt(6)
	v_mfma_f32_32x32x16_bf16 v[2:17], v[98:101], v[154:157], v[2:17]
	v_sub_f32_e32 v106, v106, v152
	v_sub_f32_e32 v107, v107, v152
	v_sub_f32_e32 v108, v108, v152
	v_sub_f32_e32 v109, v109, v152
	ds_read_b64_tr_b16 v[154:155], v153 offset:24576
	ds_read_b64_tr_b16 v[156:157], v153 offset:27136
	s_waitcnt lgkmcnt(6)
	v_mfma_f32_32x32x16_bf16 v[50:65], v[98:101], v[162:165], v[50:65]
	v_sub_f32_e32 v110, v110, v152
	v_sub_f32_e32 v111, v111, v152
	v_sub_f32_e32 v112, v112, v152
	v_sub_f32_e32 v113, v113, v152
	ds_read_b64_tr_b16 v[162:163], v153 offset:24640
	ds_read_b64_tr_b16 v[164:165], v153 offset:27200
	s_waitcnt lgkmcnt(6)
	v_mfma_f32_32x32x16_bf16 v[18:33], v[98:101], v[190:193], v[18:33]
	v_exp_f32_e32 v106, v106
	v_exp_f32_e32 v107, v107
	v_exp_f32_e32 v108, v108
	v_exp_f32_e32 v109, v109
	ds_read_b64_tr_b16 v[190:191], v153 offset:24704
	ds_read_b64_tr_b16 v[192:193], v153 offset:27264
	s_waitcnt lgkmcnt(6)
	v_mfma_f32_32x32x16_bf16 v[34:49], v[98:101], v[206:209], v[34:49]
	v_exp_f32_e32 v110, v110
	v_exp_f32_e32 v111, v111
	v_exp_f32_e32 v112, v112
	v_exp_f32_e32 v113, v113
	ds_read_b64_tr_b16 v[206:207], v153 offset:24768
	ds_read_b64_tr_b16 v[208:209], v153 offset:27328
	v_mfma_f32_32x32x16_bf16 v[66:81], v[98:101], v[86:89], v[66:81]
	v_cvt_pk_bf16_f32 v106, v106, v107
	v_cvt_pk_bf16_f32 v107, v108, v109
	v_cvt_pk_bf16_f32 v108, v110, v111
	v_cvt_pk_bf16_f32 v109, v112, v113
	s_nop 0
	s_waitcnt lgkmcnt(6)
	v_mfma_f32_32x32x16_bf16 v[2:17], v[106:109], v[154:157], v[2:17]
	s_waitcnt lgkmcnt(4)
	v_mfma_f32_32x32x16_bf16 v[50:65], v[106:109], v[162:165], v[50:65]
	s_waitcnt lgkmcnt(2)
	v_mfma_f32_32x32x16_bf16 v[18:33], v[106:109], v[190:193], v[18:33]
	s_waitcnt lgkmcnt(0)
	v_mfma_f32_32x32x16_bf16 v[34:49], v[106:109], v[206:209], v[34:49]
	v_mfma_f32_32x32x16_bf16 v[66:81], v[106:109], v[86:89], v[66:81]
	s_movk_i32 s77, 0x110
	s_andn2_b64 vcc, exec, s[28:29]
	s_cbranch_vccnz .LBB0_92
.LBB0_91:
	s_xor_b32 s23, s23, 1
	s_mulk_i32 s23, 0x7400
	s_add_i32 s23, s23, 0
	v_add3_u32 v82, s23, v174, v0
	v_add_u32_e32 v83, s23, v144
	v_add_u32_e32 v84, v83, v175
	v_add_u32_e32 v83, v83, v176
	s_waitcnt vmcnt(2)
	ds_write_b128 v82, v[114:117]
	s_waitcnt vmcnt(1)
	ds_write_b128 v84, v[130:133] offset:9216
	s_waitcnt vmcnt(0)
	ds_write_b128 v83, v[138:141] offset:9216
